# speedup vs baseline: 1.0157x; 1.0157x over previous
; template <int EPI>
; __device__ __forceinline__ void phase_gemm(const Params& p, const GemmDesc& d, char* shmc) {
;     ...
;       const int ch0 = pn * 128;
;       const float* cwp = p.conv_w + (size_t)d.layer * 3 * DFF;
;       const float* cbp = p.conv_b + (size_t)d.layer * DFF;
;       float cw[2][4];
; #pragma unroll
;       for (int n = 0; n < 2; ++n) {
;         const int chx = ch0 + ewc * 32 + n * 16 + efr;
;         cw[n][0] = cwp[chx]; cw[n][1] = cwp[DFF + chx]; cw[n][2] = cwp[2 * DFF + chx]; cw[n][3] = cbp[chx];
;       }
;       const float* rsl = reinterpret_cast<const float*>(shmc + 143360);
;       f32x4 rsv[2][4];
; #pragma unroll
;       for (int ai = 0; ai < 2; ++ai)
; #pragma unroll
;         for (int m = 0; m < 4; ++m)
;           rsv[ai][m] = *reinterpret_cast<const f32x4*>(rsl + ai * HALF + ewr * 64 + m * 16 + efq * 4);
; #pragma unroll
;       for (int ai = 0; ai < 2; ++ai)
; #pragma unroll
;         for (int m = 0; m < 4; ++m) {
;           const f32x4 rs4 = rsv[ai][m];
; #pragma unroll
;           for (int n = 0; n < 2; ++n) {
;             acc[ai][0][m][n] *= rs4;
;             acc[ai][1][m][n] *= rs4;
;             const int s = ai * 32 + ewr * 16 + m * 4 + efq;
;             const int col = ewc * 32 + n * 16 + efr;
;             top[s * 144 + col] = acc[ai][0][m][n][0];
;             bot[s * 144 + col] = acc[ai][0][m][n][3];
;           }
;         }
;       __syncthreads();
.LBB0_299:
	s_or_b64 exec, exec, s[8:9]
	v_mov_b32_e32 v38, v1
	s_movk_i32 s8, 0x60
	v_and_b32_e32 v177, 15, v38
	v_lshrrev_b32_e32 v30, 1, v38
	s_lshl_b32 s62, s34, 7
	v_and_or_b32 v162, v30, s8, v177
	v_or_b32_e32 v200, s62, v162
	v_ashrrev_i32_e32 v201, 31, v200
	v_lshlrev_b64 v[30:31], 2, v[200:201]
	v_lshl_add_u64 v[32:33], s[44:45], 0, v[30:31]
	v_add_co_u32_e32 v34, vcc, 0x5000, v32
	v_lshl_add_u64 v[30:31], s[46:47], 0, v[30:31]
	s_nop 0
	v_addc_co_u32_e32 v35, vcc, 0, v33, vcc
	v_add_co_u32_e32 v36, vcc, 0xb000, v32
	v_ashrrev_i32_e32 v175, 4, v38
	s_nop 0
	v_addc_co_u32_e32 v37, vcc, 0, v33, vcc
	global_load_dword v215, v[32:33], off
	global_load_dword v217, v[34:35], off offset:2048
	global_load_dword v216, v[36:37], off
	global_load_dword v208, v[36:37], off offset:64
	global_load_dword v210, v[34:35], off offset:2112
	global_load_dword v209, v[32:33], off offset:64
	global_load_dword v218, v[30:31], off
	global_load_dword v207, v[30:31], off offset:64
	v_bfe_u32 v178, v38, 8, 1
	v_and_b32_e32 v179, 3, v175
	v_lshlrev_b32_e32 v30, 8, v178
	v_lshlrev_b32_e32 v31, 4, v179
	v_add3_u32 v30, s76, v30, v31
	v_lshl_or_b32 v220, v178, 4, v179
	s_movk_i32 s8, 0x90
	ds_read_b128 v[62:65], v30
	ds_read_b128 v[54:57], v30 offset:64
	ds_read_b128 v[50:53], v30 offset:128
	ds_read_b128 v[46:49], v30 offset:192
	ds_read_b128 v[42:45], v30 offset:512
	ds_read_b128 v[38:41], v30 offset:576
	ds_read_b128 v[34:37], v30 offset:640
	ds_read_b128 v[30:33], v30 offset:704
	v_mad_u32_u24 v178, v220, s8, v162
	v_lshl_add_u32 v211, v178, 2, 0
	s_waitcnt lgkmcnt(0)
	v_pk_mul_f32 v[196:197], v[144:145], v[56:57]
	v_pk_mul_f32 v[198:199], v[142:143], v[54:55]
	v_pk_mul_f32 v[144:145], v[134:135], v[54:55]
	v_add_u32_e32 v134, 0x800, v211
	v_pk_mul_f32 v[190:191], v[128:129], v[52:53]
	v_pk_mul_f32 v[188:189], v[110:111], v[46:47]
	v_pk_mul_f32 v[128:129], v[102:103], v[46:47]
	v_add_u32_e32 v102, 0x1800, v211
	v_pk_mul_f32 v[142:143], v[136:137], v[56:57]
	ds_write2_b32 v134, v198, v144 offset0:64 offset1:80
	v_add_u32_e32 v134, 0x9800, v211
	v_pk_mul_f32 v[192:193], v[126:127], v[50:51]
	v_pk_mul_f32 v[136:137], v[118:119], v[50:51]
	v_add_u32_e32 v118, 0x1000, v211
	v_pk_mul_f32 v[186:187], v[112:113], v[48:49]
	v_pk_mul_f32 v[126:127], v[104:105], v[48:49]
	ds_write2_b32 v102, v188, v128 offset0:192 offset1:208
	v_add_u32_e32 v102, 0xa800, v211
	ds_write2_b32 v134, v197, v143 offset0:64 offset1:80
	v_pk_mul_f32 v[134:135], v[120:121], v[52:53]
	ds_write2_b32 v118, v192, v136 offset0:128 offset1:144
	v_add_u32_e32 v118, 0xa000, v211
	ds_write2_b32 v102, v187, v127 offset0:192 offset1:208
	v_pk_mul_f32 v[184:185], v[154:155], v[42:43]
	v_pk_mul_f32 v[120:121], v[150:151], v[42:43]
	v_add_u32_e32 v102, 0x4800, v211
	ds_write2_b32 v118, v191, v135 offset0:128 offset1:144
	v_pk_mul_f32 v[182:183], v[156:157], v[44:45]
	v_pk_mul_f32 v[118:119], v[152:153], v[44:45]
	ds_write2_b32 v102, v184, v120 offset1:16
	v_add_u32_e32 v102, 0xd800, v211
	v_pk_mul_f32 v[154:155], v[106:107], v[30:31]
	v_pk_mul_f32 v[98:99], v[98:99], v[30:31]
	v_add_u32_e32 v106, 0x6000, v211
	ds_write2_b32 v102, v183, v119 offset1:16
	v_pk_mul_f32 v[180:181], v[138:139], v[38:39]
	v_pk_mul_f32 v[112:113], v[130:131], v[38:39]
	v_add_u32_e32 v102, 0x5000, v211
	v_pk_mul_f32 v[152:153], v[108:109], v[32:33]
	v_pk_mul_f32 v[100:101], v[100:101], v[32:33]
	ds_write2_b32 v106, v154, v98 offset0:192 offset1:208
	v_add_u32_e32 v106, 0xf000, v211
	s_movk_i32 s8, 0x240
	v_pk_mul_f32 v[202:203], v[160:161], v[64:65]
	v_pk_mul_f32 v[194:195], v[158:159], v[62:63]
	v_pk_mul_f32 v[146:147], v[146:147], v[62:63]
	v_pk_mul_f32 v[178:179], v[140:141], v[40:41]
	v_pk_mul_f32 v[110:111], v[132:133], v[40:41]
	ds_write2_b32 v102, v180, v112 offset0:64 offset1:80
	v_add_u32_e32 v102, 0xe000, v211
	v_pk_mul_f32 v[160:161], v[122:123], v[34:35]
	v_pk_mul_f32 v[104:105], v[114:115], v[34:35]
	v_add_u32_e32 v114, 0x5800, v211
	ds_write2_b32 v106, v153, v101 offset0:192 offset1:208
	v_mad_u32_u24 v106, v220, s8, 0
	v_pk_mul_f32 v[158:159], v[148:149], v[64:65]
	ds_write2_b32 v211, v194, v146 offset1:16
	v_add_u32_e32 v148, 0x9000, v211
	ds_write2_b32 v102, v179, v111 offset0:64 offset1:80
	v_pk_mul_f32 v[156:157], v[124:125], v[36:37]
	v_pk_mul_f32 v[102:103], v[116:117], v[36:37]
	ds_write2_b32 v114, v160, v104 offset0:128 offset1:144
	v_add_u32_e32 v114, 0xe800, v211
	v_cmp_eq_u32_e64 s[10:11], 0, v220
	v_cmp_ne_u32_e32 vcc, 0, v220
	v_mov_b32_e32 v213, 0
	v_lshl_add_u32 v211, v162, 2, v106
	v_mov_b32_e32 v224, 0
	ds_write2_b32 v148, v203, v159 offset1:16
	ds_write2_b32 v114, v157, v103 offset0:128 offset1:144
	s_waitcnt vmcnt(0) lgkmcnt(0)
	s_barrier
; __device__ __forceinline__ float erf_f32(float x) {
;   const float ax = fabsf(x);
;   const float t = __frcp_rn(fmaf(0.3275911f, ax, 1.0f));
;   float poly = fmaf(1.061405429f, t, -1.453152027f);
;   poly = fmaf(poly, t, 1.421413741f);
;   poly = fmaf(poly, t, -0.284496736f);
;   poly = fmaf(poly, t, 0.254829592f);
;   const float y = 1.0f - poly * t * __expf(-ax * ax);
; template <int EPI>
; __device__ __forceinline__ void phase_gemm(const Params& p, const GemmDesc& d, char* shmc) {
;     ...
;       float gp[2][4][2], gn[2][4][2];
; #pragma unroll
;       for (int ai = 0; ai < 2; ++ai)
; #pragma unroll
;         for (int m = 0; m < 4; ++m)
; #pragma unroll
;           for (int n = 0; n < 2; ++n) {
;             const int s = ai * 32 + ewr * 16 + m * 4 + efq;
;             const int col = ewc * 32 + n * 16 + efr;
;             gp[ai][m][n] = (s > 0) ? bot[(s - 1) * 144 + col] : 0.f;
;             gn[ai][m][n] = (s < 63) ? top[(s + 1) * 144 + col] : 0.f;
;           }
;       float* edge = p.edge + (size_t)pm * 6 * DFF;
; #pragma unroll
;       for (int n = 0; n < 2; ++n) {
;         const int col = ewc * 32 + n * 16 + efr;
;         const int ch = ch0 + col;
;         const float w0 = cw[n][0], w1 = cw[n][1], w2 = cw[n][2], cb = cw[n][3];
; #pragma unroll
;         for (int ai = 0; ai < 2; ++ai)
; #pragma unroll
;           for (int m = 0; m < 4; ++m) {
;             const int s = ai * 32 + ewr * 16 + m * 4 + efq;
;             const f32x4 g = acc[ai][0][m][n];
;             const f32x4 v = acc[ai][1][m][n];
;             const float c0 = w0 * gp[ai][m][n] + w1 * g[0] + w2 * g[1] + cb;
;             const float c1 = w0 * g[0] + w1 * g[1] + w2 * g[2] + cb;
;             const float c2 = w0 * g[1] + w1 * g[2] + w2 * g[3] + cb;
;             const float c3 = w0 * g[2] + w1 * g[3] + w2 * gn[ai][m][n] + cb;
;             u16* sp = stg + (s * 4) * 136 + col;
;             sp[0] = f2bf(gelu_exact(c0) * v[0]);
;             sp[136] = f2bf(gelu_exact(c1) * v[1]);
;             sp[272] = f2bf(gelu_exact(c2) * v[2]);
;             sp[408] = f2bf(gelu_exact(c3) * v[3]);
;             if (s == 0) {
;               edge[0 * DFF + ch] = c0; edge[1 * DFF + ch] = g[0]; edge[2 * DFF + ch] = v[0];
;             }
;             if (s == 63) {
;               edge[3 * DFF + ch] = c3; edge[4 * DFF + ch] = g[3]; edge[5 * DFF + ch] = v[3];
;             }
;           }
	s_and_saveexec_b64 s[8:9], vcc
	ds_read_b32 v224, v211 offset:36288
	s_or_b64 exec, exec, s[8:9]
	ds_read_b32 v223, v211 offset:576
	s_and_saveexec_b64 s[8:9], vcc
	ds_read_b32 v213, v211 offset:36352
	s_or_b64 exec, exec, s[8:9]
	v_add_u32_e32 v106, 0x9400, v211
	ds_read2_b32 v[150:151], v106 offset0:176 offset1:192
	v_add_u32_e32 v106, 0x800, v211
	ds_read2_b32 v[148:149], v106 offset0:208 offset1:224
	v_add_u32_e32 v106, 0x9e00, v211
	ds_read2_b32 v[140:141], v106 offset0:112 offset1:128
	v_add_u32_e32 v106, 0x1400, v211
	ds_read2_b32 v[138:139], v106 offset0:16 offset1:32
	v_add_u32_e32 v106, 0xa800, v211
	ds_read2_b32 v[132:133], v106 offset0:48 offset1:64
	v_add_u32_e32 v106, 0x1c00, v211
	ds_read2_b32 v[130:131], v106 offset0:80 offset1:96
	v_add_u32_e32 v106, 0xd400, v211
	ds_read2_b32 v[124:125], v106 offset0:112 offset1:128
	v_add_u32_e32 v106, 0x4800, v211
	ds_read2_b32 v[122:123], v106 offset0:144 offset1:160
	v_add_u32_e32 v106, 0xdc00, v211
	ds_read2_b32 v[116:117], v106 offset0:176 offset1:192
	v_add_u32_e32 v106, 0x5000, v211
	ds_read2_b32 v[114:115], v106 offset0:208 offset1:224
	v_add_u32_e32 v106, 0xe600, v211
	ds_read2_b32 v[108:109], v106 offset0:112 offset1:128
	v_add_u32_e32 v106, 0x5c00, v211
	ds_read2_b32 v[106:107], v106 offset0:16 offset1:32
	ds_read_b32 v214, v211 offset:640
	ds_read_b32 v221, v211 offset:61632
	v_cmp_eq_u32_e64 s[8:9], 19, v220
	v_cmp_ne_u32_e32 vcc, 19, v220
	v_add_u32_e32 v222, 0x6300, v211
	v_mov_b32_e32 v211, 0
	v_mov_b32_e32 v219, 0
	s_and_saveexec_b64 s[64:65], vcc
	ds_read_b32 v219, v222 offset:576
	s_or_b64 exec, exec, s[64:65]
	ds_read_b32 v212, v222 offset:36352
	s_and_saveexec_b64 s[64:65], vcc
	ds_read_b32 v211, v222 offset:640
	s_or_b64 exec, exec, s[64:65]
	s_mul_hi_i32 s34, s14, 0x21000
	s_mul_i32 s14, s14, 0x21000
	v_readlane_b32 s72, v246, 15
	v_readlane_b32 s73, v246, 16
	s_add_u32 s64, s72, s14
	s_addc_u32 s65, s73, s34
	v_pk_mul_f32 v[226:227], v[96:97], v[64:65]
	v_pk_mul_f32 v[96:97], v[94:95], v[62:63]
	v_lshl_add_u64 v[94:95], v[200:201], 2, s[64:65]
	s_waitcnt lgkmcnt(14)
	v_mul_f32_e32 v200, v215, v224
	v_fmac_f32_e32 v200, v217, v194
	v_mul_f32_e32 v224, v217, v202
	v_fmac_f32_e32 v200, v216, v195
	v_mul_f32_e32 v201, v217, v195
	v_fmac_f32_e32 v224, v215, v195
	v_add_f32_e32 v200, v218, v200
	v_fmac_f32_e32 v201, v215, v194
	v_fmac_f32_e32 v224, v216, v203
	v_mul_f32_e32 v203, v217, v203
	v_fmac_f32_e32 v201, v216, v202
	v_fmac_f32_e32 v203, v215, v202
	v_mul_f32_e32 v202, 0x3f3504f3, v200
	v_fmac_f32_e32 v203, v216, v223
	v_fma_f32 v223, |v202|, s95, 1.0
	v_add_f32_e32 v195, v218, v224
	v_add_f32_e32 v201, v218, v201
	s_add_i32 s14, 0, 0x12000
	v_lshl_add_u32 v222, v162, 1, s14
	v_rcp_f32_e32 v223, v223
	v_mul_f32_e64 v225, |v202|, -|v202|
	v_fmamk_f32 v224, v223, 0x3f87dc22, v206
	v_mul_f32_e32 v225, 0x3fb8aa3b, v225
	v_fmaak_f32 v224, v224, v223, 0x3fb5f0e3
	v_exp_f32_e32 v225, v225
	v_fmaak_f32 v224, v224, v223, 0xbe91a98e
	v_fmaak_f32 v224, v224, v223, 0x3e827906
	v_mul_f32_e32 v223, v223, v224
	v_fma_f32 v223, -v225, v223, 1.0
	v_bfi_b32 v202, s96, v223, v202
	v_mul_f32_e32 v223, 0x3f3504f3, v201
	s_movk_i32 s34, 0x440
	v_fma_f32 v224, |v223|, s95, 1.0
	v_mad_u32_u24 v228, v220, s34, v222
	v_mul_f32_e32 v229, 0.5, v200
	v_add_f32_e32 v202, 1.0, v202
	v_mul_f32_e32 v202, v229, v202
	v_mul_f32_e32 v202, v96, v202
	v_cvt_pk_bf16_f32 v202, v202, s0
	ds_write_b16 v228, v202
	v_rcp_f32_e32 v202, v224
	v_mul_f32_e64 v225, |v223|, -|v223|
	v_fmamk_f32 v224, v202, 0x3f87dc22, v206
	v_mul_f32_e32 v225, 0x3fb8aa3b, v225
	v_fmaak_f32 v224, v224, v202, 0x3fb5f0e3
	v_exp_f32_e32 v225, v225
	v_fmaak_f32 v224, v224, v202, 0xbe91a98e
	v_fmaak_f32 v224, v224, v202, 0x3e827906
	v_mul_f32_e32 v202, v202, v224
	v_fma_f32 v202, -v225, v202, 1.0
	v_bfi_b32 v202, s96, v202, v223
	v_mul_f32_e32 v201, 0.5, v201
	v_add_f32_e32 v202, 1.0, v202
	v_mul_f32_e32 v201, v201, v202
	v_mul_f32_e32 v97, v97, v201
	v_mul_f32_e32 v201, 0x3f3504f3, v195
	v_fma_f32 v202, |v201|, s95, 1.0
	v_cvt_pk_bf16_f32 v97, v97, s0
	ds_write_b16 v228, v97 offset:272
	v_mul_f32_e32 v97, 0.5, v195
	v_rcp_f32_e32 v195, v202
	v_mul_f32_e64 v223, |v201|, -|v201|
	v_fmamk_f32 v202, v195, 0x3f87dc22, v206
	v_mul_f32_e32 v223, 0x3fb8aa3b, v223
	v_fmaak_f32 v202, v202, v195, 0x3fb5f0e3
	v_exp_f32_e32 v223, v223
	v_fmaak_f32 v202, v202, v195, 0xbe91a98e
	v_fmaak_f32 v202, v202, v195, 0x3e827906
	v_mul_f32_e32 v195, v195, v202
	v_fma_f32 v195, -v223, v195, 1.0
	v_bfi_b32 v195, s96, v195, v201
	v_add_f32_e32 v203, v218, v203
	v_add_f32_e32 v195, 1.0, v195
	v_mul_f32_e32 v97, v97, v195
	v_mul_f32_e32 v195, 0x3f3504f3, v203
	v_fma_f32 v201, |v195|, s95, 1.0
	v_mul_f32_e32 v97, v226, v97
	v_cvt_pk_bf16_f32 v97, v97, s0
	ds_write_b16 v228, v97 offset:544
	v_mul_f32_e32 v97, 0.5, v203
	v_rcp_f32_e32 v201, v201
	v_mul_f32_e64 v203, |v195|, -|v195|
	v_fmamk_f32 v202, v201, 0x3f87dc22, v206
	v_mul_f32_e32 v203, 0x3fb8aa3b, v203
	v_fmaak_f32 v202, v202, v201, 0x3fb5f0e3
	v_exp_f32_e32 v203, v203
	v_fmaak_f32 v202, v202, v201, 0xbe91a98e
	v_fmaak_f32 v202, v202, v201, 0x3e827906
	v_mul_f32_e32 v201, v201, v202
	v_fma_f32 v201, -v203, v201, 1.0
	v_bfi_b32 v195, s96, v201, v195
	v_add_f32_e32 v195, 1.0, v195
	v_mul_f32_e32 v97, v97, v195
	v_mul_f32_e32 v97, v227, v97
	v_cvt_pk_bf16_f32 v97, v97, s0
	v_readlane_b32 s74, v246, 17
	v_readlane_b32 s75, v246, 18
	ds_write_b16 v228, v97 offset:816
	s_and_saveexec_b64 s[78:79], s[10:11]
	s_cbranch_execz .LBB0_309
	global_store_dword v[94:95], v200, off
	v_add_co_u32_e32 v200, vcc, 0x5000, v94
	s_nop 1
	v_addc_co_u32_e32 v201, vcc, 0, v95, vcc
	global_store_dword v[200:201], v194, off offset:2048
	v_add_co_u32_e32 v194, vcc, 0xb000, v94
	s_nop 1
	v_addc_co_u32_e32 v195, vcc, 0, v95, vcc
	global_store_dword v[194:195], v96, off
; __device__ __forceinline__ u16 f2bf(float f) { return (u16)(pack2(f, f) & 0xffffu); }
; __device__ __forceinline__ float erf_f32(float x) {
;   const float ax = fabsf(x);
;   const float t = __frcp_rn(fmaf(0.3275911f, ax, 1.0f));
;   float poly = fmaf(1.061405429f, t, -1.453152027f);
;   poly = fmaf(poly, t, 1.421413741f);
;   poly = fmaf(poly, t, -0.284496736f);
;   poly = fmaf(poly, t, 0.254829592f);
;   const float y = 1.0f - poly * t * __expf(-ax * ax);
;   return copysignf(y, x);
; }
; __device__ __forceinline__ float gelu_exact(float x) { return 0.5f * x * (1.0f + erf_f32(x * 0.70710678118654752f)); }
; template <int EPI>
; __device__ __forceinline__ void phase_gemm(const Params& p, const GemmDesc& d, char* shmc) {
;     ...
; #pragma unroll
;       for (int n = 0; n < 2; ++n) {
;         const int col = ewc * 32 + n * 16 + efr;
;         const int ch = ch0 + col;
;         const float w0 = cw[n][0], w1 = cw[n][1], w2 = cw[n][2], cb = cw[n][3];
; #pragma unroll
;         for (int ai = 0; ai < 2; ++ai)
; #pragma unroll
;           for (int m = 0; m < 4; ++m) {
;             const int s = ai * 32 + ewr * 16 + m * 4 + efq;
;             const f32x4 g = acc[ai][0][m][n];
;             const f32x4 v = acc[ai][1][m][n];
;             const float c0 = w0 * gp[ai][m][n] + w1 * g[0] + w2 * g[1] + cb;
;             const float c1 = w0 * g[0] + w1 * g[1] + w2 * g[2] + cb;
;             const float c2 = w0 * g[1] + w1 * g[2] + w2 * g[3] + cb;
;             const float c3 = w0 * g[2] + w1 * g[3] + w2 * gn[ai][m][n] + cb;
;             u16* sp = stg + (s * 4) * 136 + col;
;             sp[0] = f2bf(gelu_exact(c0) * v[0]);
;             sp[136] = f2bf(gelu_exact(c1) * v[1]);
;             sp[272] = f2bf(gelu_exact(c2) * v[2]);
;             sp[408] = f2bf(gelu_exact(c3) * v[3]);
;             if (s == 0) {
;               edge[0 * DFF + ch] = c0; edge[1 * DFF + ch] = g[0]; edge[2 * DFF + ch] = v[0];
;             }
;             if (s == 63) {
;               edge[3 * DFF + ch] = c3; edge[4 * DFF + ch] = g[3]; edge[5 * DFF + ch] = v[3];
;             }
;           }
.LBB0_309:
	s_or_b64 exec, exec, s[78:79]
	v_pk_mul_f32 v[96:97], v[68:69], v[48:49]
	v_pk_mul_f32 v[68:69], v[78:79], v[30:31]
	v_mul_f32_e32 v78, v215, v150
	v_fmac_f32_e32 v78, v217, v198
	v_fmac_f32_e32 v78, v216, v199
	v_add_f32_e32 v79, v218, v78
	v_pk_mul_f32 v[200:201], v[72:73], v[52:53]
	v_pk_mul_f32 v[72:73], v[82:83], v[34:35]
	v_mul_f32_e32 v83, 0x3f3504f3, v79
	v_pk_mul_f32 v[202:203], v[70:71], v[50:51]
	v_pk_mul_f32 v[70:71], v[84:85], v[36:37]
	v_fma_f32 v84, |v83|, s95, 1.0
	v_mul_f32_e32 v78, v217, v199
	v_pk_mul_f32 v[224:225], v[76:77], v[56:57]
	v_pk_mul_f32 v[76:77], v[86:87], v[38:39]
	v_fmac_f32_e32 v78, v215, v198
	v_fmac_f32_e32 v78, v216, v196
	v_pk_mul_f32 v[194:195], v[66:67], v[46:47]
	v_pk_mul_f32 v[66:67], v[80:81], v[32:33]
	v_add_f32_e32 v80, v218, v78
	v_mul_f32_e32 v78, v217, v196
	v_fmac_f32_e32 v78, v215, v199
	v_pk_mul_f32 v[226:227], v[74:75], v[54:55]
	v_pk_mul_f32 v[74:75], v[88:89], v[40:41]
	v_fmac_f32_e32 v78, v216, v197
	v_add_f32_e32 v81, v218, v78
	v_mul_f32_e32 v78, v217, v197
	v_fmac_f32_e32 v78, v215, v196
	s_waitcnt lgkmcnt(14)
	v_fmac_f32_e32 v78, v216, v148
	v_rcp_f32_e32 v84, v84
	v_mul_f32_e64 v86, |v83|, -|v83|
	v_fmamk_f32 v85, v84, 0x3f87dc22, v206
	v_mul_f32_e32 v86, 0x3fb8aa3b, v86
	v_fmaak_f32 v85, v85, v84, 0x3fb5f0e3
	v_exp_f32_e32 v86, v86
	v_fmaak_f32 v85, v85, v84, 0xbe91a98e
	v_fmaak_f32 v85, v85, v84, 0x3e827906
	v_mul_f32_e32 v84, v84, v85
	v_fma_f32 v84, -v86, v84, 1.0
	v_bfi_b32 v83, s96, v84, v83
	v_mul_f32_e32 v79, 0.5, v79
	v_add_f32_e32 v83, 1.0, v83
	v_mul_f32_e32 v79, v79, v83
	v_mul_f32_e32 v83, 0x3f3504f3, v80
	v_fma_f32 v84, |v83|, s95, 1.0
	v_mul_u32_u24_e32 v220, 0x440, v220
	v_add_f32_e32 v82, v218, v78
	v_add_u32_e32 v78, 0x1100, v220
	v_mul_f32_e32 v79, v226, v79
	v_add_u32_e32 v87, v222, v78
	v_cvt_pk_bf16_f32 v79, v79, s0
	ds_write_b16 v87, v79
	v_mul_f32_e32 v79, 0.5, v80
	v_rcp_f32_e32 v80, v84
	v_mul_f32_e64 v85, |v83|, -|v83|
	v_fmamk_f32 v84, v80, 0x3f87dc22, v206
	v_mul_f32_e32 v85, 0x3fb8aa3b, v85
	v_fmaak_f32 v84, v84, v80, 0x3fb5f0e3
	v_exp_f32_e32 v85, v85
	v_fmaak_f32 v84, v84, v80, 0xbe91a98e
	v_fmaak_f32 v84, v84, v80, 0x3e827906
	v_mul_f32_e32 v80, v80, v84
	v_fma_f32 v80, -v85, v80, 1.0
	v_bfi_b32 v80, s96, v80, v83
	v_add_f32_e32 v80, 1.0, v80
	v_mul_f32_e32 v79, v79, v80
	v_mul_f32_e32 v80, 0x3f3504f3, v81
	v_fma_f32 v83, |v80|, s95, 1.0
	v_mul_f32_e32 v79, v227, v79
	v_cvt_pk_bf16_f32 v79, v79, s0
	ds_write_b16 v87, v79 offset:272
	v_mul_f32_e32 v79, 0.5, v81
	v_rcp_f32_e32 v81, v83
	v_mul_f32_e64 v84, |v80|, -|v80|
	v_fmamk_f32 v83, v81, 0x3f87dc22, v206
	v_mul_f32_e32 v84, 0x3fb8aa3b, v84
	v_fmaak_f32 v83, v83, v81, 0x3fb5f0e3
	v_exp_f32_e32 v84, v84
	v_fmaak_f32 v83, v83, v81, 0xbe91a98e
	v_fmaak_f32 v83, v83, v81, 0x3e827906
	v_mul_f32_e32 v81, v81, v83
	v_fma_f32 v81, -v84, v81, 1.0
	v_bfi_b32 v80, s96, v81, v80
	v_add_f32_e32 v80, 1.0, v80
	v_mul_f32_e32 v79, v79, v80
	v_mul_f32_e32 v80, 0x3f3504f3, v82
	v_fma_f32 v81, |v80|, s95, 1.0
	v_mul_f32_e32 v79, v224, v79
	v_cvt_pk_bf16_f32 v79, v79, s0
	ds_write_b16 v87, v79 offset:544
	v_mul_f32_e32 v79, 0.5, v82
	v_rcp_f32_e32 v81, v81
	v_mul_f32_e64 v83, |v80|, -|v80|
	v_fmamk_f32 v82, v81, 0x3f87dc22, v206
	v_mul_f32_e32 v83, 0x3fb8aa3b, v83
	v_fmaak_f32 v82, v82, v81, 0x3fb5f0e3
	v_exp_f32_e32 v83, v83
	v_fmaak_f32 v82, v82, v81, 0xbe91a98e
	v_fmaak_f32 v82, v82, v81, 0x3e827906
	v_mul_f32_e32 v81, v81, v82
	v_fma_f32 v81, -v83, v81, 1.0
	v_bfi_b32 v80, s96, v81, v80
	v_add_f32_e32 v80, 1.0, v80
	v_mul_f32_e32 v79, v79, v80
	v_mul_f32_e32 v79, v225, v79
	v_cvt_pk_bf16_f32 v79, v79, s0
	ds_write_b16 v87, v79 offset:816
	v_mul_f32_e32 v79, v215, v140
	v_fmac_f32_e32 v79, v217, v192
	v_fmac_f32_e32 v79, v216, v193
	v_add_f32_e32 v80, v218, v79
	v_mul_f32_e32 v84, 0x3f3504f3, v80
	v_mul_f32_e32 v79, v217, v193
	v_fma_f32 v85, |v84|, s95, 1.0
	v_fmac_f32_e32 v79, v215, v192
	v_fmac_f32_e32 v79, v216, v190
	v_add_f32_e32 v81, v218, v79
	v_mul_f32_e32 v79, v217, v190
	v_fmac_f32_e32 v79, v215, v193
	v_fmac_f32_e32 v79, v216, v191
	v_add_f32_e32 v82, v218, v79
	v_mul_f32_e32 v79, v217, v191
	v_fmac_f32_e32 v79, v215, v190
	v_fmac_f32_e32 v79, v216, v138
	v_rcp_f32_e32 v85, v85
	v_mul_f32_e64 v87, |v84|, -|v84|
	v_fmamk_f32 v86, v85, 0x3f87dc22, v206
	v_mul_f32_e32 v87, 0x3fb8aa3b, v87
	v_fmaak_f32 v86, v86, v85, 0x3fb5f0e3
	v_exp_f32_e32 v87, v87
	v_fmaak_f32 v86, v86, v85, 0xbe91a98e
	v_fmaak_f32 v86, v86, v85, 0x3e827906
	v_mul_f32_e32 v85, v85, v86
	v_fma_f32 v85, -v87, v85, 1.0
	v_bfi_b32 v84, s96, v85, v84
	v_mul_f32_e32 v80, 0.5, v80
	v_add_f32_e32 v84, 1.0, v84
	v_mul_f32_e32 v80, v80, v84
	v_mul_f32_e32 v84, 0x3f3504f3, v81
	v_fma_f32 v85, |v84|, s95, 1.0
	v_add_f32_e32 v83, v218, v79
	v_add_u32_e32 v79, 0x2200, v220
	v_mul_f32_e32 v80, v202, v80
	v_add_u32_e32 v88, v222, v79
	v_cvt_pk_bf16_f32 v80, v80, s0
	ds_write_b16 v88, v80
	v_mul_f32_e32 v80, 0.5, v81
	v_rcp_f32_e32 v81, v85
	v_mul_f32_e64 v86, |v84|, -|v84|
	v_fmamk_f32 v85, v81, 0x3f87dc22, v206
	v_mul_f32_e32 v86, 0x3fb8aa3b, v86
	v_fmaak_f32 v85, v85, v81, 0x3fb5f0e3
	v_exp_f32_e32 v86, v86
	v_fmaak_f32 v85, v85, v81, 0xbe91a98e
	v_fmaak_f32 v85, v85, v81, 0x3e827906
	v_mul_f32_e32 v81, v81, v85
	v_fma_f32 v81, -v86, v81, 1.0
	v_bfi_b32 v81, s96, v81, v84
	v_add_f32_e32 v81, 1.0, v81
	v_mul_f32_e32 v80, v80, v81
	v_mul_f32_e32 v81, 0x3f3504f3, v82
	v_fma_f32 v84, |v81|, s95, 1.0
	v_mul_f32_e32 v80, v203, v80
	v_cvt_pk_bf16_f32 v80, v80, s0
	ds_write_b16 v88, v80 offset:272
	v_mul_f32_e32 v80, 0.5, v82
	v_rcp_f32_e32 v82, v84
	v_mul_f32_e64 v85, |v81|, -|v81|
	v_fmamk_f32 v84, v82, 0x3f87dc22, v206
; __device__ __forceinline__ u16 f2bf(float f) { return (u16)(pack2(f, f) & 0xffffu); }
; __device__ __forceinline__ float erf_f32(float x) {
;   const float ax = fabsf(x);
;   const float t = __frcp_rn(fmaf(0.3275911f, ax, 1.0f));
;   float poly = fmaf(1.061405429f, t, -1.453152027f);
;   poly = fmaf(poly, t, 1.421413741f);
;   poly = fmaf(poly, t, -0.284496736f);
;   poly = fmaf(poly, t, 0.254829592f);
;   const float y = 1.0f - poly * t * __expf(-ax * ax);
;   return copysignf(y, x);
; }
; __device__ __forceinline__ float gelu_exact(float x) { return 0.5f * x * (1.0f + erf_f32(x * 0.70710678118654752f)); }
; template <int EPI>
; __device__ __forceinline__ void phase_gemm(const Params& p, const GemmDesc& d, char* shmc) {
;     ...
; #pragma unroll
;       for (int n = 0; n < 2; ++n) {
;         const int col = ewc * 32 + n * 16 + efr;
;         const int ch = ch0 + col;
;         const float w0 = cw[n][0], w1 = cw[n][1], w2 = cw[n][2], cb = cw[n][3];
; #pragma unroll
;         for (int ai = 0; ai < 2; ++ai)
; #pragma unroll
;           for (int m = 0; m < 4; ++m) {
;             const int s = ai * 32 + ewr * 16 + m * 4 + efq;
;             const f32x4 g = acc[ai][0][m][n];
;             const f32x4 v = acc[ai][1][m][n];
;             const float c0 = w0 * gp[ai][m][n] + w1 * g[0] + w2 * g[1] + cb;
;             const float c1 = w0 * g[0] + w1 * g[1] + w2 * g[2] + cb;
;             const float c2 = w0 * g[1] + w1 * g[2] + w2 * g[3] + cb;
;             const float c3 = w0 * g[2] + w1 * g[3] + w2 * gn[ai][m][n] + cb;
;             u16* sp = stg + (s * 4) * 136 + col;
;             sp[0] = f2bf(gelu_exact(c0) * v[0]);
;             sp[136] = f2bf(gelu_exact(c1) * v[1]);
;             sp[272] = f2bf(gelu_exact(c2) * v[2]);
;             sp[408] = f2bf(gelu_exact(c3) * v[3]);
;             if (s == 0) {
;               edge[0 * DFF + ch] = c0; edge[1 * DFF + ch] = g[0]; edge[2 * DFF + ch] = v[0];
;             }
;             if (s == 63) {
;               edge[3 * DFF + ch] = c3; edge[4 * DFF + ch] = g[3]; edge[5 * DFF + ch] = v[3];
;             }
;           }
	v_mul_f32_e32 v85, 0x3fb8aa3b, v85
	v_fmaak_f32 v84, v84, v82, 0x3fb5f0e3
	v_exp_f32_e32 v85, v85
	v_fmaak_f32 v84, v84, v82, 0xbe91a98e
	v_fmaak_f32 v84, v84, v82, 0x3e827906
	v_mul_f32_e32 v82, v82, v84
	v_fma_f32 v82, -v85, v82, 1.0
	v_bfi_b32 v81, s96, v82, v81
	v_add_f32_e32 v81, 1.0, v81
	v_mul_f32_e32 v80, v80, v81
	v_mul_f32_e32 v81, 0x3f3504f3, v83
	v_fma_f32 v82, |v81|, s95, 1.0
	v_mul_f32_e32 v80, v200, v80
	v_cvt_pk_bf16_f32 v80, v80, s0
	ds_write_b16 v88, v80 offset:544
	v_mul_f32_e32 v80, 0.5, v83
	v_rcp_f32_e32 v82, v82
	v_mul_f32_e64 v84, |v81|, -|v81|
	v_fmamk_f32 v83, v82, 0x3f87dc22, v206
	v_mul_f32_e32 v84, 0x3fb8aa3b, v84
	v_fmaak_f32 v83, v83, v82, 0x3fb5f0e3
	v_exp_f32_e32 v84, v84
	v_fmaak_f32 v83, v83, v82, 0xbe91a98e
	v_fmaak_f32 v83, v83, v82, 0x3e827906
	v_mul_f32_e32 v82, v82, v83
	v_fma_f32 v82, -v84, v82, 1.0
	v_bfi_b32 v81, s96, v82, v81
	v_add_f32_e32 v81, 1.0, v81
	v_mul_f32_e32 v80, v80, v81
	v_mul_f32_e32 v80, v201, v80
	v_cvt_pk_bf16_f32 v80, v80, s0
	ds_write_b16 v88, v80 offset:816
	v_mul_f32_e32 v80, v215, v132
	v_fmac_f32_e32 v80, v217, v188
	v_fmac_f32_e32 v80, v216, v189
	v_add_f32_e32 v81, v218, v80
	v_mul_f32_e32 v80, v217, v189
	v_fmac_f32_e32 v80, v215, v188
	v_mul_f32_e32 v85, 0x3f3504f3, v81
	v_fmac_f32_e32 v80, v216, v186
	v_fma_f32 v86, |v85|, s95, 1.0
	v_add_f32_e32 v82, v218, v80
	v_mul_f32_e32 v80, v217, v186
	v_fmac_f32_e32 v80, v215, v189
	v_fmac_f32_e32 v80, v216, v187
	v_add_f32_e32 v83, v218, v80
	v_mul_f32_e32 v80, v217, v187
	v_fmac_f32_e32 v80, v215, v186
	s_waitcnt lgkmcnt(14)
	v_fmac_f32_e32 v80, v216, v130
	v_rcp_f32_e32 v86, v86
	v_mul_f32_e64 v88, |v85|, -|v85|
	v_fmamk_f32 v87, v86, 0x3f87dc22, v206
	v_mul_f32_e32 v88, 0x3fb8aa3b, v88
	v_fmaak_f32 v87, v87, v86, 0x3fb5f0e3
	v_exp_f32_e32 v88, v88
	v_fmaak_f32 v87, v87, v86, 0xbe91a98e
	v_fmaak_f32 v87, v87, v86, 0x3e827906
	v_mul_f32_e32 v86, v86, v87
	v_fma_f32 v86, -v88, v86, 1.0
	v_bfi_b32 v85, s96, v86, v85
	v_mul_f32_e32 v81, 0.5, v81
	v_add_f32_e32 v85, 1.0, v85
	v_mul_f32_e32 v81, v81, v85
	v_mul_f32_e32 v85, 0x3f3504f3, v82
	v_fma_f32 v86, |v85|, s95, 1.0
	v_add_f32_e32 v84, v218, v80
	v_add_u32_e32 v80, 0x3300, v220
	v_mul_f32_e32 v81, v194, v81
	v_add_u32_e32 v89, v222, v80
	v_cvt_pk_bf16_f32 v81, v81, s0
	ds_write_b16 v89, v81
	v_mul_f32_e32 v81, 0.5, v82
	v_rcp_f32_e32 v82, v86
	v_mul_f32_e64 v87, |v85|, -|v85|
	v_fmamk_f32 v86, v82, 0x3f87dc22, v206
	v_mul_f32_e32 v87, 0x3fb8aa3b, v87
	v_fmaak_f32 v86, v86, v82, 0x3fb5f0e3
	v_exp_f32_e32 v87, v87
	v_fmaak_f32 v86, v86, v82, 0xbe91a98e
	v_fmaak_f32 v86, v86, v82, 0x3e827906
	v_mul_f32_e32 v82, v82, v86
	v_fma_f32 v82, -v87, v82, 1.0
	v_bfi_b32 v82, s96, v82, v85
	v_add_f32_e32 v82, 1.0, v82
	v_mul_f32_e32 v81, v81, v82
	v_mul_f32_e32 v82, 0x3f3504f3, v83
	v_fma_f32 v85, |v82|, s95, 1.0
	v_mul_f32_e32 v81, v195, v81
	v_cvt_pk_bf16_f32 v81, v81, s0
	ds_write_b16 v89, v81 offset:272
	v_mul_f32_e32 v81, 0.5, v83
	v_rcp_f32_e32 v83, v85
	v_mul_f32_e64 v86, |v82|, -|v82|
	v_fmamk_f32 v85, v83, 0x3f87dc22, v206
	v_mul_f32_e32 v86, 0x3fb8aa3b, v86
	v_fmaak_f32 v85, v85, v83, 0x3fb5f0e3
	v_exp_f32_e32 v86, v86
	v_fmaak_f32 v85, v85, v83, 0xbe91a98e
	v_fmaak_f32 v85, v85, v83, 0x3e827906
	v_mul_f32_e32 v83, v83, v85
	v_fma_f32 v83, -v86, v83, 1.0
	v_bfi_b32 v82, s96, v83, v82
	v_add_f32_e32 v82, 1.0, v82
	v_mul_f32_e32 v81, v81, v82
	v_mul_f32_e32 v82, 0x3f3504f3, v84
	v_fma_f32 v83, |v82|, s95, 1.0
	v_mul_f32_e32 v81, v96, v81
	v_cvt_pk_bf16_f32 v81, v81, s0
	ds_write_b16 v89, v81 offset:544
	v_mul_f32_e32 v81, 0.5, v84
	v_rcp_f32_e32 v83, v83
	v_mul_f32_e64 v85, |v82|, -|v82|
	v_fmamk_f32 v84, v83, 0x3f87dc22, v206
	v_mul_f32_e32 v85, 0x3fb8aa3b, v85
	v_fmaak_f32 v84, v84, v83, 0x3fb5f0e3
	v_exp_f32_e32 v85, v85
	v_fmaak_f32 v84, v84, v83, 0xbe91a98e
	v_fmaak_f32 v84, v84, v83, 0x3e827906
	v_mul_f32_e32 v83, v83, v84
	v_fma_f32 v83, -v85, v83, 1.0
	v_bfi_b32 v82, s96, v83, v82
	v_add_f32_e32 v82, 1.0, v82
	v_mul_f32_e32 v81, v81, v82
	v_mul_f32_e32 v81, v97, v81
	v_cvt_pk_bf16_f32 v81, v81, s0
	ds_write_b16 v89, v81 offset:816
	v_mul_f32_e32 v81, v215, v124
	v_fmac_f32_e32 v81, v217, v184
	v_fmac_f32_e32 v81, v216, v185
	v_add_f32_e32 v82, v218, v81
	v_mul_f32_e32 v86, 0x3f3504f3, v82
	v_mul_f32_e32 v81, v217, v185
	v_fma_f32 v87, |v86|, s95, 1.0
	v_fmac_f32_e32 v81, v215, v184
	v_fmac_f32_e32 v81, v216, v182
	v_add_f32_e32 v83, v218, v81
	v_mul_f32_e32 v81, v217, v182
	v_fmac_f32_e32 v81, v215, v185
	v_fmac_f32_e32 v81, v216, v183
	v_add_f32_e32 v84, v218, v81
	v_mul_f32_e32 v81, v217, v183
	v_fmac_f32_e32 v81, v215, v182
	v_fmac_f32_e32 v81, v216, v122
	v_rcp_f32_e32 v87, v87
	v_mul_f32_e64 v89, |v86|, -|v86|
	v_fmamk_f32 v88, v87, 0x3f87dc22, v206
	v_mul_f32_e32 v89, 0x3fb8aa3b, v89
	v_fmaak_f32 v88, v88, v87, 0x3fb5f0e3
	v_exp_f32_e32 v89, v89
	v_fmaak_f32 v88, v88, v87, 0xbe91a98e
	v_fmaak_f32 v88, v88, v87, 0x3e827906
	v_mul_f32_e32 v87, v87, v88
	v_fma_f32 v87, -v89, v87, 1.0
	v_bfi_b32 v86, s96, v87, v86
	v_mul_f32_e32 v82, 0.5, v82
	v_add_f32_e32 v86, 1.0, v86
	v_mul_f32_e32 v82, v82, v86
	v_mul_f32_e32 v86, 0x3f3504f3, v83
	v_fma_f32 v87, |v86|, s95, 1.0
	v_pk_mul_f32 v[90:91], v[90:91], v[42:43]
	v_add_f32_e32 v85, v218, v81
	v_add_u32_e32 v81, 0x8800, v220
	v_mul_f32_e32 v82, v90, v82
	v_add_u32_e32 v96, v222, v81
	v_cvt_pk_bf16_f32 v82, v82, s0
	ds_write_b16 v96, v82
	v_mul_f32_e32 v82, 0.5, v83
	v_rcp_f32_e32 v83, v87
	v_mul_f32_e64 v88, |v86|, -|v86|
	v_fmamk_f32 v87, v83, 0x3f87dc22, v206
	v_mul_f32_e32 v88, 0x3fb8aa3b, v88
	v_fmaak_f32 v87, v87, v83, 0x3fb5f0e3
	v_exp_f32_e32 v88, v88
	v_fmaak_f32 v87, v87, v83, 0xbe91a98e
	v_fmaak_f32 v87, v87, v83, 0x3e827906
; __device__ __forceinline__ u16 f2bf(float f) { return (u16)(pack2(f, f) & 0xffffu); }
; __device__ __forceinline__ float erf_f32(float x) {
;   const float ax = fabsf(x);
;   const float t = __frcp_rn(fmaf(0.3275911f, ax, 1.0f));
;   float poly = fmaf(1.061405429f, t, -1.453152027f);
;   poly = fmaf(poly, t, 1.421413741f);
;   poly = fmaf(poly, t, -0.284496736f);
;   poly = fmaf(poly, t, 0.254829592f);
;   const float y = 1.0f - poly * t * __expf(-ax * ax);
;   return copysignf(y, x);
; }
; __device__ __forceinline__ float gelu_exact(float x) { return 0.5f * x * (1.0f + erf_f32(x * 0.70710678118654752f)); }
; template <int EPI>
; __device__ __forceinline__ void phase_gemm(const Params& p, const GemmDesc& d, char* shmc) {
;     ...
; #pragma unroll
;       for (int n = 0; n < 2; ++n) {
;         const int col = ewc * 32 + n * 16 + efr;
;         const int ch = ch0 + col;
;         const float w0 = cw[n][0], w1 = cw[n][1], w2 = cw[n][2], cb = cw[n][3];
; #pragma unroll
;         for (int ai = 0; ai < 2; ++ai)
; #pragma unroll
;           for (int m = 0; m < 4; ++m) {
;             const int s = ai * 32 + ewr * 16 + m * 4 + efq;
;             const f32x4 g = acc[ai][0][m][n];
;             const f32x4 v = acc[ai][1][m][n];
;             const float c0 = w0 * gp[ai][m][n] + w1 * g[0] + w2 * g[1] + cb;
;             const float c1 = w0 * g[0] + w1 * g[1] + w2 * g[2] + cb;
;             const float c2 = w0 * g[1] + w1 * g[2] + w2 * g[3] + cb;
;             const float c3 = w0 * g[2] + w1 * g[3] + w2 * gn[ai][m][n] + cb;
;             u16* sp = stg + (s * 4) * 136 + col;
;             sp[0] = f2bf(gelu_exact(c0) * v[0]);
;             sp[136] = f2bf(gelu_exact(c1) * v[1]);
;             sp[272] = f2bf(gelu_exact(c2) * v[2]);
;             sp[408] = f2bf(gelu_exact(c3) * v[3]);
;             if (s == 0) {
;               edge[0 * DFF + ch] = c0; edge[1 * DFF + ch] = g[0]; edge[2 * DFF + ch] = v[0];
;             }
;             if (s == 63) {
;               edge[3 * DFF + ch] = c3; edge[4 * DFF + ch] = g[3]; edge[5 * DFF + ch] = v[3];
;             }
;           }
	v_mul_f32_e32 v83, v83, v87
	v_fma_f32 v83, -v88, v83, 1.0
	v_bfi_b32 v83, s96, v83, v86
	v_add_f32_e32 v83, 1.0, v83
	v_mul_f32_e32 v82, v82, v83
	v_mul_f32_e32 v83, 0x3f3504f3, v84
	v_fma_f32 v86, |v83|, s95, 1.0
	v_mul_f32_e32 v82, v91, v82
	v_cvt_pk_bf16_f32 v82, v82, s0
	ds_write_b16 v96, v82 offset:272
	v_mul_f32_e32 v82, 0.5, v84
	v_rcp_f32_e32 v84, v86
	v_mul_f32_e64 v87, |v83|, -|v83|
	v_fmamk_f32 v86, v84, 0x3f87dc22, v206
	v_mul_f32_e32 v87, 0x3fb8aa3b, v87
	v_fmaak_f32 v86, v86, v84, 0x3fb5f0e3
	v_exp_f32_e32 v87, v87
	v_fmaak_f32 v86, v86, v84, 0xbe91a98e
	v_fmaak_f32 v86, v86, v84, 0x3e827906
	v_mul_f32_e32 v84, v84, v86
	v_fma_f32 v84, -v87, v84, 1.0
	v_bfi_b32 v83, s96, v84, v83
	v_add_f32_e32 v83, 1.0, v83
	v_mul_f32_e32 v82, v82, v83
	v_mul_f32_e32 v83, 0x3f3504f3, v85
	v_fma_f32 v84, |v83|, s95, 1.0
	v_pk_mul_f32 v[92:93], v[92:93], v[44:45]
	s_nop 0
	v_mul_f32_e32 v82, v92, v82
	v_cvt_pk_bf16_f32 v82, v82, s0
	ds_write_b16 v96, v82 offset:544
	v_mul_f32_e32 v82, 0.5, v85
	v_rcp_f32_e32 v84, v84
	v_mul_f32_e64 v86, |v83|, -|v83|
	v_fmamk_f32 v85, v84, 0x3f87dc22, v206
	v_mul_f32_e32 v86, 0x3fb8aa3b, v86
	v_fmaak_f32 v85, v85, v84, 0x3fb5f0e3
	v_exp_f32_e32 v86, v86
	v_fmaak_f32 v85, v85, v84, 0xbe91a98e
	v_fmaak_f32 v85, v85, v84, 0x3e827906
	v_mul_f32_e32 v84, v84, v85
	v_fma_f32 v84, -v86, v84, 1.0
	v_bfi_b32 v83, s96, v84, v83
	v_add_f32_e32 v83, 1.0, v83
	v_mul_f32_e32 v82, v82, v83
	v_mul_f32_e32 v82, v93, v82
	v_cvt_pk_bf16_f32 v82, v82, s0
	ds_write_b16 v96, v82 offset:816
	v_mul_f32_e32 v82, v215, v116
	v_fmac_f32_e32 v82, v217, v180
	v_fmac_f32_e32 v82, v216, v181
	v_add_f32_e32 v83, v218, v82
	v_mul_f32_e32 v87, 0x3f3504f3, v83
	v_fma_f32 v88, |v87|, s95, 1.0
	v_mul_f32_e32 v82, v217, v181
	v_fmac_f32_e32 v82, v215, v180
	v_fmac_f32_e32 v82, v216, v178
	v_rcp_f32_e32 v88, v88
	v_mul_f32_e64 v90, |v87|, -|v87|
	v_fmamk_f32 v89, v88, 0x3f87dc22, v206
	v_mul_f32_e32 v90, 0x3fb8aa3b, v90
	v_fmaak_f32 v89, v89, v88, 0x3fb5f0e3
	v_exp_f32_e32 v90, v90
	v_fmaak_f32 v89, v89, v88, 0xbe91a98e
	v_fmaak_f32 v89, v89, v88, 0x3e827906
	v_mul_f32_e32 v88, v88, v89
	v_fma_f32 v88, -v90, v88, 1.0
	v_bfi_b32 v87, s96, v88, v87
	v_mul_f32_e32 v83, 0.5, v83
	v_add_f32_e32 v87, 1.0, v87
	v_add_f32_e32 v84, v218, v82
	v_mul_f32_e32 v82, v217, v178
	v_mul_f32_e32 v83, v83, v87
	v_fmac_f32_e32 v82, v215, v181
	v_mul_f32_e32 v76, v76, v83
	v_mul_f32_e32 v83, 0x3f3504f3, v84
	v_fmac_f32_e32 v82, v216, v179
	v_fma_f32 v87, |v83|, s95, 1.0
	v_add_f32_e32 v85, v218, v82
	v_mul_f32_e32 v82, v217, v179
	v_fmac_f32_e32 v82, v215, v178
	v_fmac_f32_e32 v82, v216, v114
	v_add_f32_e32 v86, v218, v82
	v_add_u32_e32 v82, 0x9900, v220
	v_add_u32_e32 v91, v222, v82
	v_cvt_pk_bf16_f32 v76, v76, s0
	ds_write_b16 v91, v76
	v_mul_f32_e32 v76, 0.5, v84
	v_rcp_f32_e32 v84, v87
	v_mul_f32_e64 v88, |v83|, -|v83|
	v_fmamk_f32 v87, v84, 0x3f87dc22, v206
	v_mul_f32_e32 v88, 0x3fb8aa3b, v88
	v_fmaak_f32 v87, v87, v84, 0x3fb5f0e3
	v_exp_f32_e32 v88, v88
	v_fmaak_f32 v87, v87, v84, 0xbe91a98e
	v_fmaak_f32 v87, v87, v84, 0x3e827906
	v_mul_f32_e32 v84, v84, v87
	v_fma_f32 v84, -v88, v84, 1.0
	v_bfi_b32 v83, s96, v84, v83
	v_add_f32_e32 v83, 1.0, v83
	v_mul_f32_e32 v76, v76, v83
	v_mul_f32_e32 v76, v77, v76
	v_mul_f32_e32 v77, 0x3f3504f3, v85
	v_fma_f32 v83, |v77|, s95, 1.0
	v_cvt_pk_bf16_f32 v76, v76, s0
	ds_write_b16 v91, v76 offset:272
	v_mul_f32_e32 v76, 0.5, v85
	v_rcp_f32_e32 v83, v83
	v_mul_f32_e64 v85, |v77|, -|v77|
	v_fmamk_f32 v84, v83, 0x3f87dc22, v206
	v_mul_f32_e32 v85, 0x3fb8aa3b, v85
	v_fmaak_f32 v84, v84, v83, 0x3fb5f0e3
	v_exp_f32_e32 v85, v85
	v_fmaak_f32 v84, v84, v83, 0xbe91a98e
	v_fmaak_f32 v84, v84, v83, 0x3e827906
	v_mul_f32_e32 v83, v83, v84
	v_fma_f32 v83, -v85, v83, 1.0
	v_bfi_b32 v77, s96, v83, v77
	v_add_f32_e32 v77, 1.0, v77
	v_mul_f32_e32 v76, v76, v77
	v_mul_f32_e32 v74, v74, v76
	v_mul_f32_e32 v76, 0x3f3504f3, v86
	v_fma_f32 v77, |v76|, s95, 1.0
	v_cvt_pk_bf16_f32 v74, v74, s0
	ds_write_b16 v91, v74 offset:544
	v_mul_f32_e32 v74, 0.5, v86
	v_rcp_f32_e32 v77, v77
	v_mul_f32_e64 v84, |v76|, -|v76|
	v_fmamk_f32 v83, v77, 0x3f87dc22, v206
	v_mul_f32_e32 v84, 0x3fb8aa3b, v84
	v_fmaak_f32 v83, v83, v77, 0x3fb5f0e3
	v_exp_f32_e32 v84, v84
	v_fmaak_f32 v83, v83, v77, 0xbe91a98e
	v_fmaak_f32 v83, v83, v77, 0x3e827906
	v_mul_f32_e32 v77, v77, v83
	v_fma_f32 v77, -v84, v77, 1.0
	v_bfi_b32 v76, s96, v77, v76
	v_add_f32_e32 v76, 1.0, v76
	v_mul_f32_e32 v74, v74, v76
	v_mul_f32_e32 v74, v75, v74
	v_cvt_pk_bf16_f32 v74, v74, s0
	ds_write_b16 v91, v74 offset:816
	v_mul_f32_e32 v74, v215, v108
	v_fmac_f32_e32 v74, v217, v160
	v_fmac_f32_e32 v74, v216, v161
	v_add_f32_e32 v75, v218, v74
	v_mul_f32_e32 v84, 0x3f3504f3, v75
	v_fma_f32 v85, |v84|, s95, 1.0
	v_mul_f32_e32 v74, v217, v161
	v_fmac_f32_e32 v74, v215, v160
	v_fmac_f32_e32 v74, v216, v156
	v_rcp_f32_e32 v85, v85
	v_mul_f32_e64 v87, |v84|, -|v84|
	v_fmamk_f32 v86, v85, 0x3f87dc22, v206
	v_mul_f32_e32 v87, 0x3fb8aa3b, v87
	v_fmaak_f32 v86, v86, v85, 0x3fb5f0e3
	v_exp_f32_e32 v87, v87
	v_fmaak_f32 v86, v86, v85, 0xbe91a98e
	v_fmaak_f32 v86, v86, v85, 0x3e827906
	v_mul_f32_e32 v85, v85, v86
	v_fma_f32 v85, -v87, v85, 1.0
	v_bfi_b32 v84, s96, v85, v84
	v_mul_f32_e32 v75, 0.5, v75
	v_add_f32_e32 v84, 1.0, v84
	v_add_f32_e32 v76, v218, v74
	v_mul_f32_e32 v74, v217, v156
	v_mul_f32_e32 v75, v75, v84
	v_fmac_f32_e32 v74, v215, v161
	v_mul_f32_e32 v72, v72, v75
	v_mul_f32_e32 v75, 0x3f3504f3, v76
	v_fmac_f32_e32 v74, v216, v157
	v_fma_f32 v84, |v75|, s95, 1.0
	v_add_f32_e32 v77, v218, v74
	v_mul_f32_e32 v74, v217, v157
	v_fmac_f32_e32 v74, v215, v156
	v_fmac_f32_e32 v74, v216, v106
	v_add_f32_e32 v83, v218, v74
; __device__ __forceinline__ u16 f2bf(float f) { return (u16)(pack2(f, f) & 0xffffu); }
; __device__ __forceinline__ float erf_f32(float x) {
;   const float ax = fabsf(x);
;   const float t = __frcp_rn(fmaf(0.3275911f, ax, 1.0f));
;   float poly = fmaf(1.061405429f, t, -1.453152027f);
;   poly = fmaf(poly, t, 1.421413741f);
;   poly = fmaf(poly, t, -0.284496736f);
;   poly = fmaf(poly, t, 0.254829592f);
;   const float y = 1.0f - poly * t * __expf(-ax * ax);
;   return copysignf(y, x);
; }
; __device__ __forceinline__ float gelu_exact(float x) { return 0.5f * x * (1.0f + erf_f32(x * 0.70710678118654752f)); }
; template <int EPI>
; __device__ __forceinline__ void phase_gemm(const Params& p, const GemmDesc& d, char* shmc) {
;     ...
; #pragma unroll
;       for (int n = 0; n < 2; ++n) {
;         const int col = ewc * 32 + n * 16 + efr;
;         const int ch = ch0 + col;
;         const float w0 = cw[n][0], w1 = cw[n][1], w2 = cw[n][2], cb = cw[n][3];
; #pragma unroll
;         for (int ai = 0; ai < 2; ++ai)
; #pragma unroll
;           for (int m = 0; m < 4; ++m) {
;             const int s = ai * 32 + ewr * 16 + m * 4 + efq;
;             const f32x4 g = acc[ai][0][m][n];
;             const f32x4 v = acc[ai][1][m][n];
;             const float c0 = w0 * gp[ai][m][n] + w1 * g[0] + w2 * g[1] + cb;
;             const float c1 = w0 * g[0] + w1 * g[1] + w2 * g[2] + cb;
;             const float c2 = w0 * g[1] + w1 * g[2] + w2 * g[3] + cb;
;             const float c3 = w0 * g[2] + w1 * g[3] + w2 * gn[ai][m][n] + cb;
;             u16* sp = stg + (s * 4) * 136 + col;
;             sp[0] = f2bf(gelu_exact(c0) * v[0]);
;             sp[136] = f2bf(gelu_exact(c1) * v[1]);
;             sp[272] = f2bf(gelu_exact(c2) * v[2]);
;             sp[408] = f2bf(gelu_exact(c3) * v[3]);
;             if (s == 0) {
;               edge[0 * DFF + ch] = c0; edge[1 * DFF + ch] = g[0]; edge[2 * DFF + ch] = v[0];
;             }
;             if (s == 63) {
;               edge[3 * DFF + ch] = c3; edge[4 * DFF + ch] = g[3]; edge[5 * DFF + ch] = v[3];
;             }
;           }
	v_add_u32_e32 v74, 0xaa00, v220
	v_add_u32_e32 v88, v222, v74
	v_cvt_pk_bf16_f32 v72, v72, s0
	ds_write_b16 v88, v72
	v_mul_f32_e32 v72, 0.5, v76
	v_rcp_f32_e32 v76, v84
	v_mul_f32_e64 v85, |v75|, -|v75|
	v_fmamk_f32 v84, v76, 0x3f87dc22, v206
	v_mul_f32_e32 v85, 0x3fb8aa3b, v85
	v_fmaak_f32 v84, v84, v76, 0x3fb5f0e3
	v_exp_f32_e32 v85, v85
	v_fmaak_f32 v84, v84, v76, 0xbe91a98e
	v_fmaak_f32 v84, v84, v76, 0x3e827906
	v_mul_f32_e32 v76, v76, v84
	v_fma_f32 v76, -v85, v76, 1.0
	v_bfi_b32 v75, s96, v76, v75
	v_add_f32_e32 v75, 1.0, v75
	v_mul_f32_e32 v72, v72, v75
	v_mul_f32_e32 v72, v73, v72
	v_mul_f32_e32 v73, 0x3f3504f3, v77
	v_fma_f32 v75, |v73|, s95, 1.0
	v_cvt_pk_bf16_f32 v72, v72, s0
	ds_write_b16 v88, v72 offset:272
	v_mul_f32_e32 v72, 0.5, v77
	v_rcp_f32_e32 v75, v75
	v_mul_f32_e64 v77, |v73|, -|v73|
	v_fmamk_f32 v76, v75, 0x3f87dc22, v206
	v_mul_f32_e32 v77, 0x3fb8aa3b, v77
	v_fmaak_f32 v76, v76, v75, 0x3fb5f0e3
	v_exp_f32_e32 v77, v77
	v_fmaak_f32 v76, v76, v75, 0xbe91a98e
	v_fmaak_f32 v76, v76, v75, 0x3e827906
	v_mul_f32_e32 v75, v75, v76
	v_fma_f32 v75, -v77, v75, 1.0
	v_bfi_b32 v73, s96, v75, v73
	v_add_f32_e32 v73, 1.0, v73
	v_mul_f32_e32 v72, v72, v73
	v_mul_f32_e32 v70, v70, v72
	v_mul_f32_e32 v72, 0x3f3504f3, v83
	v_fma_f32 v73, |v72|, s95, 1.0
	v_cvt_pk_bf16_f32 v70, v70, s0
	ds_write_b16 v88, v70 offset:544
	v_mul_f32_e32 v70, 0.5, v83
	v_rcp_f32_e32 v73, v73
	v_mul_f32_e64 v76, |v72|, -|v72|
	v_fmamk_f32 v75, v73, 0x3f87dc22, v206
	v_mul_f32_e32 v76, 0x3fb8aa3b, v76
	v_fmaak_f32 v75, v75, v73, 0x3fb5f0e3
	v_exp_f32_e32 v76, v76
	v_fmaak_f32 v75, v75, v73, 0xbe91a98e
	v_fmaak_f32 v75, v75, v73, 0x3e827906
	v_mul_f32_e32 v73, v73, v75
	v_fma_f32 v73, -v76, v73, 1.0
	v_bfi_b32 v72, s96, v73, v72
	v_add_f32_e32 v72, 1.0, v72
	v_mul_f32_e32 v70, v70, v72
	v_mul_f32_e32 v70, v71, v70
	v_cvt_pk_bf16_f32 v70, v70, s0
	ds_write_b16 v88, v70 offset:816
	s_waitcnt lgkmcnt(14)
	v_mul_f32_e32 v70, v215, v221
	v_fmac_f32_e32 v70, v217, v154
	v_fmac_f32_e32 v70, v216, v155
	v_add_f32_e32 v72, v218, v70
	v_mul_f32_e32 v76, 0x3f3504f3, v72
	v_fma_f32 v77, |v76|, s95, 1.0
	v_mul_f32_e32 v70, v217, v155
	v_fmac_f32_e32 v70, v215, v154
	v_fmac_f32_e32 v70, v216, v152
	v_rcp_f32_e32 v77, v77
	v_mul_f32_e64 v84, |v76|, -|v76|
	v_fmamk_f32 v83, v77, 0x3f87dc22, v206
	v_mul_f32_e32 v84, 0x3fb8aa3b, v84
	v_fmaak_f32 v83, v83, v77, 0x3fb5f0e3
	v_exp_f32_e32 v84, v84
	v_fmaak_f32 v83, v83, v77, 0xbe91a98e
	v_fmaak_f32 v83, v83, v77, 0x3e827906
	v_mul_f32_e32 v77, v77, v83
	v_fma_f32 v77, -v84, v77, 1.0
	v_bfi_b32 v76, s96, v77, v76
	v_mul_f32_e32 v72, 0.5, v72
	v_add_f32_e32 v76, 1.0, v76
	v_add_f32_e32 v73, v218, v70
	v_mul_f32_e32 v70, v217, v152
	v_mul_f32_e32 v72, v72, v76
	v_fmac_f32_e32 v70, v215, v155
	v_mul_f32_e32 v68, v68, v72
	v_mul_f32_e32 v72, 0x3f3504f3, v73
	v_fmac_f32_e32 v70, v216, v153
	v_fma_f32 v76, |v72|, s95, 1.0
	v_add_f32_e32 v75, v218, v70
	v_mul_f32_e32 v70, v217, v153
	v_fmac_f32_e32 v70, v215, v152
	v_fmac_f32_e32 v70, v216, v219
	v_add_f32_e32 v71, v218, v70
	v_add_u32_e32 v70, 0xbb00, v220
	v_add_u32_e32 v85, v222, v70
	v_cvt_pk_bf16_f32 v68, v68, s0
	ds_write_b16 v85, v68
	v_mul_f32_e32 v68, 0.5, v73
	v_rcp_f32_e32 v73, v76
	v_mul_f32_e64 v77, |v72|, -|v72|
	v_fmamk_f32 v76, v73, 0x3f87dc22, v206
	v_mul_f32_e32 v77, 0x3fb8aa3b, v77
	v_fmaak_f32 v76, v76, v73, 0x3fb5f0e3
	v_exp_f32_e32 v77, v77
	v_fmaak_f32 v76, v76, v73, 0xbe91a98e
	v_fmaak_f32 v76, v76, v73, 0x3e827906
	v_mul_f32_e32 v73, v73, v76
	v_fma_f32 v73, -v77, v73, 1.0
	v_bfi_b32 v72, s96, v73, v72
	v_add_f32_e32 v72, 1.0, v72
	v_mul_f32_e32 v68, v68, v72
	v_mul_f32_e32 v68, v69, v68
	v_mul_f32_e32 v69, 0x3f3504f3, v75
	v_fma_f32 v72, |v69|, s95, 1.0
	v_cvt_pk_bf16_f32 v68, v68, s0
	ds_write_b16 v85, v68 offset:272
	v_mul_f32_e32 v68, 0.5, v75
	v_rcp_f32_e32 v72, v72
	v_mul_f32_e64 v75, |v69|, -|v69|
	v_fmamk_f32 v73, v72, 0x3f87dc22, v206
	v_mul_f32_e32 v75, 0x3fb8aa3b, v75
	v_fmaak_f32 v73, v73, v72, 0x3fb5f0e3
	v_exp_f32_e32 v75, v75
	v_fmaak_f32 v73, v73, v72, 0xbe91a98e
	v_fmaak_f32 v73, v73, v72, 0x3e827906
	v_mul_f32_e32 v72, v72, v73
	v_fma_f32 v72, -v75, v72, 1.0
	v_bfi_b32 v69, s96, v72, v69
	v_add_f32_e32 v69, 1.0, v69
	v_mul_f32_e32 v68, v68, v69
	v_mul_f32_e32 v66, v66, v68
	v_mul_f32_e32 v68, 0x3f3504f3, v71
	v_fma_f32 v69, |v68|, s95, 1.0
	v_cvt_pk_bf16_f32 v66, v66, s0
	ds_write_b16 v85, v66 offset:544
	v_mul_f32_e32 v66, 0.5, v71
	v_rcp_f32_e32 v69, v69
	v_mul_f32_e64 v73, |v68|, -|v68|
	v_fmamk_f32 v72, v69, 0x3f87dc22, v206
	v_mul_f32_e32 v73, 0x3fb8aa3b, v73
	v_fmaak_f32 v72, v72, v69, 0x3fb5f0e3
	v_exp_f32_e32 v73, v73
	v_fmaak_f32 v72, v72, v69, 0xbe91a98e
	v_fmaak_f32 v72, v72, v69, 0x3e827906
	v_mul_f32_e32 v69, v69, v72
	v_fma_f32 v69, -v73, v69, 1.0
	v_bfi_b32 v68, s96, v69, v68
	v_add_f32_e32 v68, 1.0, v68
	v_mul_f32_e32 v66, v66, v68
	v_mul_f32_e32 v66, v67, v66
	v_cvt_pk_bf16_f32 v66, v66, s0
	ds_write_b16 v85, v66 offset:816
	s_and_saveexec_b64 s[78:79], s[8:9]
	s_cbranch_execz .LBB0_311
	v_add_co_u32_e32 v68, vcc, 0x10000, v94
	s_nop 1
	v_addc_co_u32_e32 v69, vcc, 0, v95, vcc
	global_store_dword v[68:69], v71, off offset:2048
	v_add_co_u32_e32 v68, vcc, 0x16000, v94
	s_nop 1
	v_addc_co_u32_e32 v69, vcc, 0, v95, vcc
	global_store_dword v[68:69], v153, off
	v_add_co_u32_e32 v68, vcc, 0x1b000, v94
	s_nop 1
	v_addc_co_u32_e32 v69, vcc, 0, v95, vcc
	global_store_dword v[68:69], v67, off offset:2048
; __device__ __forceinline__ u16 f2bf(float f) { return (u16)(pack2(f, f) & 0xffffu); }
; __device__ __forceinline__ float erf_f32(float x) {
;   const float ax = fabsf(x);
;   const float t = __frcp_rn(fmaf(0.3275911f, ax, 1.0f));
;   float poly = fmaf(1.061405429f, t, -1.453152027f);
;   poly = fmaf(poly, t, 1.421413741f);
;   poly = fmaf(poly, t, -0.284496736f);
;   poly = fmaf(poly, t, 0.254829592f);
;   const float y = 1.0f - poly * t * __expf(-ax * ax);
;   return copysignf(y, x);
; }
; __device__ __forceinline__ float gelu_exact(float x) { return 0.5f * x * (1.0f + erf_f32(x * 0.70710678118654752f)); }
; template <int EPI>
; __device__ __forceinline__ void phase_gemm(const Params& p, const GemmDesc& d, char* shmc) {
;     ...
; #pragma unroll
;       for (int n = 0; n < 2; ++n) {
;         const int col = ewc * 32 + n * 16 + efr;
;         const int ch = ch0 + col;
;         const float w0 = cw[n][0], w1 = cw[n][1], w2 = cw[n][2], cb = cw[n][3];
; #pragma unroll
;         for (int ai = 0; ai < 2; ++ai)
; #pragma unroll
;           for (int m = 0; m < 4; ++m) {
;             const int s = ai * 32 + ewr * 16 + m * 4 + efq;
;             const f32x4 g = acc[ai][0][m][n];
;             const f32x4 v = acc[ai][1][m][n];
;             const float c0 = w0 * gp[ai][m][n] + w1 * g[0] + w2 * g[1] + cb;
;             const float c1 = w0 * g[0] + w1 * g[1] + w2 * g[2] + cb;
;             const float c2 = w0 * g[1] + w1 * g[2] + w2 * g[3] + cb;
;             const float c3 = w0 * g[2] + w1 * g[3] + w2 * gn[ai][m][n] + cb;
;             u16* sp = stg + (s * 4) * 136 + col;
;             sp[0] = f2bf(gelu_exact(c0) * v[0]);
;             sp[136] = f2bf(gelu_exact(c1) * v[1]);
;             sp[272] = f2bf(gelu_exact(c2) * v[2]);
;             sp[408] = f2bf(gelu_exact(c3) * v[3]);
;             if (s == 0) {
;               edge[0 * DFF + ch] = c0; edge[1 * DFF + ch] = g[0]; edge[2 * DFF + ch] = v[0];
;             }
;             if (s == 63) {
;               edge[3 * DFF + ch] = c3; edge[4 * DFF + ch] = g[3]; edge[5 * DFF + ch] = v[3];
;             }
;           }
.LBB0_311:
	s_or_b64 exec, exec, s[78:79]
	v_pk_mul_f32 v[64:65], v[60:61], v[64:65]
	v_pk_mul_f32 v[60:61], v[58:59], v[62:63]
	v_mul_f32_e32 v62, v209, v213
	v_fmac_f32_e32 v62, v210, v146
	v_fmac_f32_e32 v62, v208, v147
	v_add_f32_e32 v63, v207, v62
	v_mul_f32_e32 v71, 0x3f3504f3, v63
	v_fma_f32 v72, |v71|, s95, 1.0
	v_mul_f32_e32 v62, v210, v147
	v_fmac_f32_e32 v62, v209, v146
	v_fmac_f32_e32 v62, v208, v158
	v_rcp_f32_e32 v72, v72
	v_mul_f32_e64 v75, |v71|, -|v71|
	v_fmamk_f32 v73, v72, 0x3f87dc22, v206
	v_mul_f32_e32 v75, 0x3fb8aa3b, v75
	v_fmaak_f32 v73, v73, v72, 0x3fb5f0e3
	v_exp_f32_e32 v75, v75
	v_fmaak_f32 v73, v73, v72, 0xbe91a98e
	v_fmaak_f32 v73, v73, v72, 0x3e827906
	v_mul_f32_e32 v72, v72, v73
	v_add_f32_e32 v67, v207, v62
	v_mul_f32_e32 v62, v210, v158
	v_fma_f32 v72, -v75, v72, 1.0
	v_fmac_f32_e32 v62, v209, v147
	v_bfi_b32 v71, s96, v72, v71
	v_mul_f32_e32 v72, 0x3f3504f3, v67
	v_fmac_f32_e32 v62, v208, v159
	v_fma_f32 v73, |v72|, s95, 1.0
	v_add_f32_e32 v68, v207, v62
	v_mul_f32_e32 v62, v210, v159
	v_mul_f32_e32 v76, 0.5, v63
	v_add_f32_e32 v71, 1.0, v71
	v_fmac_f32_e32 v62, v209, v158
	v_mul_f32_e32 v71, v76, v71
	v_or_b32_e32 v66, 16, v162
	v_fmac_f32_e32 v62, v208, v214
	v_add_f32_e32 v69, v207, v62
	v_lshlrev_b32_e32 v62, 1, v66
	v_mul_f32_e32 v71, v60, v71
	v_add3_u32 v66, s14, v220, v62
	v_cvt_pk_bf16_f32 v71, v71, s0
	ds_write_b16 v66, v71
	v_rcp_f32_e32 v71, v73
	v_mul_f32_e64 v75, |v72|, -|v72|
	v_fmamk_f32 v73, v71, 0x3f87dc22, v206
	v_mul_f32_e32 v75, 0x3fb8aa3b, v75
	v_fmaak_f32 v73, v73, v71, 0x3fb5f0e3
	v_exp_f32_e32 v75, v75
	v_fmaak_f32 v73, v73, v71, 0xbe91a98e
	v_fmaak_f32 v73, v73, v71, 0x3e827906
	v_mul_f32_e32 v71, v71, v73
	v_fma_f32 v71, -v75, v71, 1.0
	v_bfi_b32 v71, s96, v71, v72
	v_mul_f32_e32 v67, 0.5, v67
	v_add_f32_e32 v71, 1.0, v71
	v_mul_f32_e32 v67, v67, v71
	v_mul_f32_e32 v61, v61, v67
	v_mul_f32_e32 v67, 0x3f3504f3, v68
	v_fma_f32 v71, |v67|, s95, 1.0
	v_cvt_pk_bf16_f32 v61, v61, s0
	ds_write_b16 v66, v61 offset:272
	v_mul_f32_e32 v61, 0.5, v68
	v_rcp_f32_e32 v68, v71
	v_mul_f32_e64 v72, |v67|, -|v67|
	v_fmamk_f32 v71, v68, 0x3f87dc22, v206
	v_mul_f32_e32 v72, 0x3fb8aa3b, v72
	v_fmaak_f32 v71, v71, v68, 0x3fb5f0e3
	v_exp_f32_e32 v72, v72
	v_fmaak_f32 v71, v71, v68, 0xbe91a98e
	v_fmaak_f32 v71, v71, v68, 0x3e827906
	v_mul_f32_e32 v68, v68, v71
	v_fma_f32 v68, -v72, v68, 1.0
	v_bfi_b32 v67, s96, v68, v67
	v_add_f32_e32 v67, 1.0, v67
	v_mul_f32_e32 v61, v61, v67
	v_mul_f32_e32 v61, v64, v61
	v_mul_f32_e32 v64, 0x3f3504f3, v69
	v_fma_f32 v67, |v64|, s95, 1.0
	v_cvt_pk_bf16_f32 v61, v61, s0
	ds_write_b16 v66, v61 offset:544
	v_mul_f32_e32 v61, 0.5, v69
	v_rcp_f32_e32 v67, v67
	v_mul_f32_e64 v69, |v64|, -|v64|
	v_fmamk_f32 v68, v67, 0x3f87dc22, v206
	v_mul_f32_e32 v69, 0x3fb8aa3b, v69
	v_fmaak_f32 v68, v68, v67, 0x3fb5f0e3
	v_exp_f32_e32 v69, v69
	v_fmaak_f32 v68, v68, v67, 0xbe91a98e
	v_fmaak_f32 v68, v68, v67, 0x3e827906
	v_mul_f32_e32 v67, v67, v68
	v_fma_f32 v67, -v69, v67, 1.0
	v_bfi_b32 v64, s96, v67, v64
	s_ashr_i32 s63, s62, 31
	v_add_f32_e32 v64, 1.0, v64
	v_lshl_add_u64 v[58:59], v[162:163], 0, s[62:63]
	v_mul_f32_e32 v61, v61, v64
	v_lshl_add_u64 v[58:59], v[58:59], 2, s[64:65]
	v_mul_f32_e32 v61, v65, v61
	v_lshl_add_u64 v[58:59], v[58:59], 0, 64
	v_cvt_pk_bf16_f32 v61, v61, s0
	ds_write_b16 v66, v61 offset:816
	s_and_saveexec_b64 s[64:65], s[10:11]
	s_cbranch_execz .LBB0_313
	v_add_co_u32_e32 v64, vcc, 0x5000, v58
	global_store_dword v[58:59], v63, off
	s_nop 0
	v_addc_co_u32_e32 v65, vcc, 0, v59, vcc
	global_store_dword v[64:65], v146, off offset:2048
	v_add_co_u32_e32 v64, vcc, 0xb000, v58
	s_nop 1
	v_addc_co_u32_e32 v65, vcc, 0, v59, vcc
	global_store_dword v[64:65], v60, off
.LBB0_313:
	s_or_b64 exec, exec, s[64:65]
	v_pk_mul_f32 v[48:49], v[4:5], v[48:49]
	v_pk_mul_f32 v[4:5], v[14:15], v[30:31]
	v_mul_f32_e32 v14, v209, v151
	v_fmac_f32_e32 v14, v210, v144
	v_fmac_f32_e32 v14, v208, v145
	v_add_f32_e32 v14, v207, v14
	v_pk_mul_f32 v[52:53], v[8:9], v[52:53]
	v_pk_mul_f32 v[8:9], v[18:19], v[34:35]
	v_mul_f32_e32 v18, 0x3f3504f3, v14
	v_fma_f32 v19, |v18|, s95, 1.0
	v_pk_mul_f32 v[50:51], v[6:7], v[50:51]
	v_pk_mul_f32 v[6:7], v[20:21], v[36:37]
	v_pk_mul_f32 v[56:57], v[12:13], v[56:57]
	v_pk_mul_f32 v[12:13], v[22:23], v[38:39]
	v_pk_mul_f32 v[54:55], v[10:11], v[54:55]
	v_pk_mul_f32 v[10:11], v[24:25], v[40:41]
	v_rcp_f32_e32 v19, v19
	v_mul_f32_e64 v21, |v18|, -|v18|
	v_fmamk_f32 v20, v19, 0x3f87dc22, v206
	v_mul_f32_e32 v21, 0x3fb8aa3b, v21
	v_fmaak_f32 v20, v20, v19, 0x3fb5f0e3
	v_exp_f32_e32 v21, v21
	v_fmaak_f32 v20, v20, v19, 0xbe91a98e
	v_fmaak_f32 v20, v20, v19, 0x3e827906
	v_mul_f32_e32 v15, v210, v145
	v_mul_f32_e32 v19, v19, v20
	v_fmac_f32_e32 v15, v209, v144
	v_fma_f32 v19, -v21, v19, 1.0
	v_fmac_f32_e32 v15, v208, v142
	v_bfi_b32 v18, s96, v19, v18
	v_add_f32_e32 v15, v207, v15
	v_mul_f32_e32 v14, 0.5, v14
	v_add_f32_e32 v18, 1.0, v18
	v_mul_f32_e32 v14, v14, v18
	v_mul_f32_e32 v18, 0x3f3504f3, v15
	v_fma_f32 v19, |v18|, s95, 1.0
	v_mul_f32_e32 v14, v54, v14
	v_add3_u32 v22, s14, v78, v62
	v_cvt_pk_bf16_f32 v14, v14, s0
	ds_write_b16 v22, v14
	v_mul_f32_e32 v14, 0.5, v15
	v_rcp_f32_e32 v15, v19
	v_mul_f32_e64 v20, |v18|, -|v18|
	v_fmamk_f32 v19, v15, 0x3f87dc22, v206
	v_mul_f32_e32 v20, 0x3fb8aa3b, v20
	v_fmaak_f32 v19, v19, v15, 0x3fb5f0e3
	v_exp_f32_e32 v20, v20
	v_fmaak_f32 v19, v19, v15, 0xbe91a98e
	v_fmaak_f32 v19, v19, v15, 0x3e827906
	v_pk_mul_f32 v[46:47], v[2:3], v[46:47]
	v_pk_mul_f32 v[2:3], v[16:17], v[32:33]
	v_mul_f32_e32 v16, v210, v142
	v_mul_f32_e32 v15, v15, v19
	v_fmac_f32_e32 v16, v209, v145
	v_fma_f32 v15, -v20, v15, 1.0
; __device__ __forceinline__ u16 f2bf(float f) { return (u16)(pack2(f, f) & 0xffffu); }
; __device__ __forceinline__ float erf_f32(float x) {
;   const float ax = fabsf(x);
;   const float t = __frcp_rn(fmaf(0.3275911f, ax, 1.0f));
;   float poly = fmaf(1.061405429f, t, -1.453152027f);
;   poly = fmaf(poly, t, 1.421413741f);
;   poly = fmaf(poly, t, -0.284496736f);
;   poly = fmaf(poly, t, 0.254829592f);
;   const float y = 1.0f - poly * t * __expf(-ax * ax);
;   return copysignf(y, x);
; }
; __device__ __forceinline__ float gelu_exact(float x) { return 0.5f * x * (1.0f + erf_f32(x * 0.70710678118654752f)); }
; template <int EPI>
; __device__ __forceinline__ void phase_gemm(const Params& p, const GemmDesc& d, char* shmc) {
;     ...
; #pragma unroll
;       for (int n = 0; n < 2; ++n) {
;         const int col = ewc * 32 + n * 16 + efr;
;         const int ch = ch0 + col;
;         const float w0 = cw[n][0], w1 = cw[n][1], w2 = cw[n][2], cb = cw[n][3];
; #pragma unroll
;         for (int ai = 0; ai < 2; ++ai)
; #pragma unroll
;           for (int m = 0; m < 4; ++m) {
;             const int s = ai * 32 + ewr * 16 + m * 4 + efq;
;             const f32x4 g = acc[ai][0][m][n];
;             const f32x4 v = acc[ai][1][m][n];
;             const float c0 = w0 * gp[ai][m][n] + w1 * g[0] + w2 * g[1] + cb;
;             const float c1 = w0 * g[0] + w1 * g[1] + w2 * g[2] + cb;
;             const float c2 = w0 * g[1] + w1 * g[2] + w2 * g[3] + cb;
;             const float c3 = w0 * g[2] + w1 * g[3] + w2 * gn[ai][m][n] + cb;
;             u16* sp = stg + (s * 4) * 136 + col;
;             sp[0] = f2bf(gelu_exact(c0) * v[0]);
;             sp[136] = f2bf(gelu_exact(c1) * v[1]);
;             sp[272] = f2bf(gelu_exact(c2) * v[2]);
;             sp[408] = f2bf(gelu_exact(c3) * v[3]);
;             if (s == 0) {
;               edge[0 * DFF + ch] = c0; edge[1 * DFF + ch] = g[0]; edge[2 * DFF + ch] = v[0];
;             }
;             if (s == 63) {
;               edge[3 * DFF + ch] = c3; edge[4 * DFF + ch] = g[3]; edge[5 * DFF + ch] = v[3];
;             }
;           }
	v_fmac_f32_e32 v16, v208, v143
	v_bfi_b32 v15, s96, v15, v18
	v_add_f32_e32 v16, v207, v16
	v_add_f32_e32 v15, 1.0, v15
	v_mul_f32_e32 v14, v14, v15
	v_mul_f32_e32 v15, 0x3f3504f3, v16
	v_fma_f32 v18, |v15|, s95, 1.0
	v_mul_f32_e32 v14, v55, v14
	v_cvt_pk_bf16_f32 v14, v14, s0
	ds_write_b16 v22, v14 offset:272
	v_mul_f32_e32 v14, 0.5, v16
	v_rcp_f32_e32 v16, v18
	v_mul_f32_e64 v19, |v15|, -|v15|
	v_fmamk_f32 v18, v16, 0x3f87dc22, v206
	v_mul_f32_e32 v19, 0x3fb8aa3b, v19
	v_fmaak_f32 v18, v18, v16, 0x3fb5f0e3
	v_exp_f32_e32 v19, v19
	v_fmaak_f32 v18, v18, v16, 0xbe91a98e
	v_fmaak_f32 v18, v18, v16, 0x3e827906
	v_mul_f32_e32 v17, v210, v143
	v_mul_f32_e32 v16, v16, v18
	v_fmac_f32_e32 v17, v209, v142
	v_fma_f32 v16, -v19, v16, 1.0
	v_fmac_f32_e32 v17, v208, v149
	v_bfi_b32 v15, s96, v16, v15
	v_add_f32_e32 v17, v207, v17
	v_add_f32_e32 v15, 1.0, v15
	v_mul_f32_e32 v14, v14, v15
	v_mul_f32_e32 v15, 0x3f3504f3, v17
	v_fma_f32 v16, |v15|, s95, 1.0
	v_mul_f32_e32 v14, v56, v14
	v_cvt_pk_bf16_f32 v14, v14, s0
	ds_write_b16 v22, v14 offset:544
	v_mul_f32_e32 v14, 0.5, v17
	v_rcp_f32_e32 v16, v16
	v_mul_f32_e64 v18, |v15|, -|v15|
	v_fmamk_f32 v17, v16, 0x3f87dc22, v206
	v_mul_f32_e32 v18, 0x3fb8aa3b, v18
	v_fmaak_f32 v17, v17, v16, 0x3fb5f0e3
	v_exp_f32_e32 v18, v18
	v_fmaak_f32 v17, v17, v16, 0xbe91a98e
	v_fmaak_f32 v17, v17, v16, 0x3e827906
	v_mul_f32_e32 v16, v16, v17
	v_fma_f32 v16, -v18, v16, 1.0
	v_bfi_b32 v15, s96, v16, v15
	v_add_f32_e32 v15, 1.0, v15
	v_mul_f32_e32 v14, v14, v15
	v_mul_f32_e32 v14, v57, v14
	v_cvt_pk_bf16_f32 v14, v14, s0
	ds_write_b16 v22, v14 offset:816
	v_mul_f32_e32 v14, v209, v141
	v_fmac_f32_e32 v14, v210, v136
	v_fmac_f32_e32 v14, v208, v137
	v_add_f32_e32 v14, v207, v14
	v_mul_f32_e32 v18, 0x3f3504f3, v14
	v_fma_f32 v19, |v18|, s95, 1.0
	v_mul_f32_e32 v15, v210, v137
	v_fmac_f32_e32 v15, v209, v136
	v_fmac_f32_e32 v15, v208, v134
	v_rcp_f32_e32 v19, v19
	v_mul_f32_e64 v21, |v18|, -|v18|
	v_fmamk_f32 v20, v19, 0x3f87dc22, v206
	v_mul_f32_e32 v21, 0x3fb8aa3b, v21
	v_fmaak_f32 v20, v20, v19, 0x3fb5f0e3
	v_exp_f32_e32 v21, v21
	v_fmaak_f32 v20, v20, v19, 0xbe91a98e
	v_fmaak_f32 v20, v20, v19, 0x3e827906
	v_mul_f32_e32 v19, v19, v20
	v_fma_f32 v19, -v21, v19, 1.0
	v_bfi_b32 v18, s96, v19, v18
	v_add_f32_e32 v15, v207, v15
	v_mul_f32_e32 v14, 0.5, v14
	v_add_f32_e32 v18, 1.0, v18
	v_mul_f32_e32 v14, v14, v18
	v_mul_f32_e32 v18, 0x3f3504f3, v15
	v_fma_f32 v19, |v18|, s95, 1.0
	v_mul_f32_e32 v14, v50, v14
	v_add3_u32 v22, s14, v79, v62
	v_cvt_pk_bf16_f32 v14, v14, s0
	ds_write_b16 v22, v14
	v_mul_f32_e32 v14, 0.5, v15
	v_rcp_f32_e32 v15, v19
	v_mul_f32_e64 v20, |v18|, -|v18|
	v_fmamk_f32 v19, v15, 0x3f87dc22, v206
	v_mul_f32_e32 v20, 0x3fb8aa3b, v20
	v_fmaak_f32 v19, v19, v15, 0x3fb5f0e3
	v_exp_f32_e32 v20, v20
	v_fmaak_f32 v19, v19, v15, 0xbe91a98e
	v_fmaak_f32 v19, v19, v15, 0x3e827906
	v_mul_f32_e32 v16, v210, v134
	v_mul_f32_e32 v15, v15, v19
	v_fmac_f32_e32 v16, v209, v137
	v_fma_f32 v15, -v20, v15, 1.0
	v_fmac_f32_e32 v16, v208, v135
	v_bfi_b32 v15, s96, v15, v18
	v_add_f32_e32 v16, v207, v16
	v_add_f32_e32 v15, 1.0, v15
	v_mul_f32_e32 v14, v14, v15
	v_mul_f32_e32 v15, 0x3f3504f3, v16
	v_fma_f32 v18, |v15|, s95, 1.0
	v_mul_f32_e32 v14, v51, v14
	v_cvt_pk_bf16_f32 v14, v14, s0
	ds_write_b16 v22, v14 offset:272
	v_mul_f32_e32 v14, 0.5, v16
	v_rcp_f32_e32 v16, v18
	v_mul_f32_e64 v19, |v15|, -|v15|
	v_fmamk_f32 v18, v16, 0x3f87dc22, v206
	v_mul_f32_e32 v19, 0x3fb8aa3b, v19
	v_fmaak_f32 v18, v18, v16, 0x3fb5f0e3
	v_exp_f32_e32 v19, v19
	v_fmaak_f32 v18, v18, v16, 0xbe91a98e
	v_fmaak_f32 v18, v18, v16, 0x3e827906
	v_mul_f32_e32 v17, v210, v135
	v_mul_f32_e32 v16, v16, v18
	v_fmac_f32_e32 v17, v209, v134
	v_fma_f32 v16, -v19, v16, 1.0
	v_fmac_f32_e32 v17, v208, v139
	v_bfi_b32 v15, s96, v16, v15
	v_add_f32_e32 v17, v207, v17
	v_add_f32_e32 v15, 1.0, v15
	v_mul_f32_e32 v14, v14, v15
	v_mul_f32_e32 v15, 0x3f3504f3, v17
	v_fma_f32 v16, |v15|, s95, 1.0
	v_mul_f32_e32 v14, v52, v14
	v_cvt_pk_bf16_f32 v14, v14, s0
	ds_write_b16 v22, v14 offset:544
	v_mul_f32_e32 v14, 0.5, v17
	v_rcp_f32_e32 v16, v16
	v_mul_f32_e64 v18, |v15|, -|v15|
	v_fmamk_f32 v17, v16, 0x3f87dc22, v206
	v_mul_f32_e32 v18, 0x3fb8aa3b, v18
	v_fmaak_f32 v17, v17, v16, 0x3fb5f0e3
	v_exp_f32_e32 v18, v18
	v_fmaak_f32 v17, v17, v16, 0xbe91a98e
	v_fmaak_f32 v17, v17, v16, 0x3e827906
	v_mul_f32_e32 v16, v16, v17
	v_fma_f32 v16, -v18, v16, 1.0
	v_bfi_b32 v15, s96, v16, v15
	v_add_f32_e32 v15, 1.0, v15
	v_mul_f32_e32 v14, v14, v15
	v_mul_f32_e32 v14, v53, v14
	v_cvt_pk_bf16_f32 v14, v14, s0
	ds_write_b16 v22, v14 offset:816
	v_mul_f32_e32 v14, v209, v133
	v_fmac_f32_e32 v14, v210, v128
	v_fmac_f32_e32 v14, v208, v129
	v_add_f32_e32 v14, v207, v14
	v_mul_f32_e32 v18, 0x3f3504f3, v14
	v_fma_f32 v19, |v18|, s95, 1.0
	v_mul_f32_e32 v15, v210, v129
	v_fmac_f32_e32 v15, v209, v128
	v_fmac_f32_e32 v15, v208, v126
	v_rcp_f32_e32 v19, v19
	v_mul_f32_e64 v21, |v18|, -|v18|
	v_fmamk_f32 v20, v19, 0x3f87dc22, v206
	v_mul_f32_e32 v21, 0x3fb8aa3b, v21
	v_fmaak_f32 v20, v20, v19, 0x3fb5f0e3
	v_exp_f32_e32 v21, v21
	v_fmaak_f32 v20, v20, v19, 0xbe91a98e
	v_fmaak_f32 v20, v20, v19, 0x3e827906
	v_mul_f32_e32 v19, v19, v20
	v_fma_f32 v19, -v21, v19, 1.0
	v_bfi_b32 v18, s96, v19, v18
	v_add_f32_e32 v15, v207, v15
	v_mul_f32_e32 v14, 0.5, v14
	v_add_f32_e32 v18, 1.0, v18
	v_mul_f32_e32 v14, v14, v18
	v_mul_f32_e32 v18, 0x3f3504f3, v15
	v_fma_f32 v19, |v18|, s95, 1.0
	v_mul_f32_e32 v14, v46, v14
	v_add3_u32 v22, s14, v80, v62
	v_cvt_pk_bf16_f32 v14, v14, s0
	ds_write_b16 v22, v14
	v_mul_f32_e32 v14, 0.5, v15
	v_rcp_f32_e32 v15, v19
	v_mul_f32_e64 v20, |v18|, -|v18|
; __device__ __forceinline__ u16 f2bf(float f) { return (u16)(pack2(f, f) & 0xffffu); }
; __device__ __forceinline__ float erf_f32(float x) {
;   const float ax = fabsf(x);
;   const float t = __frcp_rn(fmaf(0.3275911f, ax, 1.0f));
;   float poly = fmaf(1.061405429f, t, -1.453152027f);
;   poly = fmaf(poly, t, 1.421413741f);
;   poly = fmaf(poly, t, -0.284496736f);
;   poly = fmaf(poly, t, 0.254829592f);
;   const float y = 1.0f - poly * t * __expf(-ax * ax);
;   return copysignf(y, x);
; }
; __device__ __forceinline__ float gelu_exact(float x) { return 0.5f * x * (1.0f + erf_f32(x * 0.70710678118654752f)); }
; template <int EPI>
; __device__ __forceinline__ void phase_gemm(const Params& p, const GemmDesc& d, char* shmc) {
;     ...
; #pragma unroll
;       for (int n = 0; n < 2; ++n) {
;         const int col = ewc * 32 + n * 16 + efr;
;         const int ch = ch0 + col;
;         const float w0 = cw[n][0], w1 = cw[n][1], w2 = cw[n][2], cb = cw[n][3];
; #pragma unroll
;         for (int ai = 0; ai < 2; ++ai)
; #pragma unroll
;           for (int m = 0; m < 4; ++m) {
;             const int s = ai * 32 + ewr * 16 + m * 4 + efq;
;             const f32x4 g = acc[ai][0][m][n];
;             const f32x4 v = acc[ai][1][m][n];
;             const float c0 = w0 * gp[ai][m][n] + w1 * g[0] + w2 * g[1] + cb;
;             const float c1 = w0 * g[0] + w1 * g[1] + w2 * g[2] + cb;
;             const float c2 = w0 * g[1] + w1 * g[2] + w2 * g[3] + cb;
;             const float c3 = w0 * g[2] + w1 * g[3] + w2 * gn[ai][m][n] + cb;
;             u16* sp = stg + (s * 4) * 136 + col;
;             sp[0] = f2bf(gelu_exact(c0) * v[0]);
;             sp[136] = f2bf(gelu_exact(c1) * v[1]);
;             sp[272] = f2bf(gelu_exact(c2) * v[2]);
;             sp[408] = f2bf(gelu_exact(c3) * v[3]);
;             if (s == 0) {
;               edge[0 * DFF + ch] = c0; edge[1 * DFF + ch] = g[0]; edge[2 * DFF + ch] = v[0];
;             }
;             if (s == 63) {
;               edge[3 * DFF + ch] = c3; edge[4 * DFF + ch] = g[3]; edge[5 * DFF + ch] = v[3];
;             }
;           }
	v_fmamk_f32 v19, v15, 0x3f87dc22, v206
	v_mul_f32_e32 v20, 0x3fb8aa3b, v20
	v_fmaak_f32 v19, v19, v15, 0x3fb5f0e3
	v_exp_f32_e32 v20, v20
	v_fmaak_f32 v19, v19, v15, 0xbe91a98e
	v_fmaak_f32 v19, v19, v15, 0x3e827906
	v_mul_f32_e32 v16, v210, v126
	v_mul_f32_e32 v15, v15, v19
	v_fmac_f32_e32 v16, v209, v129
	v_fma_f32 v15, -v20, v15, 1.0
	v_fmac_f32_e32 v16, v208, v127
	v_bfi_b32 v15, s96, v15, v18
	v_add_f32_e32 v16, v207, v16
	v_add_f32_e32 v15, 1.0, v15
	v_mul_f32_e32 v14, v14, v15
	v_mul_f32_e32 v15, 0x3f3504f3, v16
	v_fma_f32 v18, |v15|, s95, 1.0
	v_mul_f32_e32 v14, v47, v14
	v_cvt_pk_bf16_f32 v14, v14, s0
	ds_write_b16 v22, v14 offset:272
	v_mul_f32_e32 v14, 0.5, v16
	v_rcp_f32_e32 v16, v18
	v_mul_f32_e64 v19, |v15|, -|v15|
	v_fmamk_f32 v18, v16, 0x3f87dc22, v206
	v_mul_f32_e32 v19, 0x3fb8aa3b, v19
	v_fmaak_f32 v18, v18, v16, 0x3fb5f0e3
	v_exp_f32_e32 v19, v19
	v_fmaak_f32 v18, v18, v16, 0xbe91a98e
	v_fmaak_f32 v18, v18, v16, 0x3e827906
	v_mul_f32_e32 v17, v210, v127
	v_mul_f32_e32 v16, v16, v18
	v_fmac_f32_e32 v17, v209, v126
	v_fma_f32 v16, -v19, v16, 1.0
	v_fmac_f32_e32 v17, v208, v131
	v_bfi_b32 v15, s96, v16, v15
	v_add_f32_e32 v17, v207, v17
	v_add_f32_e32 v15, 1.0, v15
	v_mul_f32_e32 v14, v14, v15
	v_mul_f32_e32 v15, 0x3f3504f3, v17
	v_fma_f32 v16, |v15|, s95, 1.0
	v_mul_f32_e32 v14, v48, v14
	v_cvt_pk_bf16_f32 v14, v14, s0
	ds_write_b16 v22, v14 offset:544
	v_mul_f32_e32 v14, 0.5, v17
	v_rcp_f32_e32 v16, v16
	v_mul_f32_e64 v18, |v15|, -|v15|
	v_fmamk_f32 v17, v16, 0x3f87dc22, v206
	v_mul_f32_e32 v18, 0x3fb8aa3b, v18
	v_fmaak_f32 v17, v17, v16, 0x3fb5f0e3
	v_exp_f32_e32 v18, v18
	v_fmaak_f32 v17, v17, v16, 0xbe91a98e
	v_fmaak_f32 v17, v17, v16, 0x3e827906
	v_mul_f32_e32 v16, v16, v17
	v_fma_f32 v16, -v18, v16, 1.0
	v_bfi_b32 v15, s96, v16, v15
	v_add_f32_e32 v15, 1.0, v15
	v_mul_f32_e32 v14, v14, v15
	v_mul_f32_e32 v14, v49, v14
	v_cvt_pk_bf16_f32 v14, v14, s0
	ds_write_b16 v22, v14 offset:816
	v_mul_f32_e32 v14, v209, v125
	v_fmac_f32_e32 v14, v210, v120
	v_fmac_f32_e32 v14, v208, v121
	v_add_f32_e32 v14, v207, v14
	v_mul_f32_e32 v18, 0x3f3504f3, v14
	v_fma_f32 v19, |v18|, s95, 1.0
	v_mul_f32_e32 v15, v210, v121
	v_fmac_f32_e32 v15, v209, v120
	v_fmac_f32_e32 v15, v208, v118
	v_rcp_f32_e32 v19, v19
	v_mul_f32_e64 v21, |v18|, -|v18|
	v_fmamk_f32 v20, v19, 0x3f87dc22, v206
	v_mul_f32_e32 v21, 0x3fb8aa3b, v21
	v_fmaak_f32 v20, v20, v19, 0x3fb5f0e3
	v_exp_f32_e32 v21, v21
	v_fmaak_f32 v20, v20, v19, 0xbe91a98e
	v_fmaak_f32 v20, v20, v19, 0x3e827906
	v_mul_f32_e32 v19, v19, v20
	v_fma_f32 v19, -v21, v19, 1.0
	v_bfi_b32 v18, s96, v19, v18
	v_add_f32_e32 v15, v207, v15
	v_mul_f32_e32 v14, 0.5, v14
	v_add_f32_e32 v18, 1.0, v18
	v_mul_f32_e32 v14, v14, v18
	v_mul_f32_e32 v18, 0x3f3504f3, v15
	v_fma_f32 v19, |v18|, s95, 1.0
	v_pk_mul_f32 v[26:27], v[26:27], v[42:43]
	v_add3_u32 v22, s14, v81, v62
	v_mul_f32_e32 v14, v26, v14
	v_cvt_pk_bf16_f32 v14, v14, s0
	ds_write_b16 v22, v14
	v_mul_f32_e32 v14, 0.5, v15
	v_rcp_f32_e32 v15, v19
	v_mul_f32_e64 v20, |v18|, -|v18|
	v_fmamk_f32 v19, v15, 0x3f87dc22, v206
	v_mul_f32_e32 v20, 0x3fb8aa3b, v20
	v_fmaak_f32 v19, v19, v15, 0x3fb5f0e3
	v_exp_f32_e32 v20, v20
	v_fmaak_f32 v19, v19, v15, 0xbe91a98e
	v_fmaak_f32 v19, v19, v15, 0x3e827906
	v_mul_f32_e32 v16, v210, v118
	v_mul_f32_e32 v15, v15, v19
	v_fmac_f32_e32 v16, v209, v121
	v_fma_f32 v15, -v20, v15, 1.0
	v_fmac_f32_e32 v16, v208, v119
	v_bfi_b32 v15, s96, v15, v18
	v_add_f32_e32 v16, v207, v16
	v_add_f32_e32 v15, 1.0, v15
	v_mul_f32_e32 v14, v14, v15
	v_mul_f32_e32 v15, 0x3f3504f3, v16
	v_fma_f32 v18, |v15|, s95, 1.0
	v_mul_f32_e32 v14, v27, v14
	v_cvt_pk_bf16_f32 v14, v14, s0
	ds_write_b16 v22, v14 offset:272
	v_mul_f32_e32 v14, 0.5, v16
	v_rcp_f32_e32 v16, v18
	v_mul_f32_e64 v19, |v15|, -|v15|
	v_fmamk_f32 v18, v16, 0x3f87dc22, v206
	v_mul_f32_e32 v19, 0x3fb8aa3b, v19
	v_fmaak_f32 v18, v18, v16, 0x3fb5f0e3
	v_exp_f32_e32 v19, v19
	v_fmaak_f32 v18, v18, v16, 0xbe91a98e
	v_fmaak_f32 v18, v18, v16, 0x3e827906
	v_mul_f32_e32 v17, v210, v119
	v_mul_f32_e32 v16, v16, v18
	v_fmac_f32_e32 v17, v209, v118
	v_fma_f32 v16, -v19, v16, 1.0
	v_fmac_f32_e32 v17, v208, v123
	v_bfi_b32 v15, s96, v16, v15
	v_add_f32_e32 v17, v207, v17
	v_add_f32_e32 v15, 1.0, v15
	v_mul_f32_e32 v14, v14, v15
	v_mul_f32_e32 v15, 0x3f3504f3, v17
	v_fma_f32 v16, |v15|, s95, 1.0
	v_pk_mul_f32 v[28:29], v[28:29], v[44:45]
	s_nop 0
	v_mul_f32_e32 v14, v28, v14
	v_cvt_pk_bf16_f32 v14, v14, s0
	ds_write_b16 v22, v14 offset:544
	v_mul_f32_e32 v14, 0.5, v17
	v_rcp_f32_e32 v16, v16
	v_mul_f32_e64 v18, |v15|, -|v15|
	v_fmamk_f32 v17, v16, 0x3f87dc22, v206
	v_mul_f32_e32 v18, 0x3fb8aa3b, v18
	v_fmaak_f32 v17, v17, v16, 0x3fb5f0e3
	v_exp_f32_e32 v18, v18
	v_fmaak_f32 v17, v17, v16, 0xbe91a98e
	v_fmaak_f32 v17, v17, v16, 0x3e827906
	v_mul_f32_e32 v16, v16, v17
	v_fma_f32 v16, -v18, v16, 1.0
	v_bfi_b32 v15, s96, v16, v15
	v_add_f32_e32 v15, 1.0, v15
	v_mul_f32_e32 v14, v14, v15
	v_mul_f32_e32 v14, v29, v14
	v_cvt_pk_bf16_f32 v14, v14, s0
	ds_write_b16 v22, v14 offset:816
	v_mul_f32_e32 v14, v209, v117
	v_fmac_f32_e32 v14, v210, v112
	v_fmac_f32_e32 v14, v208, v113
	v_add_f32_e32 v14, v207, v14
	v_mul_f32_e32 v18, 0x3f3504f3, v14
	v_fma_f32 v19, |v18|, s95, 1.0
	v_mul_f32_e32 v15, v210, v113
	v_fmac_f32_e32 v15, v209, v112
	v_fmac_f32_e32 v15, v208, v110
	v_rcp_f32_e32 v19, v19
	v_mul_f32_e64 v21, |v18|, -|v18|
	v_fmamk_f32 v20, v19, 0x3f87dc22, v206
	v_mul_f32_e32 v21, 0x3fb8aa3b, v21
	v_fmaak_f32 v20, v20, v19, 0x3fb5f0e3
	v_exp_f32_e32 v21, v21
	v_fmaak_f32 v20, v20, v19, 0xbe91a98e
	v_fmaak_f32 v20, v20, v19, 0x3e827906
	v_mul_f32_e32 v19, v19, v20
	v_fma_f32 v19, -v21, v19, 1.0
; __device__ __forceinline__ u16 f2bf(float f) { return (u16)(pack2(f, f) & 0xffffu); }
; __device__ __forceinline__ float erf_f32(float x) {
;   const float ax = fabsf(x);
;   const float t = __frcp_rn(fmaf(0.3275911f, ax, 1.0f));
;   float poly = fmaf(1.061405429f, t, -1.453152027f);
;   poly = fmaf(poly, t, 1.421413741f);
;   poly = fmaf(poly, t, -0.284496736f);
;   poly = fmaf(poly, t, 0.254829592f);
;   const float y = 1.0f - poly * t * __expf(-ax * ax);
;   return copysignf(y, x);
; }
; __device__ __forceinline__ float gelu_exact(float x) { return 0.5f * x * (1.0f + erf_f32(x * 0.70710678118654752f)); }
; template <int EPI>
; __device__ __forceinline__ void phase_gemm(const Params& p, const GemmDesc& d, char* shmc) {
;     ...
; #pragma unroll
;       for (int n = 0; n < 2; ++n) {
;         const int col = ewc * 32 + n * 16 + efr;
;         const int ch = ch0 + col;
;         const float w0 = cw[n][0], w1 = cw[n][1], w2 = cw[n][2], cb = cw[n][3];
; #pragma unroll
;         for (int ai = 0; ai < 2; ++ai)
; #pragma unroll
;           for (int m = 0; m < 4; ++m) {
;             const int s = ai * 32 + ewr * 16 + m * 4 + efq;
;             const f32x4 g = acc[ai][0][m][n];
;             const f32x4 v = acc[ai][1][m][n];
;             const float c0 = w0 * gp[ai][m][n] + w1 * g[0] + w2 * g[1] + cb;
;             const float c1 = w0 * g[0] + w1 * g[1] + w2 * g[2] + cb;
;             const float c2 = w0 * g[1] + w1 * g[2] + w2 * g[3] + cb;
;             const float c3 = w0 * g[2] + w1 * g[3] + w2 * gn[ai][m][n] + cb;
;             u16* sp = stg + (s * 4) * 136 + col;
;             sp[0] = f2bf(gelu_exact(c0) * v[0]);
;             sp[136] = f2bf(gelu_exact(c1) * v[1]);
;             sp[272] = f2bf(gelu_exact(c2) * v[2]);
;             sp[408] = f2bf(gelu_exact(c3) * v[3]);
;             if (s == 0) {
;               edge[0 * DFF + ch] = c0; edge[1 * DFF + ch] = g[0]; edge[2 * DFF + ch] = v[0];
;             }
;             if (s == 63) {
;               edge[3 * DFF + ch] = c3; edge[4 * DFF + ch] = g[3]; edge[5 * DFF + ch] = v[3];
;             }
;           }
	v_bfi_b32 v18, s96, v19, v18
	v_mul_f32_e32 v14, 0.5, v14
	v_add_f32_e32 v18, 1.0, v18
	v_add_f32_e32 v15, v207, v15
	v_mul_f32_e32 v14, v14, v18
	v_mul_f32_e32 v12, v12, v14
	v_mul_f32_e32 v14, 0x3f3504f3, v15
	v_fma_f32 v18, |v14|, s95, 1.0
	v_add3_u32 v22, s14, v82, v62
	v_cvt_pk_bf16_f32 v12, v12, s0
	ds_write_b16 v22, v12
	v_mul_f32_e32 v12, 0.5, v15
	v_rcp_f32_e32 v15, v18
	v_mul_f32_e64 v19, |v14|, -|v14|
	v_fmamk_f32 v18, v15, 0x3f87dc22, v206
	v_mul_f32_e32 v19, 0x3fb8aa3b, v19
	v_fmaak_f32 v18, v18, v15, 0x3fb5f0e3
	v_exp_f32_e32 v19, v19
	v_fmaak_f32 v18, v18, v15, 0xbe91a98e
	v_fmaak_f32 v18, v18, v15, 0x3e827906
	v_mul_f32_e32 v15, v15, v18
	v_mul_f32_e32 v16, v210, v110
	v_fma_f32 v15, -v19, v15, 1.0
	v_fmac_f32_e32 v16, v209, v113
	v_bfi_b32 v14, s96, v15, v14
	v_fmac_f32_e32 v16, v208, v111
	v_add_f32_e32 v14, 1.0, v14
	v_add_f32_e32 v16, v207, v16
	v_mul_f32_e32 v12, v12, v14
	v_mul_f32_e32 v12, v13, v12
	v_mul_f32_e32 v13, 0x3f3504f3, v16
	v_fma_f32 v14, |v13|, s95, 1.0
	v_cvt_pk_bf16_f32 v12, v12, s0
	ds_write_b16 v22, v12 offset:272
	v_mul_f32_e32 v12, 0.5, v16
	v_rcp_f32_e32 v14, v14
	v_mul_f32_e64 v16, |v13|, -|v13|
	v_fmamk_f32 v15, v14, 0x3f87dc22, v206
	v_mul_f32_e32 v16, 0x3fb8aa3b, v16
	v_fmaak_f32 v15, v15, v14, 0x3fb5f0e3
	v_exp_f32_e32 v16, v16
	v_fmaak_f32 v15, v15, v14, 0xbe91a98e
	v_fmaak_f32 v15, v15, v14, 0x3e827906
	v_mul_f32_e32 v14, v14, v15
	v_mul_f32_e32 v17, v210, v111
	v_fma_f32 v14, -v16, v14, 1.0
	v_fmac_f32_e32 v17, v209, v110
	v_bfi_b32 v13, s96, v14, v13
	v_fmac_f32_e32 v17, v208, v115
	v_add_f32_e32 v13, 1.0, v13
	v_add_f32_e32 v17, v207, v17
	v_mul_f32_e32 v12, v12, v13
	v_mul_f32_e32 v10, v10, v12
	v_mul_f32_e32 v12, 0x3f3504f3, v17
	v_fma_f32 v13, |v12|, s95, 1.0
	v_cvt_pk_bf16_f32 v10, v10, s0
	ds_write_b16 v22, v10 offset:544
	v_mul_f32_e32 v10, 0.5, v17
	v_rcp_f32_e32 v13, v13
	v_mul_f32_e64 v15, |v12|, -|v12|
	v_fmamk_f32 v14, v13, 0x3f87dc22, v206
	v_mul_f32_e32 v15, 0x3fb8aa3b, v15
	v_fmaak_f32 v14, v14, v13, 0x3fb5f0e3
	v_exp_f32_e32 v15, v15
	v_fmaak_f32 v14, v14, v13, 0xbe91a98e
	v_fmaak_f32 v14, v14, v13, 0x3e827906
	v_mul_f32_e32 v13, v13, v14
	v_fma_f32 v13, -v15, v13, 1.0
	v_bfi_b32 v12, s96, v13, v12
	v_add_f32_e32 v12, 1.0, v12
	v_mul_f32_e32 v10, v10, v12
	v_mul_f32_e32 v10, v11, v10
	v_cvt_pk_bf16_f32 v10, v10, s0
	ds_write_b16 v22, v10 offset:816
	v_mul_f32_e32 v10, v209, v109
	v_fmac_f32_e32 v10, v210, v104
	v_fmac_f32_e32 v10, v208, v105
	v_add_f32_e32 v10, v207, v10
	v_mul_f32_e32 v14, 0x3f3504f3, v10
	v_fma_f32 v15, |v14|, s95, 1.0
	v_mul_f32_e32 v11, v210, v105
	v_fmac_f32_e32 v11, v209, v104
	v_fmac_f32_e32 v11, v208, v102
	v_rcp_f32_e32 v15, v15
	v_mul_f32_e64 v17, |v14|, -|v14|
	v_fmamk_f32 v16, v15, 0x3f87dc22, v206
	v_mul_f32_e32 v17, 0x3fb8aa3b, v17
	v_fmaak_f32 v16, v16, v15, 0x3fb5f0e3
	v_exp_f32_e32 v17, v17
	v_fmaak_f32 v16, v16, v15, 0xbe91a98e
	v_fmaak_f32 v16, v16, v15, 0x3e827906
	v_mul_f32_e32 v15, v15, v16
	v_fma_f32 v15, -v17, v15, 1.0
	v_bfi_b32 v14, s96, v15, v14
	v_mul_f32_e32 v10, 0.5, v10
	v_add_f32_e32 v14, 1.0, v14
	v_add_f32_e32 v11, v207, v11
	v_mul_f32_e32 v10, v10, v14
	v_mul_f32_e32 v8, v8, v10
	v_mul_f32_e32 v10, 0x3f3504f3, v11
	v_fma_f32 v14, |v10|, s95, 1.0
	v_add3_u32 v18, s14, v74, v62
	v_cvt_pk_bf16_f32 v8, v8, s0
	ds_write_b16 v18, v8
	v_mul_f32_e32 v8, 0.5, v11
	v_rcp_f32_e32 v11, v14
	v_mul_f32_e64 v15, |v10|, -|v10|
	v_fmamk_f32 v14, v11, 0x3f87dc22, v206
	v_mul_f32_e32 v15, 0x3fb8aa3b, v15
	v_fmaak_f32 v14, v14, v11, 0x3fb5f0e3
	v_exp_f32_e32 v15, v15
	v_fmaak_f32 v14, v14, v11, 0xbe91a98e
	v_fmaak_f32 v14, v14, v11, 0x3e827906
	v_mul_f32_e32 v11, v11, v14
	v_mul_f32_e32 v12, v210, v102
	v_fma_f32 v11, -v15, v11, 1.0
	v_fmac_f32_e32 v12, v209, v105
	v_bfi_b32 v10, s96, v11, v10
	v_fmac_f32_e32 v12, v208, v103
	v_add_f32_e32 v10, 1.0, v10
	v_add_f32_e32 v12, v207, v12
	v_mul_f32_e32 v8, v8, v10
	v_mul_f32_e32 v8, v9, v8
	v_mul_f32_e32 v9, 0x3f3504f3, v12
	v_fma_f32 v10, |v9|, s95, 1.0
	v_cvt_pk_bf16_f32 v8, v8, s0
	ds_write_b16 v18, v8 offset:272
	v_mul_f32_e32 v8, 0.5, v12
	v_rcp_f32_e32 v10, v10
	v_mul_f32_e64 v12, |v9|, -|v9|
	v_fmamk_f32 v11, v10, 0x3f87dc22, v206
	v_mul_f32_e32 v12, 0x3fb8aa3b, v12
	v_fmaak_f32 v11, v11, v10, 0x3fb5f0e3
	v_exp_f32_e32 v12, v12
	v_fmaak_f32 v11, v11, v10, 0xbe91a98e
; __device__ __forceinline__ u16 f2bf(float f) { return (u16)(pack2(f, f) & 0xffffu); }
; __device__ __forceinline__ float erf_f32(float x) {
;   const float ax = fabsf(x);
;   const float t = __frcp_rn(fmaf(0.3275911f, ax, 1.0f));
;   float poly = fmaf(1.061405429f, t, -1.453152027f);
;   poly = fmaf(poly, t, 1.421413741f);
;   poly = fmaf(poly, t, -0.284496736f);
;   poly = fmaf(poly, t, 0.254829592f);
;   const float y = 1.0f - poly * t * __expf(-ax * ax);
;   return copysignf(y, x);
; }
; __device__ __forceinline__ float gelu_exact(float x) { return 0.5f * x * (1.0f + erf_f32(x * 0.70710678118654752f)); }
; template <int EPI>
; __device__ __forceinline__ void phase_gemm(const Params& p, const GemmDesc& d, char* shmc) {
;     ...
; #pragma unroll
;       for (int n = 0; n < 2; ++n) {
;         const int col = ewc * 32 + n * 16 + efr;
;         const int ch = ch0 + col;
;         const float w0 = cw[n][0], w1 = cw[n][1], w2 = cw[n][2], cb = cw[n][3];
; #pragma unroll
;         for (int ai = 0; ai < 2; ++ai)
; #pragma unroll
;           for (int m = 0; m < 4; ++m) {
;             const int s = ai * 32 + ewr * 16 + m * 4 + efq;
;             const f32x4 g = acc[ai][0][m][n];
;             const f32x4 v = acc[ai][1][m][n];
;             const float c0 = w0 * gp[ai][m][n] + w1 * g[0] + w2 * g[1] + cb;
;             const float c1 = w0 * g[0] + w1 * g[1] + w2 * g[2] + cb;
;             const float c2 = w0 * g[1] + w1 * g[2] + w2 * g[3] + cb;
;             const float c3 = w0 * g[2] + w1 * g[3] + w2 * gn[ai][m][n] + cb;
;             u16* sp = stg + (s * 4) * 136 + col;
;             sp[0] = f2bf(gelu_exact(c0) * v[0]);
;             sp[136] = f2bf(gelu_exact(c1) * v[1]);
;             sp[272] = f2bf(gelu_exact(c2) * v[2]);
;             sp[408] = f2bf(gelu_exact(c3) * v[3]);
;             if (s == 0) {
;               edge[0 * DFF + ch] = c0; edge[1 * DFF + ch] = g[0]; edge[2 * DFF + ch] = v[0];
;             }
;             if (s == 63) {
;               edge[3 * DFF + ch] = c3; edge[4 * DFF + ch] = g[3]; edge[5 * DFF + ch] = v[3];
;             }
;           }
	v_fmaak_f32 v11, v11, v10, 0x3e827906
	v_mul_f32_e32 v10, v10, v11
	v_mul_f32_e32 v13, v210, v103
	v_fma_f32 v10, -v12, v10, 1.0
	v_fmac_f32_e32 v13, v209, v102
	v_bfi_b32 v9, s96, v10, v9
	v_fmac_f32_e32 v13, v208, v107
	v_add_f32_e32 v9, 1.0, v9
	v_add_f32_e32 v13, v207, v13
	v_mul_f32_e32 v8, v8, v9
	v_mul_f32_e32 v6, v6, v8
	v_mul_f32_e32 v8, 0x3f3504f3, v13
	v_fma_f32 v9, |v8|, s95, 1.0
	v_cvt_pk_bf16_f32 v6, v6, s0
	ds_write_b16 v18, v6 offset:544
	v_mul_f32_e32 v6, 0.5, v13
	v_rcp_f32_e32 v9, v9
	v_mul_f32_e64 v11, |v8|, -|v8|
	v_fmamk_f32 v10, v9, 0x3f87dc22, v206
	v_mul_f32_e32 v11, 0x3fb8aa3b, v11
	v_fmaak_f32 v10, v10, v9, 0x3fb5f0e3
	v_exp_f32_e32 v11, v11
	v_fmaak_f32 v10, v10, v9, 0xbe91a98e
	v_fmaak_f32 v10, v10, v9, 0x3e827906
	v_mul_f32_e32 v9, v9, v10
	v_fma_f32 v9, -v11, v9, 1.0
	v_bfi_b32 v8, s96, v9, v8
	v_add_f32_e32 v8, 1.0, v8
	v_mul_f32_e32 v6, v6, v8
	v_mul_f32_e32 v6, v7, v6
	v_cvt_pk_bf16_f32 v6, v6, s0
	ds_write_b16 v18, v6 offset:816
	v_mul_f32_e32 v6, v209, v212
	v_fmac_f32_e32 v6, v210, v98
	v_fmac_f32_e32 v6, v208, v99
	v_add_f32_e32 v7, v207, v6
	v_mul_f32_e32 v10, 0x3f3504f3, v7
	v_fma_f32 v11, |v10|, s95, 1.0
	v_mul_f32_e32 v6, v210, v99
	v_fmac_f32_e32 v6, v209, v98
	v_fmac_f32_e32 v6, v208, v100
	v_rcp_f32_e32 v11, v11
	v_mul_f32_e64 v13, |v10|, -|v10|
	v_fmamk_f32 v12, v11, 0x3f87dc22, v206
	v_mul_f32_e32 v13, 0x3fb8aa3b, v13
	v_fmaak_f32 v12, v12, v11, 0x3fb5f0e3
	v_exp_f32_e32 v13, v13
	v_fmaak_f32 v12, v12, v11, 0xbe91a98e
	v_fmaak_f32 v12, v12, v11, 0x3e827906
	v_mul_f32_e32 v11, v11, v12
	v_fma_f32 v11, -v13, v11, 1.0
	v_bfi_b32 v10, s96, v11, v10
	v_mul_f32_e32 v7, 0.5, v7
	v_add_f32_e32 v10, 1.0, v10
	v_add_f32_e32 v8, v207, v6
	v_mul_f32_e32 v7, v7, v10
	v_mul_f32_e32 v4, v4, v7
	v_mul_f32_e32 v7, 0x3f3504f3, v8
	v_fma_f32 v10, |v7|, s95, 1.0
	v_add3_u32 v14, s14, v70, v62
	v_cvt_pk_bf16_f32 v4, v4, s0
	ds_write_b16 v14, v4
	v_mul_f32_e32 v4, 0.5, v8
	v_rcp_f32_e32 v8, v10
	v_mul_f32_e64 v11, |v7|, -|v7|
	v_fmamk_f32 v10, v8, 0x3f87dc22, v206
	v_mul_f32_e32 v11, 0x3fb8aa3b, v11
	v_fmaak_f32 v10, v10, v8, 0x3fb5f0e3
	v_exp_f32_e32 v11, v11
	v_fmaak_f32 v10, v10, v8, 0xbe91a98e
	v_fmaak_f32 v10, v10, v8, 0x3e827906
	v_mul_f32_e32 v8, v8, v10
	v_mul_f32_e32 v6, v210, v100
	v_fma_f32 v8, -v11, v8, 1.0
	v_fmac_f32_e32 v6, v209, v99
	v_bfi_b32 v7, s96, v8, v7
	v_fmac_f32_e32 v6, v208, v101
	v_add_f32_e32 v7, 1.0, v7
	v_add_f32_e32 v9, v207, v6
	v_mul_f32_e32 v4, v4, v7
	v_mul_f32_e32 v4, v5, v4
	v_mul_f32_e32 v5, 0x3f3504f3, v9
	v_fma_f32 v7, |v5|, s95, 1.0
	v_cvt_pk_bf16_f32 v4, v4, s0
	ds_write_b16 v14, v4 offset:272
	v_mul_f32_e32 v4, 0.5, v9
	v_rcp_f32_e32 v7, v7
	v_mul_f32_e64 v9, |v5|, -|v5|
	v_fmamk_f32 v8, v7, 0x3f87dc22, v206
	v_mul_f32_e32 v9, 0x3fb8aa3b, v9
	v_fmaak_f32 v8, v8, v7, 0x3fb5f0e3
	v_exp_f32_e32 v9, v9
	v_fmaak_f32 v8, v8, v7, 0xbe91a98e
	v_fmaak_f32 v8, v8, v7, 0x3e827906
	v_mul_f32_e32 v7, v7, v8
	v_mul_f32_e32 v6, v210, v101
	v_fma_f32 v7, -v9, v7, 1.0
	v_fmac_f32_e32 v6, v209, v100
	v_bfi_b32 v5, s96, v7, v5
	v_fmac_f32_e32 v6, v208, v211
	v_add_f32_e32 v5, 1.0, v5
	v_add_f32_e32 v6, v207, v6
	v_mul_f32_e32 v4, v4, v5
	v_mul_f32_e32 v2, v2, v4
	v_mul_f32_e32 v4, 0x3f3504f3, v6
	v_fma_f32 v5, |v4|, s95, 1.0
	v_cvt_pk_bf16_f32 v2, v2, s0
	ds_write_b16 v14, v2 offset:544
	v_mul_f32_e32 v2, 0.5, v6
	v_rcp_f32_e32 v5, v5
	v_mul_f32_e64 v8, |v4|, -|v4|
	v_fmamk_f32 v7, v5, 0x3f87dc22, v206
	v_mul_f32_e32 v8, 0x3fb8aa3b, v8
	v_fmaak_f32 v7, v7, v5, 0x3fb5f0e3
	v_exp_f32_e32 v8, v8
	v_fmaak_f32 v7, v7, v5, 0xbe91a98e
	v_fmaak_f32 v7, v7, v5, 0x3e827906
	v_mul_f32_e32 v5, v5, v7
	v_fma_f32 v5, -v8, v5, 1.0
	v_bfi_b32 v4, s96, v5, v4
	v_add_f32_e32 v4, 1.0, v4
	v_mul_f32_e32 v2, v2, v4
	v_mul_f32_e32 v2, v3, v2
	v_cvt_pk_bf16_f32 v2, v2, s0
	ds_write_b16 v14, v2 offset:816
	s_and_saveexec_b64 s[10:11], s[8:9]
	s_cbranch_execz .LBB0_289
	v_add_co_u32_e32 v4, vcc, 0x10000, v58
	s_nop 1
	v_addc_co_u32_e32 v5, vcc, 0, v59, vcc
	global_store_dword v[4:5], v6, off offset:2048
	v_add_co_u32_e32 v4, vcc, 0x16000, v58
	s_nop 1
	v_addc_co_u32_e32 v5, vcc, 0, v59, vcc
	global_store_dword v[4:5], v101, off
	v_add_co_u32_e32 v4, vcc, 0x1b000, v58
	s_nop 1
	v_addc_co_u32_e32 v5, vcc, 0, v59, vcc
	global_store_dword v[4:5], v3, off offset:2048
	s_branch .LBB0_289

; template <int EPI>
; __device__ __forceinline__ void phase_gemm(const Params& p, const GemmDesc& d, char* shmc) {
;     ...
;       const int ch0 = pn * 128;
;       const float* cwp = p.conv_w + (size_t)d.layer * 3 * DFF;
;       const float* cbp = p.conv_b + (size_t)d.layer * DFF;
;       float cw[2][4];
; #pragma unroll
;       for (int n = 0; n < 2; ++n) {
;         const int chx = ch0 + ewc * 32 + n * 16 + efr;
;         cw[n][0] = cwp[chx]; cw[n][1] = cwp[DFF + chx]; cw[n][2] = cwp[2 * DFF + chx]; cw[n][3] = cbp[chx];
;       }
;       const float* rsl = reinterpret_cast<const float*>(shmc + 143360);
;       f32x4 rsv[2][4];
; #pragma unroll
;       for (int ai = 0; ai < 2; ++ai)
; #pragma unroll
;         for (int m = 0; m < 4; ++m)
;           rsv[ai][m] = *reinterpret_cast<const f32x4*>(rsl + ai * HALF + ewr * 64 + m * 16 + efq * 4);
; #pragma unroll
;       for (int ai = 0; ai < 2; ++ai)
; #pragma unroll
;         for (int m = 0; m < 4; ++m) {
;           const f32x4 rs4 = rsv[ai][m];
; #pragma unroll
;           for (int n = 0; n < 2; ++n) {
;             acc[ai][0][m][n] *= rs4;
;             acc[ai][1][m][n] *= rs4;
;             const int s = ai * 32 + ewr * 16 + m * 4 + efq;
;             const int col = ewc * 32 + n * 16 + efr;
;             top[s * 144 + col] = acc[ai][0][m][n][0];
;             bot[s * 144 + col] = acc[ai][0][m][n][3];
;           }
;         }
;       __syncthreads();
.LBB0_1156:
	s_or_b64 exec, exec, s[8:9]
	v_mov_b32_e32 v38, v1
	s_lshl_b32 s54, s34, 7
	v_and_b32_e32 v177, 15, v38
	v_lshrrev_b32_e32 v30, 1, v38
	v_and_or_b32 v162, v30, s79, v177
	v_or_b32_e32 v200, s54, v162
	v_ashrrev_i32_e32 v201, 31, v200
	v_lshlrev_b64 v[30:31], 2, v[200:201]
	v_lshl_add_u64 v[32:33], s[22:23], 0, v[30:31]
	v_add_co_u32_e32 v34, vcc, 0x5000, v32
	v_lshl_add_u64 v[30:31], s[24:25], 0, v[30:31]
	s_nop 0
	v_addc_co_u32_e32 v35, vcc, 0, v33, vcc
	v_add_co_u32_e32 v36, vcc, 0xb000, v32
	v_ashrrev_i32_e32 v175, 4, v38
	s_nop 0
	v_addc_co_u32_e32 v37, vcc, 0, v33, vcc
	global_load_dword v215, v[32:33], off
	global_load_dword v217, v[34:35], off offset:2048
	global_load_dword v216, v[36:37], off
	global_load_dword v218, v[30:31], off
	v_or_b32_e32 v30, 16, v200
	v_ashrrev_i32_e32 v31, 31, v30
	v_lshlrev_b64 v[30:31], 2, v[30:31]
	v_lshl_add_u64 v[32:33], s[22:23], 0, v[30:31]
	v_add_co_u32_e32 v34, vcc, s80, v32
	v_lshl_add_u64 v[30:31], s[24:25], 0, v[30:31]
	s_nop 0
	v_addc_co_u32_e32 v35, vcc, 0, v33, vcc
	v_add_co_u32_e32 v36, vcc, s81, v32
	v_bfe_u32 v178, v38, 8, 1
	s_nop 0
	v_addc_co_u32_e32 v37, vcc, 0, v33, vcc
	global_load_dword v208, v[32:33], off
	global_load_dword v210, v[34:35], off offset:2048
	global_load_dword v209, v[36:37], off
	global_load_dword v207, v[30:31], off
	v_and_b32_e32 v179, 3, v175
	v_lshlrev_b32_e32 v30, 8, v178
	v_lshlrev_b32_e32 v31, 4, v179
	v_add3_u32 v30, s63, v30, v31
	v_lshl_or_b32 v220, v178, 4, v179
	ds_read_b128 v[62:65], v30
	ds_read_b128 v[54:57], v30 offset:64
	ds_read_b128 v[50:53], v30 offset:128
	ds_read_b128 v[46:49], v30 offset:192
	ds_read_b128 v[42:45], v30 offset:512
	ds_read_b128 v[38:41], v30 offset:576
	ds_read_b128 v[34:37], v30 offset:640
	ds_read_b128 v[30:33], v30 offset:704
	v_mad_u32_u24 v178, v220, s82, v162
	v_lshl_add_u32 v211, v178, 2, 0
	s_waitcnt lgkmcnt(0)
	v_pk_mul_f32 v[196:197], v[144:145], v[56:57]
	v_pk_mul_f32 v[198:199], v[142:143], v[54:55]
	v_pk_mul_f32 v[144:145], v[134:135], v[54:55]
	v_add_u32_e32 v134, 0x800, v211
	v_pk_mul_f32 v[190:191], v[128:129], v[52:53]
	v_pk_mul_f32 v[188:189], v[110:111], v[46:47]
	v_pk_mul_f32 v[128:129], v[102:103], v[46:47]
	v_add_u32_e32 v102, 0x1800, v211
	v_pk_mul_f32 v[142:143], v[136:137], v[56:57]
	ds_write2_b32 v134, v198, v144 offset0:64 offset1:80
	v_add_u32_e32 v134, 0x9800, v211
	v_pk_mul_f32 v[192:193], v[126:127], v[50:51]
	v_pk_mul_f32 v[136:137], v[118:119], v[50:51]
	v_add_u32_e32 v118, 0x1000, v211
	v_pk_mul_f32 v[186:187], v[112:113], v[48:49]
	v_pk_mul_f32 v[126:127], v[104:105], v[48:49]
	ds_write2_b32 v102, v188, v128 offset0:192 offset1:208
	v_add_u32_e32 v102, 0xa800, v211
	ds_write2_b32 v134, v197, v143 offset0:64 offset1:80
	v_pk_mul_f32 v[134:135], v[120:121], v[52:53]
	ds_write2_b32 v118, v192, v136 offset0:128 offset1:144
	v_add_u32_e32 v118, 0xa000, v211
	ds_write2_b32 v102, v187, v127 offset0:192 offset1:208
	v_pk_mul_f32 v[184:185], v[154:155], v[42:43]
	v_pk_mul_f32 v[120:121], v[150:151], v[42:43]
	v_add_u32_e32 v102, 0x4800, v211
	ds_write2_b32 v118, v191, v135 offset0:128 offset1:144
	v_pk_mul_f32 v[182:183], v[156:157], v[44:45]
	v_pk_mul_f32 v[118:119], v[152:153], v[44:45]
	ds_write2_b32 v102, v184, v120 offset1:16
	v_add_u32_e32 v102, 0xd800, v211
	v_pk_mul_f32 v[154:155], v[106:107], v[30:31]
	v_pk_mul_f32 v[98:99], v[98:99], v[30:31]
	v_add_u32_e32 v106, 0x6000, v211
	ds_write2_b32 v102, v183, v119 offset1:16
	v_pk_mul_f32 v[180:181], v[138:139], v[38:39]
	v_pk_mul_f32 v[112:113], v[130:131], v[38:39]
	v_add_u32_e32 v102, 0x5000, v211
	v_pk_mul_f32 v[152:153], v[108:109], v[32:33]
	v_pk_mul_f32 v[100:101], v[100:101], v[32:33]
	ds_write2_b32 v106, v154, v98 offset0:192 offset1:208
	v_add_u32_e32 v106, 0xf000, v211
	v_pk_mul_f32 v[202:203], v[160:161], v[64:65]
	v_pk_mul_f32 v[194:195], v[158:159], v[62:63]
	v_pk_mul_f32 v[146:147], v[146:147], v[62:63]
	v_pk_mul_f32 v[178:179], v[140:141], v[40:41]
	v_pk_mul_f32 v[110:111], v[132:133], v[40:41]
	ds_write2_b32 v102, v180, v112 offset0:64 offset1:80
	v_add_u32_e32 v102, 0xe000, v211
	v_pk_mul_f32 v[160:161], v[122:123], v[34:35]
	v_pk_mul_f32 v[104:105], v[114:115], v[34:35]
	v_add_u32_e32 v114, 0x5800, v211
	ds_write2_b32 v106, v153, v101 offset0:192 offset1:208
	v_mad_u32_u24 v106, v220, s83, 0
	v_pk_mul_f32 v[158:159], v[148:149], v[64:65]
	ds_write2_b32 v211, v194, v146 offset1:16
	v_add_u32_e32 v148, 0x9000, v211
	ds_write2_b32 v102, v179, v111 offset0:64 offset1:80
	v_pk_mul_f32 v[156:157], v[124:125], v[36:37]
	v_pk_mul_f32 v[102:103], v[116:117], v[36:37]
	ds_write2_b32 v114, v160, v104 offset0:128 offset1:144
	v_add_u32_e32 v114, 0xe800, v211
	v_cmp_eq_u32_e64 s[10:11], 0, v220
	v_cmp_ne_u32_e32 vcc, 0, v220
	v_mov_b32_e32 v213, 0
	v_lshl_add_u32 v211, v162, 2, v106
	v_mov_b32_e32 v224, 0
	ds_write2_b32 v148, v203, v159 offset1:16
	ds_write2_b32 v114, v157, v103 offset0:128 offset1:144
	s_waitcnt vmcnt(0) lgkmcnt(0)
	s_barrier
; __device__ __forceinline__ float erf_f32(float x) {
;   const float ax = fabsf(x);
;   const float t = __frcp_rn(fmaf(0.3275911f, ax, 1.0f));
;   float poly = fmaf(1.061405429f, t, -1.453152027f);
;   poly = fmaf(poly, t, 1.421413741f);
;   poly = fmaf(poly, t, -0.284496736f);
;   poly = fmaf(poly, t, 0.254829592f);
;   const float y = 1.0f - poly * t * __expf(-ax * ax);
; template <int EPI>
; __device__ __forceinline__ void phase_gemm(const Params& p, const GemmDesc& d, char* shmc) {
;     ...
;       float gp[2][4][2], gn[2][4][2];
; #pragma unroll
;       for (int ai = 0; ai < 2; ++ai)
; #pragma unroll
;         for (int m = 0; m < 4; ++m)
; #pragma unroll
;           for (int n = 0; n < 2; ++n) {
;             const int s = ai * 32 + ewr * 16 + m * 4 + efq;
;             const int col = ewc * 32 + n * 16 + efr;
;             gp[ai][m][n] = (s > 0) ? bot[(s - 1) * 144 + col] : 0.f;
;             gn[ai][m][n] = (s < 63) ? top[(s + 1) * 144 + col] : 0.f;
;           }
;       float* edge = p.edge + (size_t)pm * 6 * DFF;
; #pragma unroll
;       for (int n = 0; n < 2; ++n) {
;         const int col = ewc * 32 + n * 16 + efr;
;         const int ch = ch0 + col;
;         const float w0 = cw[n][0], w1 = cw[n][1], w2 = cw[n][2], cb = cw[n][3];
; #pragma unroll
;         for (int ai = 0; ai < 2; ++ai)
; #pragma unroll
;           for (int m = 0; m < 4; ++m) {
;             const int s = ai * 32 + ewr * 16 + m * 4 + efq;
;             const f32x4 g = acc[ai][0][m][n];
;             const f32x4 v = acc[ai][1][m][n];
;             const float c0 = w0 * gp[ai][m][n] + w1 * g[0] + w2 * g[1] + cb;
;             const float c1 = w0 * g[0] + w1 * g[1] + w2 * g[2] + cb;
;             const float c2 = w0 * g[1] + w1 * g[2] + w2 * g[3] + cb;
;             const float c3 = w0 * g[2] + w1 * g[3] + w2 * gn[ai][m][n] + cb;
;             u16* sp = stg + (s * 4) * 136 + col;
;             sp[0] = f2bf(gelu_exact(c0) * v[0]);
;             sp[136] = f2bf(gelu_exact(c1) * v[1]);
;             sp[272] = f2bf(gelu_exact(c2) * v[2]);
;             sp[408] = f2bf(gelu_exact(c3) * v[3]);
;             if (s == 0) {
;               edge[0 * DFF + ch] = c0; edge[1 * DFF + ch] = g[0]; edge[2 * DFF + ch] = v[0];
;             }
;             if (s == 63) {
;               edge[3 * DFF + ch] = c3; edge[4 * DFF + ch] = g[3]; edge[5 * DFF + ch] = v[3];
;             }
;           }
	s_and_saveexec_b64 s[8:9], vcc
	ds_read_b32 v224, v211 offset:36288
	s_or_b64 exec, exec, s[8:9]
	ds_read_b32 v223, v211 offset:576
	s_and_saveexec_b64 s[8:9], vcc
	ds_read_b32 v213, v211 offset:36352
	s_or_b64 exec, exec, s[8:9]
	v_add_u32_e32 v106, 0x9400, v211
	ds_read2_b32 v[150:151], v106 offset0:176 offset1:192
	v_add_u32_e32 v106, 0x800, v211
	ds_read2_b32 v[148:149], v106 offset0:208 offset1:224
	v_add_u32_e32 v106, 0x9e00, v211
	ds_read2_b32 v[140:141], v106 offset0:112 offset1:128
	v_add_u32_e32 v106, 0x1400, v211
	ds_read2_b32 v[138:139], v106 offset0:16 offset1:32
	v_add_u32_e32 v106, 0xa800, v211
	ds_read2_b32 v[132:133], v106 offset0:48 offset1:64
	v_add_u32_e32 v106, 0x1c00, v211
	ds_read2_b32 v[130:131], v106 offset0:80 offset1:96
	v_add_u32_e32 v106, 0xd400, v211
	ds_read2_b32 v[124:125], v106 offset0:112 offset1:128
	v_add_u32_e32 v106, 0x4800, v211
	ds_read2_b32 v[122:123], v106 offset0:144 offset1:160
	v_add_u32_e32 v106, 0xdc00, v211
	ds_read2_b32 v[116:117], v106 offset0:176 offset1:192
	v_add_u32_e32 v106, 0x5000, v211
	ds_read2_b32 v[114:115], v106 offset0:208 offset1:224
	v_add_u32_e32 v106, 0xe600, v211
	ds_read2_b32 v[108:109], v106 offset0:112 offset1:128
	v_add_u32_e32 v106, 0x5c00, v211
	ds_read2_b32 v[106:107], v106 offset0:16 offset1:32
	ds_read_b32 v214, v211 offset:640
	ds_read_b32 v221, v211 offset:61632
	v_cmp_eq_u32_e64 s[8:9], 19, v220
	v_cmp_ne_u32_e32 vcc, 19, v220
	v_add_u32_e32 v222, 0x6300, v211
	v_mov_b32_e32 v211, 0
	v_mov_b32_e32 v219, 0
	s_and_saveexec_b64 s[56:57], vcc
	ds_read_b32 v219, v222 offset:576
	s_or_b64 exec, exec, s[56:57]
	ds_read_b32 v212, v222 offset:36352
	s_and_saveexec_b64 s[56:57], vcc
	ds_read_b32 v211, v222 offset:640
	s_or_b64 exec, exec, s[56:57]
	s_mul_hi_i32 s34, s14, 0x21000
	s_mul_i32 s14, s14, 0x21000
	v_readlane_b32 s56, v246, 15
	v_readlane_b32 s57, v246, 16
	s_add_u32 s56, s56, s14
	s_addc_u32 s57, s57, s34
	v_pk_mul_f32 v[226:227], v[96:97], v[64:65]
	v_pk_mul_f32 v[96:97], v[94:95], v[62:63]
	v_lshl_add_u64 v[94:95], v[200:201], 2, s[56:57]
	s_waitcnt lgkmcnt(14)
	v_mul_f32_e32 v200, v215, v224
	v_fmac_f32_e32 v200, v217, v194
	v_mul_f32_e32 v224, v217, v202
	v_fmac_f32_e32 v200, v216, v195
	v_mul_f32_e32 v201, v217, v195
	v_fmac_f32_e32 v224, v215, v195
	v_add_f32_e32 v200, v218, v200
	v_fmac_f32_e32 v201, v215, v194
	v_fmac_f32_e32 v224, v216, v203
	v_mul_f32_e32 v203, v217, v203
	v_fmac_f32_e32 v201, v216, v202
	v_fmac_f32_e32 v203, v215, v202
	v_mul_f32_e32 v202, 0x3f3504f3, v200
	v_fmac_f32_e32 v203, v216, v223
	v_fma_f32 v223, |v202|, s85, 1.0
	v_add_f32_e32 v195, v218, v224
	v_add_f32_e32 v201, v218, v201
	v_mul_f32_e32 v229, 0.5, v200
	s_add_i32 s14, 0, 0x12000
	v_rcp_f32_e32 v223, v223
	v_mul_f32_e64 v225, |v202|, -|v202|
	v_fmamk_f32 v224, v223, 0x3f87dc22, v206
	v_mul_f32_e32 v225, 0x3fb8aa3b, v225
	v_fmaak_f32 v224, v224, v223, 0x3fb5f0e3
	v_exp_f32_e32 v225, v225
	v_fmaak_f32 v224, v224, v223, 0xbe91a98e
	v_fmaak_f32 v224, v224, v223, 0x3e827906
	v_mul_f32_e32 v223, v223, v224
	v_fma_f32 v223, -v225, v223, 1.0
	v_bfi_b32 v202, s86, v223, v202
	v_mul_f32_e32 v223, 0x3f3504f3, v201
	v_fma_f32 v224, |v223|, s85, 1.0
	v_add_f32_e32 v202, 1.0, v202
	v_mul_f32_e32 v202, v229, v202
	v_lshl_add_u32 v222, v162, 1, s14
	v_mul_f32_e32 v202, v96, v202
	v_mad_u32_u24 v228, v220, s84, v222
	v_cvt_pk_bf16_f32 v202, v202, s0
	ds_write_b16 v228, v202
	v_rcp_f32_e32 v202, v224
	v_mul_f32_e64 v225, |v223|, -|v223|
	v_fmamk_f32 v224, v202, 0x3f87dc22, v206
	v_mul_f32_e32 v225, 0x3fb8aa3b, v225
	v_fmaak_f32 v224, v224, v202, 0x3fb5f0e3
	v_exp_f32_e32 v225, v225
	v_fmaak_f32 v224, v224, v202, 0xbe91a98e
	v_fmaak_f32 v224, v224, v202, 0x3e827906
	v_mul_f32_e32 v202, v202, v224
	v_fma_f32 v202, -v225, v202, 1.0
	v_bfi_b32 v202, s86, v202, v223
	v_mul_f32_e32 v201, 0.5, v201
	v_add_f32_e32 v202, 1.0, v202
	v_mul_f32_e32 v201, v201, v202
	v_mul_f32_e32 v97, v97, v201
	v_mul_f32_e32 v201, 0x3f3504f3, v195
	v_fma_f32 v202, |v201|, s85, 1.0
	v_cvt_pk_bf16_f32 v97, v97, s0
	ds_write_b16 v228, v97 offset:272
	v_mul_f32_e32 v97, 0.5, v195
	v_rcp_f32_e32 v195, v202
	v_mul_f32_e64 v223, |v201|, -|v201|
	v_fmamk_f32 v202, v195, 0x3f87dc22, v206
	v_mul_f32_e32 v223, 0x3fb8aa3b, v223
	v_fmaak_f32 v202, v202, v195, 0x3fb5f0e3
	v_exp_f32_e32 v223, v223
	v_fmaak_f32 v202, v202, v195, 0xbe91a98e
	v_fmaak_f32 v202, v202, v195, 0x3e827906
	v_mul_f32_e32 v195, v195, v202
	v_fma_f32 v195, -v223, v195, 1.0
	v_bfi_b32 v195, s86, v195, v201
	v_add_f32_e32 v203, v218, v203
	v_add_f32_e32 v195, 1.0, v195
	v_mul_f32_e32 v97, v97, v195
	v_mul_f32_e32 v195, 0x3f3504f3, v203
	v_fma_f32 v201, |v195|, s85, 1.0
	v_mul_f32_e32 v97, v226, v97
	v_cvt_pk_bf16_f32 v97, v97, s0
	ds_write_b16 v228, v97 offset:544
	v_mul_f32_e32 v97, 0.5, v203
	v_rcp_f32_e32 v201, v201
	v_mul_f32_e64 v203, |v195|, -|v195|
	v_fmamk_f32 v202, v201, 0x3f87dc22, v206
	v_mul_f32_e32 v203, 0x3fb8aa3b, v203
	v_fmaak_f32 v202, v202, v201, 0x3fb5f0e3
	v_exp_f32_e32 v203, v203
	v_fmaak_f32 v202, v202, v201, 0xbe91a98e
	v_fmaak_f32 v202, v202, v201, 0x3e827906
	v_mul_f32_e32 v201, v201, v202
	v_fma_f32 v201, -v203, v201, 1.0
	v_bfi_b32 v195, s86, v201, v195
	v_add_f32_e32 v195, 1.0, v195
	v_mul_f32_e32 v97, v97, v195
	v_mul_f32_e32 v97, v227, v97
	v_readlane_b32 s58, v246, 17
	v_readlane_b32 s59, v246, 18
	v_cvt_pk_bf16_f32 v97, v97, s0
	ds_write_b16 v228, v97 offset:816
	s_and_saveexec_b64 s[58:59], s[10:11]
	s_cbranch_execz .LBB0_1166
	global_store_dword v[94:95], v200, off
	v_add_co_u32_e32 v200, vcc, 0x5000, v94
	s_nop 1
	v_addc_co_u32_e32 v201, vcc, 0, v95, vcc
	global_store_dword v[200:201], v194, off offset:2048
	v_add_co_u32_e32 v194, vcc, 0xb000, v94
	s_nop 1
	v_addc_co_u32_e32 v195, vcc, 0, v95, vcc
	global_store_dword v[194:195], v96, off
; __device__ __forceinline__ u16 f2bf(float f) { return (u16)(pack2(f, f) & 0xffffu); }
; __device__ __forceinline__ float erf_f32(float x) {
;   const float ax = fabsf(x);
;   const float t = __frcp_rn(fmaf(0.3275911f, ax, 1.0f));
;   float poly = fmaf(1.061405429f, t, -1.453152027f);
;   poly = fmaf(poly, t, 1.421413741f);
;   poly = fmaf(poly, t, -0.284496736f);
;   poly = fmaf(poly, t, 0.254829592f);
;   const float y = 1.0f - poly * t * __expf(-ax * ax);
;   return copysignf(y, x);
; }
; __device__ __forceinline__ float gelu_exact(float x) { return 0.5f * x * (1.0f + erf_f32(x * 0.70710678118654752f)); }
; template <int EPI>
; __device__ __forceinline__ void phase_gemm(const Params& p, const GemmDesc& d, char* shmc) {
;     ...
; #pragma unroll
;       for (int n = 0; n < 2; ++n) {
;         const int col = ewc * 32 + n * 16 + efr;
;         const int ch = ch0 + col;
;         const float w0 = cw[n][0], w1 = cw[n][1], w2 = cw[n][2], cb = cw[n][3];
; #pragma unroll
;         for (int ai = 0; ai < 2; ++ai)
; #pragma unroll
;           for (int m = 0; m < 4; ++m) {
;             const int s = ai * 32 + ewr * 16 + m * 4 + efq;
;             const f32x4 g = acc[ai][0][m][n];
;             const f32x4 v = acc[ai][1][m][n];
;             const float c0 = w0 * gp[ai][m][n] + w1 * g[0] + w2 * g[1] + cb;
;             const float c1 = w0 * g[0] + w1 * g[1] + w2 * g[2] + cb;
;             const float c2 = w0 * g[1] + w1 * g[2] + w2 * g[3] + cb;
;             const float c3 = w0 * g[2] + w1 * g[3] + w2 * gn[ai][m][n] + cb;
;             u16* sp = stg + (s * 4) * 136 + col;
;             sp[0] = f2bf(gelu_exact(c0) * v[0]);
;             sp[136] = f2bf(gelu_exact(c1) * v[1]);
;             sp[272] = f2bf(gelu_exact(c2) * v[2]);
;             sp[408] = f2bf(gelu_exact(c3) * v[3]);
;             if (s == 0) {
;               edge[0 * DFF + ch] = c0; edge[1 * DFF + ch] = g[0]; edge[2 * DFF + ch] = v[0];
;             }
;             if (s == 63) {
;               edge[3 * DFF + ch] = c3; edge[4 * DFF + ch] = g[3]; edge[5 * DFF + ch] = v[3];
;             }
;           }
.LBB0_1166:
	s_or_b64 exec, exec, s[58:59]
	v_pk_mul_f32 v[96:97], v[68:69], v[48:49]
	v_pk_mul_f32 v[68:69], v[78:79], v[30:31]
	v_mul_f32_e32 v78, v215, v150
	v_fmac_f32_e32 v78, v217, v198
	v_fmac_f32_e32 v78, v216, v199
	v_add_f32_e32 v79, v218, v78
	v_pk_mul_f32 v[200:201], v[72:73], v[52:53]
	v_pk_mul_f32 v[72:73], v[82:83], v[34:35]
	v_mul_f32_e32 v83, 0x3f3504f3, v79
	v_pk_mul_f32 v[202:203], v[70:71], v[50:51]
	v_pk_mul_f32 v[70:71], v[84:85], v[36:37]
	v_fma_f32 v84, |v83|, s85, 1.0
	v_mul_f32_e32 v78, v217, v199
	v_pk_mul_f32 v[224:225], v[76:77], v[56:57]
	v_pk_mul_f32 v[76:77], v[86:87], v[38:39]
	v_fmac_f32_e32 v78, v215, v198
	v_fmac_f32_e32 v78, v216, v196
	v_pk_mul_f32 v[194:195], v[66:67], v[46:47]
	v_pk_mul_f32 v[66:67], v[80:81], v[32:33]
	v_add_f32_e32 v80, v218, v78
	v_mul_f32_e32 v78, v217, v196
	v_fmac_f32_e32 v78, v215, v199
	v_pk_mul_f32 v[226:227], v[74:75], v[54:55]
	v_pk_mul_f32 v[74:75], v[88:89], v[40:41]
	v_fmac_f32_e32 v78, v216, v197
	v_add_f32_e32 v81, v218, v78
	v_mul_f32_e32 v78, v217, v197
	v_fmac_f32_e32 v78, v215, v196
	s_waitcnt lgkmcnt(14)
	v_fmac_f32_e32 v78, v216, v148
	v_rcp_f32_e32 v84, v84
	v_mul_f32_e64 v86, |v83|, -|v83|
	v_fmamk_f32 v85, v84, 0x3f87dc22, v206
	v_mul_f32_e32 v86, 0x3fb8aa3b, v86
	v_fmaak_f32 v85, v85, v84, 0x3fb5f0e3
	v_exp_f32_e32 v86, v86
	v_fmaak_f32 v85, v85, v84, 0xbe91a98e
	v_fmaak_f32 v85, v85, v84, 0x3e827906
	v_mul_f32_e32 v84, v84, v85
	v_fma_f32 v84, -v86, v84, 1.0
	v_bfi_b32 v83, s86, v84, v83
	v_mul_f32_e32 v79, 0.5, v79
	v_add_f32_e32 v83, 1.0, v83
	v_mul_f32_e32 v79, v79, v83
	v_mul_f32_e32 v83, 0x3f3504f3, v80
	v_fma_f32 v84, |v83|, s85, 1.0
	v_mul_u32_u24_e32 v220, 0x440, v220
	v_add_f32_e32 v82, v218, v78
	v_add_u32_e32 v78, 0x1100, v220
	v_mul_f32_e32 v79, v226, v79
	v_add_u32_e32 v87, v222, v78
	v_cvt_pk_bf16_f32 v79, v79, s0
	ds_write_b16 v87, v79
	v_mul_f32_e32 v79, 0.5, v80
	v_rcp_f32_e32 v80, v84
	v_mul_f32_e64 v85, |v83|, -|v83|
	v_fmamk_f32 v84, v80, 0x3f87dc22, v206
	v_mul_f32_e32 v85, 0x3fb8aa3b, v85
	v_fmaak_f32 v84, v84, v80, 0x3fb5f0e3
	v_exp_f32_e32 v85, v85
	v_fmaak_f32 v84, v84, v80, 0xbe91a98e
	v_fmaak_f32 v84, v84, v80, 0x3e827906
	v_mul_f32_e32 v80, v80, v84
	v_fma_f32 v80, -v85, v80, 1.0
	v_bfi_b32 v80, s86, v80, v83
	v_add_f32_e32 v80, 1.0, v80
	v_mul_f32_e32 v79, v79, v80
	v_mul_f32_e32 v80, 0x3f3504f3, v81
	v_fma_f32 v83, |v80|, s85, 1.0
	v_mul_f32_e32 v79, v227, v79
	v_cvt_pk_bf16_f32 v79, v79, s0
	ds_write_b16 v87, v79 offset:272
	v_mul_f32_e32 v79, 0.5, v81
	v_rcp_f32_e32 v81, v83
	v_mul_f32_e64 v84, |v80|, -|v80|
	v_fmamk_f32 v83, v81, 0x3f87dc22, v206
	v_mul_f32_e32 v84, 0x3fb8aa3b, v84
	v_fmaak_f32 v83, v83, v81, 0x3fb5f0e3
	v_exp_f32_e32 v84, v84
	v_fmaak_f32 v83, v83, v81, 0xbe91a98e
	v_fmaak_f32 v83, v83, v81, 0x3e827906
	v_mul_f32_e32 v81, v81, v83
	v_fma_f32 v81, -v84, v81, 1.0
	v_bfi_b32 v80, s86, v81, v80
	v_add_f32_e32 v80, 1.0, v80
	v_mul_f32_e32 v79, v79, v80
	v_mul_f32_e32 v80, 0x3f3504f3, v82
	v_fma_f32 v81, |v80|, s85, 1.0
	v_mul_f32_e32 v79, v224, v79
	v_cvt_pk_bf16_f32 v79, v79, s0
	ds_write_b16 v87, v79 offset:544
	v_mul_f32_e32 v79, 0.5, v82
	v_rcp_f32_e32 v81, v81
	v_mul_f32_e64 v83, |v80|, -|v80|
	v_fmamk_f32 v82, v81, 0x3f87dc22, v206
	v_mul_f32_e32 v83, 0x3fb8aa3b, v83
	v_fmaak_f32 v82, v82, v81, 0x3fb5f0e3
	v_exp_f32_e32 v83, v83
	v_fmaak_f32 v82, v82, v81, 0xbe91a98e
	v_fmaak_f32 v82, v82, v81, 0x3e827906
	v_mul_f32_e32 v81, v81, v82
	v_fma_f32 v81, -v83, v81, 1.0
	v_bfi_b32 v80, s86, v81, v80
	v_add_f32_e32 v80, 1.0, v80
	v_mul_f32_e32 v79, v79, v80
	v_mul_f32_e32 v79, v225, v79
	v_cvt_pk_bf16_f32 v79, v79, s0
	ds_write_b16 v87, v79 offset:816
	v_mul_f32_e32 v79, v215, v140
	v_fmac_f32_e32 v79, v217, v192
	v_fmac_f32_e32 v79, v216, v193
	v_add_f32_e32 v80, v218, v79
	v_mul_f32_e32 v84, 0x3f3504f3, v80
	v_mul_f32_e32 v79, v217, v193
	v_fma_f32 v85, |v84|, s85, 1.0
	v_fmac_f32_e32 v79, v215, v192
	v_fmac_f32_e32 v79, v216, v190
	v_add_f32_e32 v81, v218, v79
	v_mul_f32_e32 v79, v217, v190
	v_fmac_f32_e32 v79, v215, v193
	v_fmac_f32_e32 v79, v216, v191
	v_add_f32_e32 v82, v218, v79
	v_mul_f32_e32 v79, v217, v191
	v_fmac_f32_e32 v79, v215, v190
	v_fmac_f32_e32 v79, v216, v138
	v_rcp_f32_e32 v85, v85
	v_mul_f32_e64 v87, |v84|, -|v84|
	v_fmamk_f32 v86, v85, 0x3f87dc22, v206
	v_mul_f32_e32 v87, 0x3fb8aa3b, v87
	v_fmaak_f32 v86, v86, v85, 0x3fb5f0e3
	v_exp_f32_e32 v87, v87
	v_fmaak_f32 v86, v86, v85, 0xbe91a98e
	v_fmaak_f32 v86, v86, v85, 0x3e827906
	v_mul_f32_e32 v85, v85, v86
	v_fma_f32 v85, -v87, v85, 1.0
	v_bfi_b32 v84, s86, v85, v84
	v_mul_f32_e32 v80, 0.5, v80
	v_add_f32_e32 v84, 1.0, v84
	v_mul_f32_e32 v80, v80, v84
	v_mul_f32_e32 v84, 0x3f3504f3, v81
	v_fma_f32 v85, |v84|, s85, 1.0
	v_add_f32_e32 v83, v218, v79
	v_add_u32_e32 v79, 0x2200, v220
	v_mul_f32_e32 v80, v202, v80
	v_add_u32_e32 v88, v222, v79
	v_cvt_pk_bf16_f32 v80, v80, s0
	ds_write_b16 v88, v80
	v_mul_f32_e32 v80, 0.5, v81
	v_rcp_f32_e32 v81, v85
	v_mul_f32_e64 v86, |v84|, -|v84|
	v_fmamk_f32 v85, v81, 0x3f87dc22, v206
	v_mul_f32_e32 v86, 0x3fb8aa3b, v86
	v_fmaak_f32 v85, v85, v81, 0x3fb5f0e3
	v_exp_f32_e32 v86, v86
	v_fmaak_f32 v85, v85, v81, 0xbe91a98e
	v_fmaak_f32 v85, v85, v81, 0x3e827906
	v_mul_f32_e32 v81, v81, v85
	v_fma_f32 v81, -v86, v81, 1.0
	v_bfi_b32 v81, s86, v81, v84
	v_add_f32_e32 v81, 1.0, v81
	v_mul_f32_e32 v80, v80, v81
	v_mul_f32_e32 v81, 0x3f3504f3, v82
	v_fma_f32 v84, |v81|, s85, 1.0
	v_mul_f32_e32 v80, v203, v80
	v_cvt_pk_bf16_f32 v80, v80, s0
	ds_write_b16 v88, v80 offset:272
	v_mul_f32_e32 v80, 0.5, v82
	v_rcp_f32_e32 v82, v84
	v_mul_f32_e64 v85, |v81|, -|v81|
	v_fmamk_f32 v84, v82, 0x3f87dc22, v206
; __device__ __forceinline__ u16 f2bf(float f) { return (u16)(pack2(f, f) & 0xffffu); }
; __device__ __forceinline__ float erf_f32(float x) {
;   const float ax = fabsf(x);
;   const float t = __frcp_rn(fmaf(0.3275911f, ax, 1.0f));
;   float poly = fmaf(1.061405429f, t, -1.453152027f);
;   poly = fmaf(poly, t, 1.421413741f);
;   poly = fmaf(poly, t, -0.284496736f);
;   poly = fmaf(poly, t, 0.254829592f);
;   const float y = 1.0f - poly * t * __expf(-ax * ax);
;   return copysignf(y, x);
; }
; __device__ __forceinline__ float gelu_exact(float x) { return 0.5f * x * (1.0f + erf_f32(x * 0.70710678118654752f)); }
; template <int EPI>
; __device__ __forceinline__ void phase_gemm(const Params& p, const GemmDesc& d, char* shmc) {
;     ...
; #pragma unroll
;       for (int n = 0; n < 2; ++n) {
;         const int col = ewc * 32 + n * 16 + efr;
;         const int ch = ch0 + col;
;         const float w0 = cw[n][0], w1 = cw[n][1], w2 = cw[n][2], cb = cw[n][3];
; #pragma unroll
;         for (int ai = 0; ai < 2; ++ai)
; #pragma unroll
;           for (int m = 0; m < 4; ++m) {
;             const int s = ai * 32 + ewr * 16 + m * 4 + efq;
;             const f32x4 g = acc[ai][0][m][n];
;             const f32x4 v = acc[ai][1][m][n];
;             const float c0 = w0 * gp[ai][m][n] + w1 * g[0] + w2 * g[1] + cb;
;             const float c1 = w0 * g[0] + w1 * g[1] + w2 * g[2] + cb;
;             const float c2 = w0 * g[1] + w1 * g[2] + w2 * g[3] + cb;
;             const float c3 = w0 * g[2] + w1 * g[3] + w2 * gn[ai][m][n] + cb;
;             u16* sp = stg + (s * 4) * 136 + col;
;             sp[0] = f2bf(gelu_exact(c0) * v[0]);
;             sp[136] = f2bf(gelu_exact(c1) * v[1]);
;             sp[272] = f2bf(gelu_exact(c2) * v[2]);
;             sp[408] = f2bf(gelu_exact(c3) * v[3]);
;             if (s == 0) {
;               edge[0 * DFF + ch] = c0; edge[1 * DFF + ch] = g[0]; edge[2 * DFF + ch] = v[0];
;             }
;             if (s == 63) {
;               edge[3 * DFF + ch] = c3; edge[4 * DFF + ch] = g[3]; edge[5 * DFF + ch] = v[3];
;             }
;           }
	v_mul_f32_e32 v85, 0x3fb8aa3b, v85
	v_fmaak_f32 v84, v84, v82, 0x3fb5f0e3
	v_exp_f32_e32 v85, v85
	v_fmaak_f32 v84, v84, v82, 0xbe91a98e
	v_fmaak_f32 v84, v84, v82, 0x3e827906
	v_mul_f32_e32 v82, v82, v84
	v_fma_f32 v82, -v85, v82, 1.0
	v_bfi_b32 v81, s86, v82, v81
	v_add_f32_e32 v81, 1.0, v81
	v_mul_f32_e32 v80, v80, v81
	v_mul_f32_e32 v81, 0x3f3504f3, v83
	v_fma_f32 v82, |v81|, s85, 1.0
	v_mul_f32_e32 v80, v200, v80
	v_cvt_pk_bf16_f32 v80, v80, s0
	ds_write_b16 v88, v80 offset:544
	v_mul_f32_e32 v80, 0.5, v83
	v_rcp_f32_e32 v82, v82
	v_mul_f32_e64 v84, |v81|, -|v81|
	v_fmamk_f32 v83, v82, 0x3f87dc22, v206
	v_mul_f32_e32 v84, 0x3fb8aa3b, v84
	v_fmaak_f32 v83, v83, v82, 0x3fb5f0e3
	v_exp_f32_e32 v84, v84
	v_fmaak_f32 v83, v83, v82, 0xbe91a98e
	v_fmaak_f32 v83, v83, v82, 0x3e827906
	v_mul_f32_e32 v82, v82, v83
	v_fma_f32 v82, -v84, v82, 1.0
	v_bfi_b32 v81, s86, v82, v81
	v_add_f32_e32 v81, 1.0, v81
	v_mul_f32_e32 v80, v80, v81
	v_mul_f32_e32 v80, v201, v80
	v_cvt_pk_bf16_f32 v80, v80, s0
	ds_write_b16 v88, v80 offset:816
	v_mul_f32_e32 v80, v215, v132
	v_fmac_f32_e32 v80, v217, v188
	v_fmac_f32_e32 v80, v216, v189
	v_add_f32_e32 v81, v218, v80
	v_mul_f32_e32 v80, v217, v189
	v_fmac_f32_e32 v80, v215, v188
	v_mul_f32_e32 v85, 0x3f3504f3, v81
	v_fmac_f32_e32 v80, v216, v186
	v_fma_f32 v86, |v85|, s85, 1.0
	v_add_f32_e32 v82, v218, v80
	v_mul_f32_e32 v80, v217, v186
	v_fmac_f32_e32 v80, v215, v189
	v_fmac_f32_e32 v80, v216, v187
	v_add_f32_e32 v83, v218, v80
	v_mul_f32_e32 v80, v217, v187
	v_fmac_f32_e32 v80, v215, v186
	s_waitcnt lgkmcnt(14)
	v_fmac_f32_e32 v80, v216, v130
	v_rcp_f32_e32 v86, v86
	v_mul_f32_e64 v88, |v85|, -|v85|
	v_fmamk_f32 v87, v86, 0x3f87dc22, v206
	v_mul_f32_e32 v88, 0x3fb8aa3b, v88
	v_fmaak_f32 v87, v87, v86, 0x3fb5f0e3
	v_exp_f32_e32 v88, v88
	v_fmaak_f32 v87, v87, v86, 0xbe91a98e
	v_fmaak_f32 v87, v87, v86, 0x3e827906
	v_mul_f32_e32 v86, v86, v87
	v_fma_f32 v86, -v88, v86, 1.0
	v_bfi_b32 v85, s86, v86, v85
	v_mul_f32_e32 v81, 0.5, v81
	v_add_f32_e32 v85, 1.0, v85
	v_mul_f32_e32 v81, v81, v85
	v_mul_f32_e32 v85, 0x3f3504f3, v82
	v_fma_f32 v86, |v85|, s85, 1.0
	v_add_f32_e32 v84, v218, v80
	v_add_u32_e32 v80, 0x3300, v220
	v_mul_f32_e32 v81, v194, v81
	v_add_u32_e32 v89, v222, v80
	v_cvt_pk_bf16_f32 v81, v81, s0
	ds_write_b16 v89, v81
	v_mul_f32_e32 v81, 0.5, v82
	v_rcp_f32_e32 v82, v86
	v_mul_f32_e64 v87, |v85|, -|v85|
	v_fmamk_f32 v86, v82, 0x3f87dc22, v206
	v_mul_f32_e32 v87, 0x3fb8aa3b, v87
	v_fmaak_f32 v86, v86, v82, 0x3fb5f0e3
	v_exp_f32_e32 v87, v87
	v_fmaak_f32 v86, v86, v82, 0xbe91a98e
	v_fmaak_f32 v86, v86, v82, 0x3e827906
	v_mul_f32_e32 v82, v82, v86
	v_fma_f32 v82, -v87, v82, 1.0
	v_bfi_b32 v82, s86, v82, v85
	v_add_f32_e32 v82, 1.0, v82
	v_mul_f32_e32 v81, v81, v82
	v_mul_f32_e32 v82, 0x3f3504f3, v83
	v_fma_f32 v85, |v82|, s85, 1.0
	v_mul_f32_e32 v81, v195, v81
	v_cvt_pk_bf16_f32 v81, v81, s0
	ds_write_b16 v89, v81 offset:272
	v_mul_f32_e32 v81, 0.5, v83
	v_rcp_f32_e32 v83, v85
	v_mul_f32_e64 v86, |v82|, -|v82|
	v_fmamk_f32 v85, v83, 0x3f87dc22, v206
	v_mul_f32_e32 v86, 0x3fb8aa3b, v86
	v_fmaak_f32 v85, v85, v83, 0x3fb5f0e3
	v_exp_f32_e32 v86, v86
	v_fmaak_f32 v85, v85, v83, 0xbe91a98e
	v_fmaak_f32 v85, v85, v83, 0x3e827906
	v_mul_f32_e32 v83, v83, v85
	v_fma_f32 v83, -v86, v83, 1.0
	v_bfi_b32 v82, s86, v83, v82
	v_add_f32_e32 v82, 1.0, v82
	v_mul_f32_e32 v81, v81, v82
	v_mul_f32_e32 v82, 0x3f3504f3, v84
	v_fma_f32 v83, |v82|, s85, 1.0
	v_mul_f32_e32 v81, v96, v81
	v_cvt_pk_bf16_f32 v81, v81, s0
	ds_write_b16 v89, v81 offset:544
	v_mul_f32_e32 v81, 0.5, v84
	v_rcp_f32_e32 v83, v83
	v_mul_f32_e64 v85, |v82|, -|v82|
	v_fmamk_f32 v84, v83, 0x3f87dc22, v206
	v_mul_f32_e32 v85, 0x3fb8aa3b, v85
	v_fmaak_f32 v84, v84, v83, 0x3fb5f0e3
	v_exp_f32_e32 v85, v85
	v_fmaak_f32 v84, v84, v83, 0xbe91a98e
	v_fmaak_f32 v84, v84, v83, 0x3e827906
	v_mul_f32_e32 v83, v83, v84
	v_fma_f32 v83, -v85, v83, 1.0
	v_bfi_b32 v82, s86, v83, v82
	v_add_f32_e32 v82, 1.0, v82
	v_mul_f32_e32 v81, v81, v82
	v_mul_f32_e32 v81, v97, v81
	v_cvt_pk_bf16_f32 v81, v81, s0
	ds_write_b16 v89, v81 offset:816
	v_mul_f32_e32 v81, v215, v124
	v_fmac_f32_e32 v81, v217, v184
	v_fmac_f32_e32 v81, v216, v185
	v_add_f32_e32 v82, v218, v81
	v_mul_f32_e32 v86, 0x3f3504f3, v82
	v_mul_f32_e32 v81, v217, v185
	v_fma_f32 v87, |v86|, s85, 1.0
	v_fmac_f32_e32 v81, v215, v184
	v_fmac_f32_e32 v81, v216, v182
	v_add_f32_e32 v83, v218, v81
	v_mul_f32_e32 v81, v217, v182
	v_fmac_f32_e32 v81, v215, v185
	v_fmac_f32_e32 v81, v216, v183
	v_add_f32_e32 v84, v218, v81
	v_mul_f32_e32 v81, v217, v183
	v_fmac_f32_e32 v81, v215, v182
	v_fmac_f32_e32 v81, v216, v122
	v_rcp_f32_e32 v87, v87
	v_mul_f32_e64 v89, |v86|, -|v86|
	v_fmamk_f32 v88, v87, 0x3f87dc22, v206
	v_mul_f32_e32 v89, 0x3fb8aa3b, v89
	v_fmaak_f32 v88, v88, v87, 0x3fb5f0e3
	v_exp_f32_e32 v89, v89
	v_fmaak_f32 v88, v88, v87, 0xbe91a98e
	v_fmaak_f32 v88, v88, v87, 0x3e827906
	v_mul_f32_e32 v87, v87, v88
	v_fma_f32 v87, -v89, v87, 1.0
	v_bfi_b32 v86, s86, v87, v86
	v_mul_f32_e32 v82, 0.5, v82
	v_add_f32_e32 v86, 1.0, v86
	v_mul_f32_e32 v82, v82, v86
	v_mul_f32_e32 v86, 0x3f3504f3, v83
	v_fma_f32 v87, |v86|, s85, 1.0
	v_pk_mul_f32 v[90:91], v[90:91], v[42:43]
	v_add_f32_e32 v85, v218, v81
	v_add_u32_e32 v81, 0x8800, v220
	v_mul_f32_e32 v82, v90, v82
	v_add_u32_e32 v96, v222, v81
	v_cvt_pk_bf16_f32 v82, v82, s0
	ds_write_b16 v96, v82
	v_mul_f32_e32 v82, 0.5, v83
	v_rcp_f32_e32 v83, v87
	v_mul_f32_e64 v88, |v86|, -|v86|
	v_fmamk_f32 v87, v83, 0x3f87dc22, v206
	v_mul_f32_e32 v88, 0x3fb8aa3b, v88
	v_fmaak_f32 v87, v87, v83, 0x3fb5f0e3
	v_exp_f32_e32 v88, v88
	v_fmaak_f32 v87, v87, v83, 0xbe91a98e
	v_fmaak_f32 v87, v87, v83, 0x3e827906
; __device__ __forceinline__ u16 f2bf(float f) { return (u16)(pack2(f, f) & 0xffffu); }
; __device__ __forceinline__ float erf_f32(float x) {
;   const float ax = fabsf(x);
;   const float t = __frcp_rn(fmaf(0.3275911f, ax, 1.0f));
;   float poly = fmaf(1.061405429f, t, -1.453152027f);
;   poly = fmaf(poly, t, 1.421413741f);
;   poly = fmaf(poly, t, -0.284496736f);
;   poly = fmaf(poly, t, 0.254829592f);
;   const float y = 1.0f - poly * t * __expf(-ax * ax);
;   return copysignf(y, x);
; }
; __device__ __forceinline__ float gelu_exact(float x) { return 0.5f * x * (1.0f + erf_f32(x * 0.70710678118654752f)); }
; template <int EPI>
; __device__ __forceinline__ void phase_gemm(const Params& p, const GemmDesc& d, char* shmc) {
;     ...
; #pragma unroll
;       for (int n = 0; n < 2; ++n) {
;         const int col = ewc * 32 + n * 16 + efr;
;         const int ch = ch0 + col;
;         const float w0 = cw[n][0], w1 = cw[n][1], w2 = cw[n][2], cb = cw[n][3];
; #pragma unroll
;         for (int ai = 0; ai < 2; ++ai)
; #pragma unroll
;           for (int m = 0; m < 4; ++m) {
;             const int s = ai * 32 + ewr * 16 + m * 4 + efq;
;             const f32x4 g = acc[ai][0][m][n];
;             const f32x4 v = acc[ai][1][m][n];
;             const float c0 = w0 * gp[ai][m][n] + w1 * g[0] + w2 * g[1] + cb;
;             const float c1 = w0 * g[0] + w1 * g[1] + w2 * g[2] + cb;
;             const float c2 = w0 * g[1] + w1 * g[2] + w2 * g[3] + cb;
;             const float c3 = w0 * g[2] + w1 * g[3] + w2 * gn[ai][m][n] + cb;
;             u16* sp = stg + (s * 4) * 136 + col;
;             sp[0] = f2bf(gelu_exact(c0) * v[0]);
;             sp[136] = f2bf(gelu_exact(c1) * v[1]);
;             sp[272] = f2bf(gelu_exact(c2) * v[2]);
;             sp[408] = f2bf(gelu_exact(c3) * v[3]);
;             if (s == 0) {
;               edge[0 * DFF + ch] = c0; edge[1 * DFF + ch] = g[0]; edge[2 * DFF + ch] = v[0];
;             }
;             if (s == 63) {
;               edge[3 * DFF + ch] = c3; edge[4 * DFF + ch] = g[3]; edge[5 * DFF + ch] = v[3];
;             }
;           }
	v_mul_f32_e32 v83, v83, v87
	v_fma_f32 v83, -v88, v83, 1.0
	v_bfi_b32 v83, s86, v83, v86
	v_add_f32_e32 v83, 1.0, v83
	v_mul_f32_e32 v82, v82, v83
	v_mul_f32_e32 v83, 0x3f3504f3, v84
	v_fma_f32 v86, |v83|, s85, 1.0
	v_mul_f32_e32 v82, v91, v82
	v_cvt_pk_bf16_f32 v82, v82, s0
	ds_write_b16 v96, v82 offset:272
	v_mul_f32_e32 v82, 0.5, v84
	v_rcp_f32_e32 v84, v86
	v_mul_f32_e64 v87, |v83|, -|v83|
	v_fmamk_f32 v86, v84, 0x3f87dc22, v206
	v_mul_f32_e32 v87, 0x3fb8aa3b, v87
	v_fmaak_f32 v86, v86, v84, 0x3fb5f0e3
	v_exp_f32_e32 v87, v87
	v_fmaak_f32 v86, v86, v84, 0xbe91a98e
	v_fmaak_f32 v86, v86, v84, 0x3e827906
	v_mul_f32_e32 v84, v84, v86
	v_fma_f32 v84, -v87, v84, 1.0
	v_bfi_b32 v83, s86, v84, v83
	v_add_f32_e32 v83, 1.0, v83
	v_mul_f32_e32 v82, v82, v83
	v_mul_f32_e32 v83, 0x3f3504f3, v85
	v_fma_f32 v84, |v83|, s85, 1.0
	v_pk_mul_f32 v[92:93], v[92:93], v[44:45]
	s_nop 0
	v_mul_f32_e32 v82, v92, v82
	v_cvt_pk_bf16_f32 v82, v82, s0
	ds_write_b16 v96, v82 offset:544
	v_mul_f32_e32 v82, 0.5, v85
	v_rcp_f32_e32 v84, v84
	v_mul_f32_e64 v86, |v83|, -|v83|
	v_fmamk_f32 v85, v84, 0x3f87dc22, v206
	v_mul_f32_e32 v86, 0x3fb8aa3b, v86
	v_fmaak_f32 v85, v85, v84, 0x3fb5f0e3
	v_exp_f32_e32 v86, v86
	v_fmaak_f32 v85, v85, v84, 0xbe91a98e
	v_fmaak_f32 v85, v85, v84, 0x3e827906
	v_mul_f32_e32 v84, v84, v85
	v_fma_f32 v84, -v86, v84, 1.0
	v_bfi_b32 v83, s86, v84, v83
	v_add_f32_e32 v83, 1.0, v83
	v_mul_f32_e32 v82, v82, v83
	v_mul_f32_e32 v82, v93, v82
	v_cvt_pk_bf16_f32 v82, v82, s0
	ds_write_b16 v96, v82 offset:816
	v_mul_f32_e32 v82, v215, v116
	v_fmac_f32_e32 v82, v217, v180
	v_fmac_f32_e32 v82, v216, v181
	v_add_f32_e32 v83, v218, v82
	v_mul_f32_e32 v87, 0x3f3504f3, v83
	v_fma_f32 v88, |v87|, s85, 1.0
	v_mul_f32_e32 v82, v217, v181
	v_fmac_f32_e32 v82, v215, v180
	v_fmac_f32_e32 v82, v216, v178
	v_rcp_f32_e32 v88, v88
	v_mul_f32_e64 v90, |v87|, -|v87|
	v_fmamk_f32 v89, v88, 0x3f87dc22, v206
	v_mul_f32_e32 v90, 0x3fb8aa3b, v90
	v_fmaak_f32 v89, v89, v88, 0x3fb5f0e3
	v_exp_f32_e32 v90, v90
	v_fmaak_f32 v89, v89, v88, 0xbe91a98e
	v_fmaak_f32 v89, v89, v88, 0x3e827906
	v_mul_f32_e32 v88, v88, v89
	v_fma_f32 v88, -v90, v88, 1.0
	v_bfi_b32 v87, s86, v88, v87
	v_mul_f32_e32 v83, 0.5, v83
	v_add_f32_e32 v87, 1.0, v87
	v_add_f32_e32 v84, v218, v82
	v_mul_f32_e32 v82, v217, v178
	v_mul_f32_e32 v83, v83, v87
	v_fmac_f32_e32 v82, v215, v181
	v_mul_f32_e32 v76, v76, v83
	v_mul_f32_e32 v83, 0x3f3504f3, v84
	v_fmac_f32_e32 v82, v216, v179
	v_fma_f32 v87, |v83|, s85, 1.0
	v_add_f32_e32 v85, v218, v82
	v_mul_f32_e32 v82, v217, v179
	v_fmac_f32_e32 v82, v215, v178
	v_fmac_f32_e32 v82, v216, v114
	v_add_f32_e32 v86, v218, v82
	v_add_u32_e32 v82, 0x9900, v220
	v_add_u32_e32 v91, v222, v82
	v_cvt_pk_bf16_f32 v76, v76, s0
	ds_write_b16 v91, v76
	v_mul_f32_e32 v76, 0.5, v84
	v_rcp_f32_e32 v84, v87
	v_mul_f32_e64 v88, |v83|, -|v83|
	v_fmamk_f32 v87, v84, 0x3f87dc22, v206
	v_mul_f32_e32 v88, 0x3fb8aa3b, v88
	v_fmaak_f32 v87, v87, v84, 0x3fb5f0e3
	v_exp_f32_e32 v88, v88
	v_fmaak_f32 v87, v87, v84, 0xbe91a98e
	v_fmaak_f32 v87, v87, v84, 0x3e827906
	v_mul_f32_e32 v84, v84, v87
	v_fma_f32 v84, -v88, v84, 1.0
	v_bfi_b32 v83, s86, v84, v83
	v_add_f32_e32 v83, 1.0, v83
	v_mul_f32_e32 v76, v76, v83
	v_mul_f32_e32 v76, v77, v76
	v_mul_f32_e32 v77, 0x3f3504f3, v85
	v_fma_f32 v83, |v77|, s85, 1.0
	v_cvt_pk_bf16_f32 v76, v76, s0
	ds_write_b16 v91, v76 offset:272
	v_mul_f32_e32 v76, 0.5, v85
	v_rcp_f32_e32 v83, v83
	v_mul_f32_e64 v85, |v77|, -|v77|
	v_fmamk_f32 v84, v83, 0x3f87dc22, v206
	v_mul_f32_e32 v85, 0x3fb8aa3b, v85
	v_fmaak_f32 v84, v84, v83, 0x3fb5f0e3
	v_exp_f32_e32 v85, v85
	v_fmaak_f32 v84, v84, v83, 0xbe91a98e
	v_fmaak_f32 v84, v84, v83, 0x3e827906
	v_mul_f32_e32 v83, v83, v84
	v_fma_f32 v83, -v85, v83, 1.0
	v_bfi_b32 v77, s86, v83, v77
	v_add_f32_e32 v77, 1.0, v77
	v_mul_f32_e32 v76, v76, v77
	v_mul_f32_e32 v74, v74, v76
	v_mul_f32_e32 v76, 0x3f3504f3, v86
	v_fma_f32 v77, |v76|, s85, 1.0
	v_cvt_pk_bf16_f32 v74, v74, s0
	ds_write_b16 v91, v74 offset:544
	v_mul_f32_e32 v74, 0.5, v86
	v_rcp_f32_e32 v77, v77
	v_mul_f32_e64 v84, |v76|, -|v76|
	v_fmamk_f32 v83, v77, 0x3f87dc22, v206
	v_mul_f32_e32 v84, 0x3fb8aa3b, v84
	v_fmaak_f32 v83, v83, v77, 0x3fb5f0e3
	v_exp_f32_e32 v84, v84
	v_fmaak_f32 v83, v83, v77, 0xbe91a98e
	v_fmaak_f32 v83, v83, v77, 0x3e827906
	v_mul_f32_e32 v77, v77, v83
	v_fma_f32 v77, -v84, v77, 1.0
	v_bfi_b32 v76, s86, v77, v76
	v_add_f32_e32 v76, 1.0, v76
	v_mul_f32_e32 v74, v74, v76
	v_mul_f32_e32 v74, v75, v74
	v_cvt_pk_bf16_f32 v74, v74, s0
	ds_write_b16 v91, v74 offset:816
	v_mul_f32_e32 v74, v215, v108
	v_fmac_f32_e32 v74, v217, v160
	v_fmac_f32_e32 v74, v216, v161
	v_add_f32_e32 v75, v218, v74
	v_mul_f32_e32 v84, 0x3f3504f3, v75
	v_fma_f32 v85, |v84|, s85, 1.0
	v_mul_f32_e32 v74, v217, v161
	v_fmac_f32_e32 v74, v215, v160
	v_fmac_f32_e32 v74, v216, v156
	v_rcp_f32_e32 v85, v85
	v_mul_f32_e64 v87, |v84|, -|v84|
	v_fmamk_f32 v86, v85, 0x3f87dc22, v206
	v_mul_f32_e32 v87, 0x3fb8aa3b, v87
	v_fmaak_f32 v86, v86, v85, 0x3fb5f0e3
	v_exp_f32_e32 v87, v87
	v_fmaak_f32 v86, v86, v85, 0xbe91a98e
	v_fmaak_f32 v86, v86, v85, 0x3e827906
	v_mul_f32_e32 v85, v85, v86
	v_fma_f32 v85, -v87, v85, 1.0
	v_bfi_b32 v84, s86, v85, v84
	v_mul_f32_e32 v75, 0.5, v75
	v_add_f32_e32 v84, 1.0, v84
	v_add_f32_e32 v76, v218, v74
	v_mul_f32_e32 v74, v217, v156
	v_mul_f32_e32 v75, v75, v84
	v_fmac_f32_e32 v74, v215, v161
	v_mul_f32_e32 v72, v72, v75
	v_mul_f32_e32 v75, 0x3f3504f3, v76
	v_fmac_f32_e32 v74, v216, v157
	v_fma_f32 v84, |v75|, s85, 1.0
	v_add_f32_e32 v77, v218, v74
	v_mul_f32_e32 v74, v217, v157
	v_fmac_f32_e32 v74, v215, v156
	v_fmac_f32_e32 v74, v216, v106
	v_add_f32_e32 v83, v218, v74
; __device__ __forceinline__ u16 f2bf(float f) { return (u16)(pack2(f, f) & 0xffffu); }
; __device__ __forceinline__ float erf_f32(float x) {
;   const float ax = fabsf(x);
;   const float t = __frcp_rn(fmaf(0.3275911f, ax, 1.0f));
;   float poly = fmaf(1.061405429f, t, -1.453152027f);
;   poly = fmaf(poly, t, 1.421413741f);
;   poly = fmaf(poly, t, -0.284496736f);
;   poly = fmaf(poly, t, 0.254829592f);
;   const float y = 1.0f - poly * t * __expf(-ax * ax);
;   return copysignf(y, x);
; }
; __device__ __forceinline__ float gelu_exact(float x) { return 0.5f * x * (1.0f + erf_f32(x * 0.70710678118654752f)); }
; template <int EPI>
; __device__ __forceinline__ void phase_gemm(const Params& p, const GemmDesc& d, char* shmc) {
;     ...
; #pragma unroll
;       for (int n = 0; n < 2; ++n) {
;         const int col = ewc * 32 + n * 16 + efr;
;         const int ch = ch0 + col;
;         const float w0 = cw[n][0], w1 = cw[n][1], w2 = cw[n][2], cb = cw[n][3];
; #pragma unroll
;         for (int ai = 0; ai < 2; ++ai)
; #pragma unroll
;           for (int m = 0; m < 4; ++m) {
;             const int s = ai * 32 + ewr * 16 + m * 4 + efq;
;             const f32x4 g = acc[ai][0][m][n];
;             const f32x4 v = acc[ai][1][m][n];
;             const float c0 = w0 * gp[ai][m][n] + w1 * g[0] + w2 * g[1] + cb;
;             const float c1 = w0 * g[0] + w1 * g[1] + w2 * g[2] + cb;
;             const float c2 = w0 * g[1] + w1 * g[2] + w2 * g[3] + cb;
;             const float c3 = w0 * g[2] + w1 * g[3] + w2 * gn[ai][m][n] + cb;
;             u16* sp = stg + (s * 4) * 136 + col;
;             sp[0] = f2bf(gelu_exact(c0) * v[0]);
;             sp[136] = f2bf(gelu_exact(c1) * v[1]);
;             sp[272] = f2bf(gelu_exact(c2) * v[2]);
;             sp[408] = f2bf(gelu_exact(c3) * v[3]);
;             if (s == 0) {
;               edge[0 * DFF + ch] = c0; edge[1 * DFF + ch] = g[0]; edge[2 * DFF + ch] = v[0];
;             }
;             if (s == 63) {
;               edge[3 * DFF + ch] = c3; edge[4 * DFF + ch] = g[3]; edge[5 * DFF + ch] = v[3];
;             }
;           }
	v_add_u32_e32 v74, 0xaa00, v220
	v_add_u32_e32 v88, v222, v74
	v_cvt_pk_bf16_f32 v72, v72, s0
	ds_write_b16 v88, v72
	v_mul_f32_e32 v72, 0.5, v76
	v_rcp_f32_e32 v76, v84
	v_mul_f32_e64 v85, |v75|, -|v75|
	v_fmamk_f32 v84, v76, 0x3f87dc22, v206
	v_mul_f32_e32 v85, 0x3fb8aa3b, v85
	v_fmaak_f32 v84, v84, v76, 0x3fb5f0e3
	v_exp_f32_e32 v85, v85
	v_fmaak_f32 v84, v84, v76, 0xbe91a98e
	v_fmaak_f32 v84, v84, v76, 0x3e827906
	v_mul_f32_e32 v76, v76, v84
	v_fma_f32 v76, -v85, v76, 1.0
	v_bfi_b32 v75, s86, v76, v75
	v_add_f32_e32 v75, 1.0, v75
	v_mul_f32_e32 v72, v72, v75
	v_mul_f32_e32 v72, v73, v72
	v_mul_f32_e32 v73, 0x3f3504f3, v77
	v_fma_f32 v75, |v73|, s85, 1.0
	v_cvt_pk_bf16_f32 v72, v72, s0
	ds_write_b16 v88, v72 offset:272
	v_mul_f32_e32 v72, 0.5, v77
	v_rcp_f32_e32 v75, v75
	v_mul_f32_e64 v77, |v73|, -|v73|
	v_fmamk_f32 v76, v75, 0x3f87dc22, v206
	v_mul_f32_e32 v77, 0x3fb8aa3b, v77
	v_fmaak_f32 v76, v76, v75, 0x3fb5f0e3
	v_exp_f32_e32 v77, v77
	v_fmaak_f32 v76, v76, v75, 0xbe91a98e
	v_fmaak_f32 v76, v76, v75, 0x3e827906
	v_mul_f32_e32 v75, v75, v76
	v_fma_f32 v75, -v77, v75, 1.0
	v_bfi_b32 v73, s86, v75, v73
	v_add_f32_e32 v73, 1.0, v73
	v_mul_f32_e32 v72, v72, v73
	v_mul_f32_e32 v70, v70, v72
	v_mul_f32_e32 v72, 0x3f3504f3, v83
	v_fma_f32 v73, |v72|, s85, 1.0
	v_cvt_pk_bf16_f32 v70, v70, s0
	ds_write_b16 v88, v70 offset:544
	v_mul_f32_e32 v70, 0.5, v83
	v_rcp_f32_e32 v73, v73
	v_mul_f32_e64 v76, |v72|, -|v72|
	v_fmamk_f32 v75, v73, 0x3f87dc22, v206
	v_mul_f32_e32 v76, 0x3fb8aa3b, v76
	v_fmaak_f32 v75, v75, v73, 0x3fb5f0e3
	v_exp_f32_e32 v76, v76
	v_fmaak_f32 v75, v75, v73, 0xbe91a98e
	v_fmaak_f32 v75, v75, v73, 0x3e827906
	v_mul_f32_e32 v73, v73, v75
	v_fma_f32 v73, -v76, v73, 1.0
	v_bfi_b32 v72, s86, v73, v72
	v_add_f32_e32 v72, 1.0, v72
	v_mul_f32_e32 v70, v70, v72
	v_mul_f32_e32 v70, v71, v70
	v_cvt_pk_bf16_f32 v70, v70, s0
	ds_write_b16 v88, v70 offset:816
	s_waitcnt lgkmcnt(14)
	v_mul_f32_e32 v70, v215, v221
	v_fmac_f32_e32 v70, v217, v154
	v_fmac_f32_e32 v70, v216, v155
	v_add_f32_e32 v72, v218, v70
	v_mul_f32_e32 v76, 0x3f3504f3, v72
	v_fma_f32 v77, |v76|, s85, 1.0
	v_mul_f32_e32 v70, v217, v155
	v_fmac_f32_e32 v70, v215, v154
	v_fmac_f32_e32 v70, v216, v152
	v_rcp_f32_e32 v77, v77
	v_mul_f32_e64 v84, |v76|, -|v76|
	v_fmamk_f32 v83, v77, 0x3f87dc22, v206
	v_mul_f32_e32 v84, 0x3fb8aa3b, v84
	v_fmaak_f32 v83, v83, v77, 0x3fb5f0e3
	v_exp_f32_e32 v84, v84
	v_fmaak_f32 v83, v83, v77, 0xbe91a98e
	v_fmaak_f32 v83, v83, v77, 0x3e827906
	v_mul_f32_e32 v77, v77, v83
	v_fma_f32 v77, -v84, v77, 1.0
	v_bfi_b32 v76, s86, v77, v76
	v_mul_f32_e32 v72, 0.5, v72
	v_add_f32_e32 v76, 1.0, v76
	v_add_f32_e32 v73, v218, v70
	v_mul_f32_e32 v70, v217, v152
	v_mul_f32_e32 v72, v72, v76
	v_fmac_f32_e32 v70, v215, v155
	v_mul_f32_e32 v68, v68, v72
	v_mul_f32_e32 v72, 0x3f3504f3, v73
	v_fmac_f32_e32 v70, v216, v153
	v_fma_f32 v76, |v72|, s85, 1.0
	v_add_f32_e32 v75, v218, v70
	v_mul_f32_e32 v70, v217, v153
	v_fmac_f32_e32 v70, v215, v152
	v_fmac_f32_e32 v70, v216, v219
	v_add_f32_e32 v71, v218, v70
	v_add_u32_e32 v70, 0xbb00, v220
	v_add_u32_e32 v85, v222, v70
	v_cvt_pk_bf16_f32 v68, v68, s0
	ds_write_b16 v85, v68
	v_mul_f32_e32 v68, 0.5, v73
	v_rcp_f32_e32 v73, v76
	v_mul_f32_e64 v77, |v72|, -|v72|
	v_fmamk_f32 v76, v73, 0x3f87dc22, v206
	v_mul_f32_e32 v77, 0x3fb8aa3b, v77
	v_fmaak_f32 v76, v76, v73, 0x3fb5f0e3
	v_exp_f32_e32 v77, v77
	v_fmaak_f32 v76, v76, v73, 0xbe91a98e
	v_fmaak_f32 v76, v76, v73, 0x3e827906
	v_mul_f32_e32 v73, v73, v76
	v_fma_f32 v73, -v77, v73, 1.0
	v_bfi_b32 v72, s86, v73, v72
	v_add_f32_e32 v72, 1.0, v72
	v_mul_f32_e32 v68, v68, v72
	v_mul_f32_e32 v68, v69, v68
	v_mul_f32_e32 v69, 0x3f3504f3, v75
	v_fma_f32 v72, |v69|, s85, 1.0
	v_cvt_pk_bf16_f32 v68, v68, s0
	ds_write_b16 v85, v68 offset:272
	v_mul_f32_e32 v68, 0.5, v75
	v_rcp_f32_e32 v72, v72
	v_mul_f32_e64 v75, |v69|, -|v69|
	v_fmamk_f32 v73, v72, 0x3f87dc22, v206
	v_mul_f32_e32 v75, 0x3fb8aa3b, v75
	v_fmaak_f32 v73, v73, v72, 0x3fb5f0e3
	v_exp_f32_e32 v75, v75
	v_fmaak_f32 v73, v73, v72, 0xbe91a98e
	v_fmaak_f32 v73, v73, v72, 0x3e827906
	v_mul_f32_e32 v72, v72, v73
	v_fma_f32 v72, -v75, v72, 1.0
	v_bfi_b32 v69, s86, v72, v69
	v_add_f32_e32 v69, 1.0, v69
	v_mul_f32_e32 v68, v68, v69
	v_mul_f32_e32 v66, v66, v68
	v_mul_f32_e32 v68, 0x3f3504f3, v71
	v_fma_f32 v69, |v68|, s85, 1.0
	v_cvt_pk_bf16_f32 v66, v66, s0
	ds_write_b16 v85, v66 offset:544
	v_mul_f32_e32 v66, 0.5, v71
	v_rcp_f32_e32 v69, v69
	v_mul_f32_e64 v73, |v68|, -|v68|
	v_fmamk_f32 v72, v69, 0x3f87dc22, v206
	v_mul_f32_e32 v73, 0x3fb8aa3b, v73
	v_fmaak_f32 v72, v72, v69, 0x3fb5f0e3
	v_exp_f32_e32 v73, v73
	v_fmaak_f32 v72, v72, v69, 0xbe91a98e
	v_fmaak_f32 v72, v72, v69, 0x3e827906
	v_mul_f32_e32 v69, v69, v72
	v_fma_f32 v69, -v73, v69, 1.0
	v_bfi_b32 v68, s86, v69, v68
	v_add_f32_e32 v68, 1.0, v68
	v_mul_f32_e32 v66, v66, v68
	v_mul_f32_e32 v66, v67, v66
	v_cvt_pk_bf16_f32 v66, v66, s0
	ds_write_b16 v85, v66 offset:816
	s_and_saveexec_b64 s[58:59], s[8:9]
	s_cbranch_execz .LBB0_1168
	v_add_co_u32_e32 v68, vcc, 0x10000, v94
	s_nop 1
	v_addc_co_u32_e32 v69, vcc, 0, v95, vcc
	global_store_dword v[68:69], v71, off offset:2048
	v_add_co_u32_e32 v68, vcc, 0x16000, v94
	s_nop 1
	v_addc_co_u32_e32 v69, vcc, 0, v95, vcc
	global_store_dword v[68:69], v153, off
	v_add_co_u32_e32 v68, vcc, 0x1b000, v94
	s_nop 1
	v_addc_co_u32_e32 v69, vcc, 0, v95, vcc
	global_store_dword v[68:69], v67, off offset:2048
; __device__ __forceinline__ u16 f2bf(float f) { return (u16)(pack2(f, f) & 0xffffu); }
; __device__ __forceinline__ float erf_f32(float x) {
;   const float ax = fabsf(x);
;   const float t = __frcp_rn(fmaf(0.3275911f, ax, 1.0f));
;   float poly = fmaf(1.061405429f, t, -1.453152027f);
;   poly = fmaf(poly, t, 1.421413741f);
;   poly = fmaf(poly, t, -0.284496736f);
;   poly = fmaf(poly, t, 0.254829592f);
;   const float y = 1.0f - poly * t * __expf(-ax * ax);
;   return copysignf(y, x);
; }
; __device__ __forceinline__ float gelu_exact(float x) { return 0.5f * x * (1.0f + erf_f32(x * 0.70710678118654752f)); }
; template <int EPI>
; __device__ __forceinline__ void phase_gemm(const Params& p, const GemmDesc& d, char* shmc) {
;     ...
; #pragma unroll
;       for (int n = 0; n < 2; ++n) {
;         const int col = ewc * 32 + n * 16 + efr;
;         const int ch = ch0 + col;
;         const float w0 = cw[n][0], w1 = cw[n][1], w2 = cw[n][2], cb = cw[n][3];
; #pragma unroll
;         for (int ai = 0; ai < 2; ++ai)
; #pragma unroll
;           for (int m = 0; m < 4; ++m) {
;             const int s = ai * 32 + ewr * 16 + m * 4 + efq;
;             const f32x4 g = acc[ai][0][m][n];
;             const f32x4 v = acc[ai][1][m][n];
;             const float c0 = w0 * gp[ai][m][n] + w1 * g[0] + w2 * g[1] + cb;
;             const float c1 = w0 * g[0] + w1 * g[1] + w2 * g[2] + cb;
;             const float c2 = w0 * g[1] + w1 * g[2] + w2 * g[3] + cb;
;             const float c3 = w0 * g[2] + w1 * g[3] + w2 * gn[ai][m][n] + cb;
;             u16* sp = stg + (s * 4) * 136 + col;
;             sp[0] = f2bf(gelu_exact(c0) * v[0]);
;             sp[136] = f2bf(gelu_exact(c1) * v[1]);
;             sp[272] = f2bf(gelu_exact(c2) * v[2]);
;             sp[408] = f2bf(gelu_exact(c3) * v[3]);
;             if (s == 0) {
;               edge[0 * DFF + ch] = c0; edge[1 * DFF + ch] = g[0]; edge[2 * DFF + ch] = v[0];
;             }
;             if (s == 63) {
;               edge[3 * DFF + ch] = c3; edge[4 * DFF + ch] = g[3]; edge[5 * DFF + ch] = v[3];
;             }
;           }
.LBB0_1168:
	s_or_b64 exec, exec, s[58:59]
	v_pk_mul_f32 v[64:65], v[60:61], v[64:65]
	v_pk_mul_f32 v[60:61], v[58:59], v[62:63]
	v_mul_f32_e32 v62, v208, v213
	v_fmac_f32_e32 v62, v210, v146
	v_fmac_f32_e32 v62, v209, v147
	v_add_f32_e32 v63, v207, v62
	v_mul_f32_e32 v71, 0x3f3504f3, v63
	v_fma_f32 v72, |v71|, s85, 1.0
	v_mul_f32_e32 v62, v210, v147
	v_fmac_f32_e32 v62, v208, v146
	v_fmac_f32_e32 v62, v209, v158
	v_rcp_f32_e32 v72, v72
	v_mul_f32_e64 v75, |v71|, -|v71|
	v_fmamk_f32 v73, v72, 0x3f87dc22, v206
	v_mul_f32_e32 v75, 0x3fb8aa3b, v75
	v_fmaak_f32 v73, v73, v72, 0x3fb5f0e3
	v_exp_f32_e32 v75, v75
	v_fmaak_f32 v73, v73, v72, 0xbe91a98e
	v_fmaak_f32 v73, v73, v72, 0x3e827906
	v_mul_f32_e32 v72, v72, v73
	v_add_f32_e32 v67, v207, v62
	v_mul_f32_e32 v62, v210, v158
	v_fma_f32 v72, -v75, v72, 1.0
	v_fmac_f32_e32 v62, v208, v147
	v_bfi_b32 v71, s86, v72, v71
	v_mul_f32_e32 v72, 0x3f3504f3, v67
	v_fmac_f32_e32 v62, v209, v159
	v_fma_f32 v73, |v72|, s85, 1.0
	v_add_f32_e32 v68, v207, v62
	v_mul_f32_e32 v62, v210, v159
	v_mul_f32_e32 v76, 0.5, v63
	v_add_f32_e32 v71, 1.0, v71
	v_fmac_f32_e32 v62, v208, v158
	v_mul_f32_e32 v71, v76, v71
	v_or_b32_e32 v66, 16, v162
	v_fmac_f32_e32 v62, v209, v214
	v_add_f32_e32 v69, v207, v62
	v_lshlrev_b32_e32 v62, 1, v66
	v_mul_f32_e32 v71, v60, v71
	v_add3_u32 v66, s14, v220, v62
	v_cvt_pk_bf16_f32 v71, v71, s0
	ds_write_b16 v66, v71
	v_rcp_f32_e32 v71, v73
	v_mul_f32_e64 v75, |v72|, -|v72|
	v_fmamk_f32 v73, v71, 0x3f87dc22, v206
	v_mul_f32_e32 v75, 0x3fb8aa3b, v75
	v_fmaak_f32 v73, v73, v71, 0x3fb5f0e3
	v_exp_f32_e32 v75, v75
	v_fmaak_f32 v73, v73, v71, 0xbe91a98e
	v_fmaak_f32 v73, v73, v71, 0x3e827906
	v_mul_f32_e32 v71, v71, v73
	v_fma_f32 v71, -v75, v71, 1.0
	v_bfi_b32 v71, s86, v71, v72
	v_mul_f32_e32 v67, 0.5, v67
	v_add_f32_e32 v71, 1.0, v71
	v_mul_f32_e32 v67, v67, v71
	v_mul_f32_e32 v61, v61, v67
	v_mul_f32_e32 v67, 0x3f3504f3, v68
	v_fma_f32 v71, |v67|, s85, 1.0
	v_cvt_pk_bf16_f32 v61, v61, s0
	ds_write_b16 v66, v61 offset:272
	v_mul_f32_e32 v61, 0.5, v68
	v_rcp_f32_e32 v68, v71
	v_mul_f32_e64 v72, |v67|, -|v67|
	v_fmamk_f32 v71, v68, 0x3f87dc22, v206
	v_mul_f32_e32 v72, 0x3fb8aa3b, v72
	v_fmaak_f32 v71, v71, v68, 0x3fb5f0e3
	v_exp_f32_e32 v72, v72
	v_fmaak_f32 v71, v71, v68, 0xbe91a98e
	v_fmaak_f32 v71, v71, v68, 0x3e827906
	v_mul_f32_e32 v68, v68, v71
	v_fma_f32 v68, -v72, v68, 1.0
	v_bfi_b32 v67, s86, v68, v67
	v_add_f32_e32 v67, 1.0, v67
	v_mul_f32_e32 v61, v61, v67
	v_mul_f32_e32 v61, v64, v61
	v_mul_f32_e32 v64, 0x3f3504f3, v69
	v_fma_f32 v67, |v64|, s85, 1.0
	v_cvt_pk_bf16_f32 v61, v61, s0
	ds_write_b16 v66, v61 offset:544
	v_mul_f32_e32 v61, 0.5, v69
	v_rcp_f32_e32 v67, v67
	v_mul_f32_e64 v69, |v64|, -|v64|
	v_fmamk_f32 v68, v67, 0x3f87dc22, v206
	v_mul_f32_e32 v69, 0x3fb8aa3b, v69
	v_fmaak_f32 v68, v68, v67, 0x3fb5f0e3
	v_exp_f32_e32 v69, v69
	v_fmaak_f32 v68, v68, v67, 0xbe91a98e
	v_fmaak_f32 v68, v68, v67, 0x3e827906
	v_mul_f32_e32 v67, v67, v68
	v_fma_f32 v67, -v69, v67, 1.0
	v_bfi_b32 v64, s86, v67, v64
	s_ashr_i32 s55, s54, 31
	v_add_f32_e32 v64, 1.0, v64
	v_lshl_add_u64 v[58:59], v[162:163], 0, s[54:55]
	v_mul_f32_e32 v61, v61, v64
	v_lshl_add_u64 v[58:59], v[58:59], 2, s[56:57]
	v_mul_f32_e32 v61, v65, v61
	v_lshl_add_u64 v[58:59], v[58:59], 0, 64
	v_cvt_pk_bf16_f32 v61, v61, s0
	ds_write_b16 v66, v61 offset:816
	s_and_saveexec_b64 s[56:57], s[10:11]
	s_cbranch_execz .LBB0_1170
	v_add_co_u32_e32 v64, vcc, 0x5000, v58
	global_store_dword v[58:59], v63, off
	s_nop 0
	v_addc_co_u32_e32 v65, vcc, 0, v59, vcc
	global_store_dword v[64:65], v146, off offset:2048
	v_add_co_u32_e32 v64, vcc, 0xb000, v58
	s_nop 1
	v_addc_co_u32_e32 v65, vcc, 0, v59, vcc
	global_store_dword v[64:65], v60, off
.LBB0_1170:
	s_or_b64 exec, exec, s[56:57]
	v_pk_mul_f32 v[48:49], v[4:5], v[48:49]
	v_pk_mul_f32 v[4:5], v[14:15], v[30:31]
	v_mul_f32_e32 v14, v208, v151
	v_fmac_f32_e32 v14, v210, v144
	v_fmac_f32_e32 v14, v209, v145
	v_add_f32_e32 v14, v207, v14
	v_pk_mul_f32 v[52:53], v[8:9], v[52:53]
	v_pk_mul_f32 v[8:9], v[18:19], v[34:35]
	v_mul_f32_e32 v18, 0x3f3504f3, v14
	v_fma_f32 v19, |v18|, s85, 1.0
	v_pk_mul_f32 v[50:51], v[6:7], v[50:51]
	v_pk_mul_f32 v[6:7], v[20:21], v[36:37]
	v_pk_mul_f32 v[56:57], v[12:13], v[56:57]
	v_pk_mul_f32 v[12:13], v[22:23], v[38:39]
	v_pk_mul_f32 v[54:55], v[10:11], v[54:55]
	v_pk_mul_f32 v[10:11], v[24:25], v[40:41]
	v_rcp_f32_e32 v19, v19
	v_mul_f32_e64 v21, |v18|, -|v18|
	v_fmamk_f32 v20, v19, 0x3f87dc22, v206
	v_mul_f32_e32 v21, 0x3fb8aa3b, v21
	v_fmaak_f32 v20, v20, v19, 0x3fb5f0e3
	v_exp_f32_e32 v21, v21
	v_fmaak_f32 v20, v20, v19, 0xbe91a98e
	v_fmaak_f32 v20, v20, v19, 0x3e827906
	v_mul_f32_e32 v15, v210, v145
	v_mul_f32_e32 v19, v19, v20
	v_fmac_f32_e32 v15, v208, v144
	v_fma_f32 v19, -v21, v19, 1.0
	v_fmac_f32_e32 v15, v209, v142
	v_bfi_b32 v18, s86, v19, v18
	v_add_f32_e32 v15, v207, v15
	v_mul_f32_e32 v14, 0.5, v14
	v_add_f32_e32 v18, 1.0, v18
	v_mul_f32_e32 v14, v14, v18
	v_mul_f32_e32 v18, 0x3f3504f3, v15
	v_fma_f32 v19, |v18|, s85, 1.0
	v_mul_f32_e32 v14, v54, v14
	v_add3_u32 v22, s14, v78, v62
	v_cvt_pk_bf16_f32 v14, v14, s0
	ds_write_b16 v22, v14
	v_mul_f32_e32 v14, 0.5, v15
	v_rcp_f32_e32 v15, v19
	v_mul_f32_e64 v20, |v18|, -|v18|
	v_fmamk_f32 v19, v15, 0x3f87dc22, v206
	v_mul_f32_e32 v20, 0x3fb8aa3b, v20
	v_fmaak_f32 v19, v19, v15, 0x3fb5f0e3
	v_exp_f32_e32 v20, v20
	v_fmaak_f32 v19, v19, v15, 0xbe91a98e
	v_fmaak_f32 v19, v19, v15, 0x3e827906
	v_pk_mul_f32 v[46:47], v[2:3], v[46:47]
	v_pk_mul_f32 v[2:3], v[16:17], v[32:33]
	v_mul_f32_e32 v16, v210, v142
	v_mul_f32_e32 v15, v15, v19
	v_fmac_f32_e32 v16, v208, v145
	v_fma_f32 v15, -v20, v15, 1.0
; __device__ __forceinline__ u16 f2bf(float f) { return (u16)(pack2(f, f) & 0xffffu); }
; __device__ __forceinline__ float erf_f32(float x) {
;   const float ax = fabsf(x);
;   const float t = __frcp_rn(fmaf(0.3275911f, ax, 1.0f));
;   float poly = fmaf(1.061405429f, t, -1.453152027f);
;   poly = fmaf(poly, t, 1.421413741f);
;   poly = fmaf(poly, t, -0.284496736f);
;   poly = fmaf(poly, t, 0.254829592f);
;   const float y = 1.0f - poly * t * __expf(-ax * ax);
;   return copysignf(y, x);
; }
; __device__ __forceinline__ float gelu_exact(float x) { return 0.5f * x * (1.0f + erf_f32(x * 0.70710678118654752f)); }
; template <int EPI>
; __device__ __forceinline__ void phase_gemm(const Params& p, const GemmDesc& d, char* shmc) {
;     ...
; #pragma unroll
;       for (int n = 0; n < 2; ++n) {
;         const int col = ewc * 32 + n * 16 + efr;
;         const int ch = ch0 + col;
;         const float w0 = cw[n][0], w1 = cw[n][1], w2 = cw[n][2], cb = cw[n][3];
; #pragma unroll
;         for (int ai = 0; ai < 2; ++ai)
; #pragma unroll
;           for (int m = 0; m < 4; ++m) {
;             const int s = ai * 32 + ewr * 16 + m * 4 + efq;
;             const f32x4 g = acc[ai][0][m][n];
;             const f32x4 v = acc[ai][1][m][n];
;             const float c0 = w0 * gp[ai][m][n] + w1 * g[0] + w2 * g[1] + cb;
;             const float c1 = w0 * g[0] + w1 * g[1] + w2 * g[2] + cb;
;             const float c2 = w0 * g[1] + w1 * g[2] + w2 * g[3] + cb;
;             const float c3 = w0 * g[2] + w1 * g[3] + w2 * gn[ai][m][n] + cb;
;             u16* sp = stg + (s * 4) * 136 + col;
;             sp[0] = f2bf(gelu_exact(c0) * v[0]);
;             sp[136] = f2bf(gelu_exact(c1) * v[1]);
;             sp[272] = f2bf(gelu_exact(c2) * v[2]);
;             sp[408] = f2bf(gelu_exact(c3) * v[3]);
;             if (s == 0) {
;               edge[0 * DFF + ch] = c0; edge[1 * DFF + ch] = g[0]; edge[2 * DFF + ch] = v[0];
;             }
;             if (s == 63) {
;               edge[3 * DFF + ch] = c3; edge[4 * DFF + ch] = g[3]; edge[5 * DFF + ch] = v[3];
;             }
;           }
	v_fmac_f32_e32 v16, v209, v143
	v_bfi_b32 v15, s86, v15, v18
	v_add_f32_e32 v16, v207, v16
	v_add_f32_e32 v15, 1.0, v15
	v_mul_f32_e32 v14, v14, v15
	v_mul_f32_e32 v15, 0x3f3504f3, v16
	v_fma_f32 v18, |v15|, s85, 1.0
	v_mul_f32_e32 v14, v55, v14
	v_cvt_pk_bf16_f32 v14, v14, s0
	ds_write_b16 v22, v14 offset:272
	v_mul_f32_e32 v14, 0.5, v16
	v_rcp_f32_e32 v16, v18
	v_mul_f32_e64 v19, |v15|, -|v15|
	v_fmamk_f32 v18, v16, 0x3f87dc22, v206
	v_mul_f32_e32 v19, 0x3fb8aa3b, v19
	v_fmaak_f32 v18, v18, v16, 0x3fb5f0e3
	v_exp_f32_e32 v19, v19
	v_fmaak_f32 v18, v18, v16, 0xbe91a98e
	v_fmaak_f32 v18, v18, v16, 0x3e827906
	v_mul_f32_e32 v17, v210, v143
	v_mul_f32_e32 v16, v16, v18
	v_fmac_f32_e32 v17, v208, v142
	v_fma_f32 v16, -v19, v16, 1.0
	v_fmac_f32_e32 v17, v209, v149
	v_bfi_b32 v15, s86, v16, v15
	v_add_f32_e32 v17, v207, v17
	v_add_f32_e32 v15, 1.0, v15
	v_mul_f32_e32 v14, v14, v15
	v_mul_f32_e32 v15, 0x3f3504f3, v17
	v_fma_f32 v16, |v15|, s85, 1.0
	v_mul_f32_e32 v14, v56, v14
	v_cvt_pk_bf16_f32 v14, v14, s0
	ds_write_b16 v22, v14 offset:544
	v_mul_f32_e32 v14, 0.5, v17
	v_rcp_f32_e32 v16, v16
	v_mul_f32_e64 v18, |v15|, -|v15|
	v_fmamk_f32 v17, v16, 0x3f87dc22, v206
	v_mul_f32_e32 v18, 0x3fb8aa3b, v18
	v_fmaak_f32 v17, v17, v16, 0x3fb5f0e3
	v_exp_f32_e32 v18, v18
	v_fmaak_f32 v17, v17, v16, 0xbe91a98e
	v_fmaak_f32 v17, v17, v16, 0x3e827906
	v_mul_f32_e32 v16, v16, v17
	v_fma_f32 v16, -v18, v16, 1.0
	v_bfi_b32 v15, s86, v16, v15
	v_add_f32_e32 v15, 1.0, v15
	v_mul_f32_e32 v14, v14, v15
	v_mul_f32_e32 v14, v57, v14
	v_cvt_pk_bf16_f32 v14, v14, s0
	ds_write_b16 v22, v14 offset:816
	v_mul_f32_e32 v14, v208, v141
	v_fmac_f32_e32 v14, v210, v136
	v_fmac_f32_e32 v14, v209, v137
	v_add_f32_e32 v14, v207, v14
	v_mul_f32_e32 v18, 0x3f3504f3, v14
	v_fma_f32 v19, |v18|, s85, 1.0
	v_mul_f32_e32 v15, v210, v137
	v_fmac_f32_e32 v15, v208, v136
	v_fmac_f32_e32 v15, v209, v134
	v_rcp_f32_e32 v19, v19
	v_mul_f32_e64 v21, |v18|, -|v18|
	v_fmamk_f32 v20, v19, 0x3f87dc22, v206
	v_mul_f32_e32 v21, 0x3fb8aa3b, v21
	v_fmaak_f32 v20, v20, v19, 0x3fb5f0e3
	v_exp_f32_e32 v21, v21
	v_fmaak_f32 v20, v20, v19, 0xbe91a98e
	v_fmaak_f32 v20, v20, v19, 0x3e827906
	v_mul_f32_e32 v19, v19, v20
	v_fma_f32 v19, -v21, v19, 1.0
	v_bfi_b32 v18, s86, v19, v18
	v_add_f32_e32 v15, v207, v15
	v_mul_f32_e32 v14, 0.5, v14
	v_add_f32_e32 v18, 1.0, v18
	v_mul_f32_e32 v14, v14, v18
	v_mul_f32_e32 v18, 0x3f3504f3, v15
	v_fma_f32 v19, |v18|, s85, 1.0
	v_mul_f32_e32 v14, v50, v14
	v_add3_u32 v22, s14, v79, v62
	v_cvt_pk_bf16_f32 v14, v14, s0
	ds_write_b16 v22, v14
	v_mul_f32_e32 v14, 0.5, v15
	v_rcp_f32_e32 v15, v19
	v_mul_f32_e64 v20, |v18|, -|v18|
	v_fmamk_f32 v19, v15, 0x3f87dc22, v206
	v_mul_f32_e32 v20, 0x3fb8aa3b, v20
	v_fmaak_f32 v19, v19, v15, 0x3fb5f0e3
	v_exp_f32_e32 v20, v20
	v_fmaak_f32 v19, v19, v15, 0xbe91a98e
	v_fmaak_f32 v19, v19, v15, 0x3e827906
	v_mul_f32_e32 v16, v210, v134
	v_mul_f32_e32 v15, v15, v19
	v_fmac_f32_e32 v16, v208, v137
	v_fma_f32 v15, -v20, v15, 1.0
	v_fmac_f32_e32 v16, v209, v135
	v_bfi_b32 v15, s86, v15, v18
	v_add_f32_e32 v16, v207, v16
	v_add_f32_e32 v15, 1.0, v15
	v_mul_f32_e32 v14, v14, v15
	v_mul_f32_e32 v15, 0x3f3504f3, v16
	v_fma_f32 v18, |v15|, s85, 1.0
	v_mul_f32_e32 v14, v51, v14
	v_cvt_pk_bf16_f32 v14, v14, s0
	ds_write_b16 v22, v14 offset:272
	v_mul_f32_e32 v14, 0.5, v16
	v_rcp_f32_e32 v16, v18
	v_mul_f32_e64 v19, |v15|, -|v15|
	v_fmamk_f32 v18, v16, 0x3f87dc22, v206
	v_mul_f32_e32 v19, 0x3fb8aa3b, v19
	v_fmaak_f32 v18, v18, v16, 0x3fb5f0e3
	v_exp_f32_e32 v19, v19
	v_fmaak_f32 v18, v18, v16, 0xbe91a98e
	v_fmaak_f32 v18, v18, v16, 0x3e827906
	v_mul_f32_e32 v17, v210, v135
	v_mul_f32_e32 v16, v16, v18
	v_fmac_f32_e32 v17, v208, v134
	v_fma_f32 v16, -v19, v16, 1.0
	v_fmac_f32_e32 v17, v209, v139
	v_bfi_b32 v15, s86, v16, v15
	v_add_f32_e32 v17, v207, v17
	v_add_f32_e32 v15, 1.0, v15
	v_mul_f32_e32 v14, v14, v15
	v_mul_f32_e32 v15, 0x3f3504f3, v17
	v_fma_f32 v16, |v15|, s85, 1.0
	v_mul_f32_e32 v14, v52, v14
	v_cvt_pk_bf16_f32 v14, v14, s0
	ds_write_b16 v22, v14 offset:544
	v_mul_f32_e32 v14, 0.5, v17
	v_rcp_f32_e32 v16, v16
	v_mul_f32_e64 v18, |v15|, -|v15|
	v_fmamk_f32 v17, v16, 0x3f87dc22, v206
	v_mul_f32_e32 v18, 0x3fb8aa3b, v18
	v_fmaak_f32 v17, v17, v16, 0x3fb5f0e3
	v_exp_f32_e32 v18, v18
	v_fmaak_f32 v17, v17, v16, 0xbe91a98e
	v_fmaak_f32 v17, v17, v16, 0x3e827906
	v_mul_f32_e32 v16, v16, v17
	v_fma_f32 v16, -v18, v16, 1.0
	v_bfi_b32 v15, s86, v16, v15
	v_add_f32_e32 v15, 1.0, v15
	v_mul_f32_e32 v14, v14, v15
	v_mul_f32_e32 v14, v53, v14
	v_cvt_pk_bf16_f32 v14, v14, s0
	ds_write_b16 v22, v14 offset:816
	v_mul_f32_e32 v14, v208, v133
	v_fmac_f32_e32 v14, v210, v128
	v_fmac_f32_e32 v14, v209, v129
	v_add_f32_e32 v14, v207, v14
	v_mul_f32_e32 v18, 0x3f3504f3, v14
	v_fma_f32 v19, |v18|, s85, 1.0
	v_mul_f32_e32 v15, v210, v129
	v_fmac_f32_e32 v15, v208, v128
	v_fmac_f32_e32 v15, v209, v126
	v_rcp_f32_e32 v19, v19
	v_mul_f32_e64 v21, |v18|, -|v18|
	v_fmamk_f32 v20, v19, 0x3f87dc22, v206
	v_mul_f32_e32 v21, 0x3fb8aa3b, v21
	v_fmaak_f32 v20, v20, v19, 0x3fb5f0e3
	v_exp_f32_e32 v21, v21
	v_fmaak_f32 v20, v20, v19, 0xbe91a98e
	v_fmaak_f32 v20, v20, v19, 0x3e827906
	v_mul_f32_e32 v19, v19, v20
	v_fma_f32 v19, -v21, v19, 1.0
	v_bfi_b32 v18, s86, v19, v18
	v_add_f32_e32 v15, v207, v15
	v_mul_f32_e32 v14, 0.5, v14
	v_add_f32_e32 v18, 1.0, v18
	v_mul_f32_e32 v14, v14, v18
	v_mul_f32_e32 v18, 0x3f3504f3, v15
	v_fma_f32 v19, |v18|, s85, 1.0
	v_mul_f32_e32 v14, v46, v14
	v_add3_u32 v22, s14, v80, v62
	v_cvt_pk_bf16_f32 v14, v14, s0
	ds_write_b16 v22, v14
	v_mul_f32_e32 v14, 0.5, v15
	v_rcp_f32_e32 v15, v19
	v_mul_f32_e64 v20, |v18|, -|v18|
; __device__ __forceinline__ u16 f2bf(float f) { return (u16)(pack2(f, f) & 0xffffu); }
; __device__ __forceinline__ float erf_f32(float x) {
;   const float ax = fabsf(x);
;   const float t = __frcp_rn(fmaf(0.3275911f, ax, 1.0f));
;   float poly = fmaf(1.061405429f, t, -1.453152027f);
;   poly = fmaf(poly, t, 1.421413741f);
;   poly = fmaf(poly, t, -0.284496736f);
;   poly = fmaf(poly, t, 0.254829592f);
;   const float y = 1.0f - poly * t * __expf(-ax * ax);
;   return copysignf(y, x);
; }
; __device__ __forceinline__ float gelu_exact(float x) { return 0.5f * x * (1.0f + erf_f32(x * 0.70710678118654752f)); }
; template <int EPI>
; __device__ __forceinline__ void phase_gemm(const Params& p, const GemmDesc& d, char* shmc) {
;     ...
; #pragma unroll
;       for (int n = 0; n < 2; ++n) {
;         const int col = ewc * 32 + n * 16 + efr;
;         const int ch = ch0 + col;
;         const float w0 = cw[n][0], w1 = cw[n][1], w2 = cw[n][2], cb = cw[n][3];
; #pragma unroll
;         for (int ai = 0; ai < 2; ++ai)
; #pragma unroll
;           for (int m = 0; m < 4; ++m) {
;             const int s = ai * 32 + ewr * 16 + m * 4 + efq;
;             const f32x4 g = acc[ai][0][m][n];
;             const f32x4 v = acc[ai][1][m][n];
;             const float c0 = w0 * gp[ai][m][n] + w1 * g[0] + w2 * g[1] + cb;
;             const float c1 = w0 * g[0] + w1 * g[1] + w2 * g[2] + cb;
;             const float c2 = w0 * g[1] + w1 * g[2] + w2 * g[3] + cb;
;             const float c3 = w0 * g[2] + w1 * g[3] + w2 * gn[ai][m][n] + cb;
;             u16* sp = stg + (s * 4) * 136 + col;
;             sp[0] = f2bf(gelu_exact(c0) * v[0]);
;             sp[136] = f2bf(gelu_exact(c1) * v[1]);
;             sp[272] = f2bf(gelu_exact(c2) * v[2]);
;             sp[408] = f2bf(gelu_exact(c3) * v[3]);
;             if (s == 0) {
;               edge[0 * DFF + ch] = c0; edge[1 * DFF + ch] = g[0]; edge[2 * DFF + ch] = v[0];
;             }
;             if (s == 63) {
;               edge[3 * DFF + ch] = c3; edge[4 * DFF + ch] = g[3]; edge[5 * DFF + ch] = v[3];
;             }
;           }
	v_fmamk_f32 v19, v15, 0x3f87dc22, v206
	v_mul_f32_e32 v20, 0x3fb8aa3b, v20
	v_fmaak_f32 v19, v19, v15, 0x3fb5f0e3
	v_exp_f32_e32 v20, v20
	v_fmaak_f32 v19, v19, v15, 0xbe91a98e
	v_fmaak_f32 v19, v19, v15, 0x3e827906
	v_mul_f32_e32 v16, v210, v126
	v_mul_f32_e32 v15, v15, v19
	v_fmac_f32_e32 v16, v208, v129
	v_fma_f32 v15, -v20, v15, 1.0
	v_fmac_f32_e32 v16, v209, v127
	v_bfi_b32 v15, s86, v15, v18
	v_add_f32_e32 v16, v207, v16
	v_add_f32_e32 v15, 1.0, v15
	v_mul_f32_e32 v14, v14, v15
	v_mul_f32_e32 v15, 0x3f3504f3, v16
	v_fma_f32 v18, |v15|, s85, 1.0
	v_mul_f32_e32 v14, v47, v14
	v_cvt_pk_bf16_f32 v14, v14, s0
	ds_write_b16 v22, v14 offset:272
	v_mul_f32_e32 v14, 0.5, v16
	v_rcp_f32_e32 v16, v18
	v_mul_f32_e64 v19, |v15|, -|v15|
	v_fmamk_f32 v18, v16, 0x3f87dc22, v206
	v_mul_f32_e32 v19, 0x3fb8aa3b, v19
	v_fmaak_f32 v18, v18, v16, 0x3fb5f0e3
	v_exp_f32_e32 v19, v19
	v_fmaak_f32 v18, v18, v16, 0xbe91a98e
	v_fmaak_f32 v18, v18, v16, 0x3e827906
	v_mul_f32_e32 v17, v210, v127
	v_mul_f32_e32 v16, v16, v18
	v_fmac_f32_e32 v17, v208, v126
	v_fma_f32 v16, -v19, v16, 1.0
	v_fmac_f32_e32 v17, v209, v131
	v_bfi_b32 v15, s86, v16, v15
	v_add_f32_e32 v17, v207, v17
	v_add_f32_e32 v15, 1.0, v15
	v_mul_f32_e32 v14, v14, v15
	v_mul_f32_e32 v15, 0x3f3504f3, v17
	v_fma_f32 v16, |v15|, s85, 1.0
	v_mul_f32_e32 v14, v48, v14
	v_cvt_pk_bf16_f32 v14, v14, s0
	ds_write_b16 v22, v14 offset:544
	v_mul_f32_e32 v14, 0.5, v17
	v_rcp_f32_e32 v16, v16
	v_mul_f32_e64 v18, |v15|, -|v15|
	v_fmamk_f32 v17, v16, 0x3f87dc22, v206
	v_mul_f32_e32 v18, 0x3fb8aa3b, v18
	v_fmaak_f32 v17, v17, v16, 0x3fb5f0e3
	v_exp_f32_e32 v18, v18
	v_fmaak_f32 v17, v17, v16, 0xbe91a98e
	v_fmaak_f32 v17, v17, v16, 0x3e827906
	v_mul_f32_e32 v16, v16, v17
	v_fma_f32 v16, -v18, v16, 1.0
	v_bfi_b32 v15, s86, v16, v15
	v_add_f32_e32 v15, 1.0, v15
	v_mul_f32_e32 v14, v14, v15
	v_mul_f32_e32 v14, v49, v14
	v_cvt_pk_bf16_f32 v14, v14, s0
	ds_write_b16 v22, v14 offset:816
	v_mul_f32_e32 v14, v208, v125
	v_fmac_f32_e32 v14, v210, v120
	v_fmac_f32_e32 v14, v209, v121
	v_add_f32_e32 v14, v207, v14
	v_mul_f32_e32 v18, 0x3f3504f3, v14
	v_fma_f32 v19, |v18|, s85, 1.0
	v_mul_f32_e32 v15, v210, v121
	v_fmac_f32_e32 v15, v208, v120
	v_fmac_f32_e32 v15, v209, v118
	v_rcp_f32_e32 v19, v19
	v_mul_f32_e64 v21, |v18|, -|v18|
	v_fmamk_f32 v20, v19, 0x3f87dc22, v206
	v_mul_f32_e32 v21, 0x3fb8aa3b, v21
	v_fmaak_f32 v20, v20, v19, 0x3fb5f0e3
	v_exp_f32_e32 v21, v21
	v_fmaak_f32 v20, v20, v19, 0xbe91a98e
	v_fmaak_f32 v20, v20, v19, 0x3e827906
	v_mul_f32_e32 v19, v19, v20
	v_fma_f32 v19, -v21, v19, 1.0
	v_bfi_b32 v18, s86, v19, v18
	v_add_f32_e32 v15, v207, v15
	v_mul_f32_e32 v14, 0.5, v14
	v_add_f32_e32 v18, 1.0, v18
	v_mul_f32_e32 v14, v14, v18
	v_mul_f32_e32 v18, 0x3f3504f3, v15
	v_fma_f32 v19, |v18|, s85, 1.0
	v_pk_mul_f32 v[26:27], v[26:27], v[42:43]
	v_add3_u32 v22, s14, v81, v62
	v_mul_f32_e32 v14, v26, v14
	v_cvt_pk_bf16_f32 v14, v14, s0
	ds_write_b16 v22, v14
	v_mul_f32_e32 v14, 0.5, v15
	v_rcp_f32_e32 v15, v19
	v_mul_f32_e64 v20, |v18|, -|v18|
	v_fmamk_f32 v19, v15, 0x3f87dc22, v206
	v_mul_f32_e32 v20, 0x3fb8aa3b, v20
	v_fmaak_f32 v19, v19, v15, 0x3fb5f0e3
	v_exp_f32_e32 v20, v20
	v_fmaak_f32 v19, v19, v15, 0xbe91a98e
	v_fmaak_f32 v19, v19, v15, 0x3e827906
	v_mul_f32_e32 v16, v210, v118
	v_mul_f32_e32 v15, v15, v19
	v_fmac_f32_e32 v16, v208, v121
	v_fma_f32 v15, -v20, v15, 1.0
	v_fmac_f32_e32 v16, v209, v119
	v_bfi_b32 v15, s86, v15, v18
	v_add_f32_e32 v16, v207, v16
	v_add_f32_e32 v15, 1.0, v15
	v_mul_f32_e32 v14, v14, v15
	v_mul_f32_e32 v15, 0x3f3504f3, v16
	v_fma_f32 v18, |v15|, s85, 1.0
	v_mul_f32_e32 v14, v27, v14
	v_cvt_pk_bf16_f32 v14, v14, s0
	ds_write_b16 v22, v14 offset:272
	v_mul_f32_e32 v14, 0.5, v16
	v_rcp_f32_e32 v16, v18
	v_mul_f32_e64 v19, |v15|, -|v15|
	v_fmamk_f32 v18, v16, 0x3f87dc22, v206
	v_mul_f32_e32 v19, 0x3fb8aa3b, v19
	v_fmaak_f32 v18, v18, v16, 0x3fb5f0e3
	v_exp_f32_e32 v19, v19
	v_fmaak_f32 v18, v18, v16, 0xbe91a98e
	v_fmaak_f32 v18, v18, v16, 0x3e827906
	v_mul_f32_e32 v17, v210, v119
	v_mul_f32_e32 v16, v16, v18
	v_fmac_f32_e32 v17, v208, v118
	v_fma_f32 v16, -v19, v16, 1.0
	v_fmac_f32_e32 v17, v209, v123
	v_bfi_b32 v15, s86, v16, v15
	v_add_f32_e32 v17, v207, v17
	v_add_f32_e32 v15, 1.0, v15
	v_mul_f32_e32 v14, v14, v15
	v_mul_f32_e32 v15, 0x3f3504f3, v17
	v_fma_f32 v16, |v15|, s85, 1.0
	v_pk_mul_f32 v[28:29], v[28:29], v[44:45]
	s_nop 0
	v_mul_f32_e32 v14, v28, v14
	v_cvt_pk_bf16_f32 v14, v14, s0
	ds_write_b16 v22, v14 offset:544
	v_mul_f32_e32 v14, 0.5, v17
	v_rcp_f32_e32 v16, v16
	v_mul_f32_e64 v18, |v15|, -|v15|
	v_fmamk_f32 v17, v16, 0x3f87dc22, v206
	v_mul_f32_e32 v18, 0x3fb8aa3b, v18
	v_fmaak_f32 v17, v17, v16, 0x3fb5f0e3
	v_exp_f32_e32 v18, v18
	v_fmaak_f32 v17, v17, v16, 0xbe91a98e
	v_fmaak_f32 v17, v17, v16, 0x3e827906
	v_mul_f32_e32 v16, v16, v17
	v_fma_f32 v16, -v18, v16, 1.0
	v_bfi_b32 v15, s86, v16, v15
	v_add_f32_e32 v15, 1.0, v15
	v_mul_f32_e32 v14, v14, v15
	v_mul_f32_e32 v14, v29, v14
	v_cvt_pk_bf16_f32 v14, v14, s0
	ds_write_b16 v22, v14 offset:816
	v_mul_f32_e32 v14, v208, v117
	v_fmac_f32_e32 v14, v210, v112
	v_fmac_f32_e32 v14, v209, v113
	v_add_f32_e32 v14, v207, v14
	v_mul_f32_e32 v18, 0x3f3504f3, v14
	v_fma_f32 v19, |v18|, s85, 1.0
	v_mul_f32_e32 v15, v210, v113
	v_fmac_f32_e32 v15, v208, v112
	v_fmac_f32_e32 v15, v209, v110
	v_rcp_f32_e32 v19, v19
	v_mul_f32_e64 v21, |v18|, -|v18|
	v_fmamk_f32 v20, v19, 0x3f87dc22, v206
	v_mul_f32_e32 v21, 0x3fb8aa3b, v21
	v_fmaak_f32 v20, v20, v19, 0x3fb5f0e3
	v_exp_f32_e32 v21, v21
	v_fmaak_f32 v20, v20, v19, 0xbe91a98e
	v_fmaak_f32 v20, v20, v19, 0x3e827906
	v_mul_f32_e32 v19, v19, v20
	v_fma_f32 v19, -v21, v19, 1.0
; __device__ __forceinline__ u16 f2bf(float f) { return (u16)(pack2(f, f) & 0xffffu); }
; __device__ __forceinline__ float erf_f32(float x) {
;   const float ax = fabsf(x);
;   const float t = __frcp_rn(fmaf(0.3275911f, ax, 1.0f));
;   float poly = fmaf(1.061405429f, t, -1.453152027f);
;   poly = fmaf(poly, t, 1.421413741f);
;   poly = fmaf(poly, t, -0.284496736f);
;   poly = fmaf(poly, t, 0.254829592f);
;   const float y = 1.0f - poly * t * __expf(-ax * ax);
;   return copysignf(y, x);
; }
; __device__ __forceinline__ float gelu_exact(float x) { return 0.5f * x * (1.0f + erf_f32(x * 0.70710678118654752f)); }
; template <int EPI>
; __device__ __forceinline__ void phase_gemm(const Params& p, const GemmDesc& d, char* shmc) {
;     ...
; #pragma unroll
;       for (int n = 0; n < 2; ++n) {
;         const int col = ewc * 32 + n * 16 + efr;
;         const int ch = ch0 + col;
;         const float w0 = cw[n][0], w1 = cw[n][1], w2 = cw[n][2], cb = cw[n][3];
; #pragma unroll
;         for (int ai = 0; ai < 2; ++ai)
; #pragma unroll
;           for (int m = 0; m < 4; ++m) {
;             const int s = ai * 32 + ewr * 16 + m * 4 + efq;
;             const f32x4 g = acc[ai][0][m][n];
;             const f32x4 v = acc[ai][1][m][n];
;             const float c0 = w0 * gp[ai][m][n] + w1 * g[0] + w2 * g[1] + cb;
;             const float c1 = w0 * g[0] + w1 * g[1] + w2 * g[2] + cb;
;             const float c2 = w0 * g[1] + w1 * g[2] + w2 * g[3] + cb;
;             const float c3 = w0 * g[2] + w1 * g[3] + w2 * gn[ai][m][n] + cb;
;             u16* sp = stg + (s * 4) * 136 + col;
;             sp[0] = f2bf(gelu_exact(c0) * v[0]);
;             sp[136] = f2bf(gelu_exact(c1) * v[1]);
;             sp[272] = f2bf(gelu_exact(c2) * v[2]);
;             sp[408] = f2bf(gelu_exact(c3) * v[3]);
;             if (s == 0) {
;               edge[0 * DFF + ch] = c0; edge[1 * DFF + ch] = g[0]; edge[2 * DFF + ch] = v[0];
;             }
;             if (s == 63) {
;               edge[3 * DFF + ch] = c3; edge[4 * DFF + ch] = g[3]; edge[5 * DFF + ch] = v[3];
;             }
;           }
	v_bfi_b32 v18, s86, v19, v18
	v_mul_f32_e32 v14, 0.5, v14
	v_add_f32_e32 v18, 1.0, v18
	v_add_f32_e32 v15, v207, v15
	v_mul_f32_e32 v14, v14, v18
	v_mul_f32_e32 v12, v12, v14
	v_mul_f32_e32 v14, 0x3f3504f3, v15
	v_fma_f32 v18, |v14|, s85, 1.0
	v_add3_u32 v22, s14, v82, v62
	v_cvt_pk_bf16_f32 v12, v12, s0
	ds_write_b16 v22, v12
	v_mul_f32_e32 v12, 0.5, v15
	v_rcp_f32_e32 v15, v18
	v_mul_f32_e64 v19, |v14|, -|v14|
	v_fmamk_f32 v18, v15, 0x3f87dc22, v206
	v_mul_f32_e32 v19, 0x3fb8aa3b, v19
	v_fmaak_f32 v18, v18, v15, 0x3fb5f0e3
	v_exp_f32_e32 v19, v19
	v_fmaak_f32 v18, v18, v15, 0xbe91a98e
	v_fmaak_f32 v18, v18, v15, 0x3e827906
	v_mul_f32_e32 v15, v15, v18
	v_mul_f32_e32 v16, v210, v110
	v_fma_f32 v15, -v19, v15, 1.0
	v_fmac_f32_e32 v16, v208, v113
	v_bfi_b32 v14, s86, v15, v14
	v_fmac_f32_e32 v16, v209, v111
	v_add_f32_e32 v14, 1.0, v14
	v_add_f32_e32 v16, v207, v16
	v_mul_f32_e32 v12, v12, v14
	v_mul_f32_e32 v12, v13, v12
	v_mul_f32_e32 v13, 0x3f3504f3, v16
	v_fma_f32 v14, |v13|, s85, 1.0
	v_cvt_pk_bf16_f32 v12, v12, s0
	ds_write_b16 v22, v12 offset:272
	v_mul_f32_e32 v12, 0.5, v16
	v_rcp_f32_e32 v14, v14
	v_mul_f32_e64 v16, |v13|, -|v13|
	v_fmamk_f32 v15, v14, 0x3f87dc22, v206
	v_mul_f32_e32 v16, 0x3fb8aa3b, v16
	v_fmaak_f32 v15, v15, v14, 0x3fb5f0e3
	v_exp_f32_e32 v16, v16
	v_fmaak_f32 v15, v15, v14, 0xbe91a98e
	v_fmaak_f32 v15, v15, v14, 0x3e827906
	v_mul_f32_e32 v14, v14, v15
	v_mul_f32_e32 v17, v210, v111
	v_fma_f32 v14, -v16, v14, 1.0
	v_fmac_f32_e32 v17, v208, v110
	v_bfi_b32 v13, s86, v14, v13
	v_fmac_f32_e32 v17, v209, v115
	v_add_f32_e32 v13, 1.0, v13
	v_add_f32_e32 v17, v207, v17
	v_mul_f32_e32 v12, v12, v13
	v_mul_f32_e32 v10, v10, v12
	v_mul_f32_e32 v12, 0x3f3504f3, v17
	v_fma_f32 v13, |v12|, s85, 1.0
	v_cvt_pk_bf16_f32 v10, v10, s0
	ds_write_b16 v22, v10 offset:544
	v_mul_f32_e32 v10, 0.5, v17
	v_rcp_f32_e32 v13, v13
	v_mul_f32_e64 v15, |v12|, -|v12|
	v_fmamk_f32 v14, v13, 0x3f87dc22, v206
	v_mul_f32_e32 v15, 0x3fb8aa3b, v15
	v_fmaak_f32 v14, v14, v13, 0x3fb5f0e3
	v_exp_f32_e32 v15, v15
	v_fmaak_f32 v14, v14, v13, 0xbe91a98e
	v_fmaak_f32 v14, v14, v13, 0x3e827906
	v_mul_f32_e32 v13, v13, v14
	v_fma_f32 v13, -v15, v13, 1.0
	v_bfi_b32 v12, s86, v13, v12
	v_add_f32_e32 v12, 1.0, v12
	v_mul_f32_e32 v10, v10, v12
	v_mul_f32_e32 v10, v11, v10
	v_cvt_pk_bf16_f32 v10, v10, s0
	ds_write_b16 v22, v10 offset:816
	v_mul_f32_e32 v10, v208, v109
	v_fmac_f32_e32 v10, v210, v104
	v_fmac_f32_e32 v10, v209, v105
	v_add_f32_e32 v10, v207, v10
	v_mul_f32_e32 v14, 0x3f3504f3, v10
	v_fma_f32 v15, |v14|, s85, 1.0
	v_mul_f32_e32 v11, v210, v105
	v_fmac_f32_e32 v11, v208, v104
	v_fmac_f32_e32 v11, v209, v102
	v_rcp_f32_e32 v15, v15
	v_mul_f32_e64 v17, |v14|, -|v14|
	v_fmamk_f32 v16, v15, 0x3f87dc22, v206
	v_mul_f32_e32 v17, 0x3fb8aa3b, v17
	v_fmaak_f32 v16, v16, v15, 0x3fb5f0e3
	v_exp_f32_e32 v17, v17
	v_fmaak_f32 v16, v16, v15, 0xbe91a98e
	v_fmaak_f32 v16, v16, v15, 0x3e827906
	v_mul_f32_e32 v15, v15, v16
	v_fma_f32 v15, -v17, v15, 1.0
	v_bfi_b32 v14, s86, v15, v14
	v_mul_f32_e32 v10, 0.5, v10
	v_add_f32_e32 v14, 1.0, v14
	v_add_f32_e32 v11, v207, v11
	v_mul_f32_e32 v10, v10, v14
	v_mul_f32_e32 v8, v8, v10
	v_mul_f32_e32 v10, 0x3f3504f3, v11
	v_fma_f32 v14, |v10|, s85, 1.0
	v_add3_u32 v18, s14, v74, v62
	v_cvt_pk_bf16_f32 v8, v8, s0
	ds_write_b16 v18, v8
	v_mul_f32_e32 v8, 0.5, v11
	v_rcp_f32_e32 v11, v14
	v_mul_f32_e64 v15, |v10|, -|v10|
	v_fmamk_f32 v14, v11, 0x3f87dc22, v206
	v_mul_f32_e32 v15, 0x3fb8aa3b, v15
	v_fmaak_f32 v14, v14, v11, 0x3fb5f0e3
	v_exp_f32_e32 v15, v15
	v_fmaak_f32 v14, v14, v11, 0xbe91a98e
	v_fmaak_f32 v14, v14, v11, 0x3e827906
	v_mul_f32_e32 v11, v11, v14
	v_mul_f32_e32 v12, v210, v102
	v_fma_f32 v11, -v15, v11, 1.0
	v_fmac_f32_e32 v12, v208, v105
	v_bfi_b32 v10, s86, v11, v10
	v_fmac_f32_e32 v12, v209, v103
	v_add_f32_e32 v10, 1.0, v10
	v_add_f32_e32 v12, v207, v12
	v_mul_f32_e32 v8, v8, v10
	v_mul_f32_e32 v8, v9, v8
	v_mul_f32_e32 v9, 0x3f3504f3, v12
	v_fma_f32 v10, |v9|, s85, 1.0
	v_cvt_pk_bf16_f32 v8, v8, s0
	ds_write_b16 v18, v8 offset:272
	v_mul_f32_e32 v8, 0.5, v12
	v_rcp_f32_e32 v10, v10
	v_mul_f32_e64 v12, |v9|, -|v9|
	v_fmamk_f32 v11, v10, 0x3f87dc22, v206
	v_mul_f32_e32 v12, 0x3fb8aa3b, v12
	v_fmaak_f32 v11, v11, v10, 0x3fb5f0e3
	v_exp_f32_e32 v12, v12
	v_fmaak_f32 v11, v11, v10, 0xbe91a98e
; __device__ __forceinline__ u16 f2bf(float f) { return (u16)(pack2(f, f) & 0xffffu); }
; __device__ __forceinline__ float erf_f32(float x) {
;   const float ax = fabsf(x);
;   const float t = __frcp_rn(fmaf(0.3275911f, ax, 1.0f));
;   float poly = fmaf(1.061405429f, t, -1.453152027f);
;   poly = fmaf(poly, t, 1.421413741f);
;   poly = fmaf(poly, t, -0.284496736f);
;   poly = fmaf(poly, t, 0.254829592f);
;   const float y = 1.0f - poly * t * __expf(-ax * ax);
;   return copysignf(y, x);
; }
; __device__ __forceinline__ float gelu_exact(float x) { return 0.5f * x * (1.0f + erf_f32(x * 0.70710678118654752f)); }
; template <int EPI>
; __device__ __forceinline__ void phase_gemm(const Params& p, const GemmDesc& d, char* shmc) {
;     ...
; #pragma unroll
;       for (int n = 0; n < 2; ++n) {
;         const int col = ewc * 32 + n * 16 + efr;
;         const int ch = ch0 + col;
;         const float w0 = cw[n][0], w1 = cw[n][1], w2 = cw[n][2], cb = cw[n][3];
; #pragma unroll
;         for (int ai = 0; ai < 2; ++ai)
; #pragma unroll
;           for (int m = 0; m < 4; ++m) {
;             const int s = ai * 32 + ewr * 16 + m * 4 + efq;
;             const f32x4 g = acc[ai][0][m][n];
;             const f32x4 v = acc[ai][1][m][n];
;             const float c0 = w0 * gp[ai][m][n] + w1 * g[0] + w2 * g[1] + cb;
;             const float c1 = w0 * g[0] + w1 * g[1] + w2 * g[2] + cb;
;             const float c2 = w0 * g[1] + w1 * g[2] + w2 * g[3] + cb;
;             const float c3 = w0 * g[2] + w1 * g[3] + w2 * gn[ai][m][n] + cb;
;             u16* sp = stg + (s * 4) * 136 + col;
;             sp[0] = f2bf(gelu_exact(c0) * v[0]);
;             sp[136] = f2bf(gelu_exact(c1) * v[1]);
;             sp[272] = f2bf(gelu_exact(c2) * v[2]);
;             sp[408] = f2bf(gelu_exact(c3) * v[3]);
;             if (s == 0) {
;               edge[0 * DFF + ch] = c0; edge[1 * DFF + ch] = g[0]; edge[2 * DFF + ch] = v[0];
;             }
;             if (s == 63) {
;               edge[3 * DFF + ch] = c3; edge[4 * DFF + ch] = g[3]; edge[5 * DFF + ch] = v[3];
;             }
;           }
	v_fmaak_f32 v11, v11, v10, 0x3e827906
	v_mul_f32_e32 v10, v10, v11
	v_mul_f32_e32 v13, v210, v103
	v_fma_f32 v10, -v12, v10, 1.0
	v_fmac_f32_e32 v13, v208, v102
	v_bfi_b32 v9, s86, v10, v9
	v_fmac_f32_e32 v13, v209, v107
	v_add_f32_e32 v9, 1.0, v9
	v_add_f32_e32 v13, v207, v13
	v_mul_f32_e32 v8, v8, v9
	v_mul_f32_e32 v6, v6, v8
	v_mul_f32_e32 v8, 0x3f3504f3, v13
	v_fma_f32 v9, |v8|, s85, 1.0
	v_cvt_pk_bf16_f32 v6, v6, s0
	ds_write_b16 v18, v6 offset:544
	v_mul_f32_e32 v6, 0.5, v13
	v_rcp_f32_e32 v9, v9
	v_mul_f32_e64 v11, |v8|, -|v8|
	v_fmamk_f32 v10, v9, 0x3f87dc22, v206
	v_mul_f32_e32 v11, 0x3fb8aa3b, v11
	v_fmaak_f32 v10, v10, v9, 0x3fb5f0e3
	v_exp_f32_e32 v11, v11
	v_fmaak_f32 v10, v10, v9, 0xbe91a98e
	v_fmaak_f32 v10, v10, v9, 0x3e827906
	v_mul_f32_e32 v9, v9, v10
	v_fma_f32 v9, -v11, v9, 1.0
	v_bfi_b32 v8, s86, v9, v8
	v_add_f32_e32 v8, 1.0, v8
	v_mul_f32_e32 v6, v6, v8
	v_mul_f32_e32 v6, v7, v6
	v_cvt_pk_bf16_f32 v6, v6, s0
	ds_write_b16 v18, v6 offset:816
	v_mul_f32_e32 v6, v208, v212
	v_fmac_f32_e32 v6, v210, v98
	v_fmac_f32_e32 v6, v209, v99
	v_add_f32_e32 v7, v207, v6
	v_mul_f32_e32 v10, 0x3f3504f3, v7
	v_fma_f32 v11, |v10|, s85, 1.0
	v_mul_f32_e32 v6, v210, v99
	v_fmac_f32_e32 v6, v208, v98
	v_fmac_f32_e32 v6, v209, v100
	v_rcp_f32_e32 v11, v11
	v_mul_f32_e64 v13, |v10|, -|v10|
	v_fmamk_f32 v12, v11, 0x3f87dc22, v206
	v_mul_f32_e32 v13, 0x3fb8aa3b, v13
	v_fmaak_f32 v12, v12, v11, 0x3fb5f0e3
	v_exp_f32_e32 v13, v13
	v_fmaak_f32 v12, v12, v11, 0xbe91a98e
	v_fmaak_f32 v12, v12, v11, 0x3e827906
	v_mul_f32_e32 v11, v11, v12
	v_fma_f32 v11, -v13, v11, 1.0
	v_bfi_b32 v10, s86, v11, v10
	v_mul_f32_e32 v7, 0.5, v7
	v_add_f32_e32 v10, 1.0, v10
	v_add_f32_e32 v8, v207, v6
	v_mul_f32_e32 v7, v7, v10
	v_mul_f32_e32 v4, v4, v7
	v_mul_f32_e32 v7, 0x3f3504f3, v8
	v_fma_f32 v10, |v7|, s85, 1.0
	v_add3_u32 v14, s14, v70, v62
	v_cvt_pk_bf16_f32 v4, v4, s0
	ds_write_b16 v14, v4
	v_mul_f32_e32 v4, 0.5, v8
	v_rcp_f32_e32 v8, v10
	v_mul_f32_e64 v11, |v7|, -|v7|
	v_fmamk_f32 v10, v8, 0x3f87dc22, v206
	v_mul_f32_e32 v11, 0x3fb8aa3b, v11
	v_fmaak_f32 v10, v10, v8, 0x3fb5f0e3
	v_exp_f32_e32 v11, v11
	v_fmaak_f32 v10, v10, v8, 0xbe91a98e
	v_fmaak_f32 v10, v10, v8, 0x3e827906
	v_mul_f32_e32 v8, v8, v10
	v_mul_f32_e32 v6, v210, v100
	v_fma_f32 v8, -v11, v8, 1.0
	v_fmac_f32_e32 v6, v208, v99
	v_bfi_b32 v7, s86, v8, v7
	v_fmac_f32_e32 v6, v209, v101
	v_add_f32_e32 v7, 1.0, v7
	v_add_f32_e32 v9, v207, v6
	v_mul_f32_e32 v4, v4, v7
	v_mul_f32_e32 v4, v5, v4
	v_mul_f32_e32 v5, 0x3f3504f3, v9
	v_fma_f32 v7, |v5|, s85, 1.0
	v_cvt_pk_bf16_f32 v4, v4, s0
	ds_write_b16 v14, v4 offset:272
	v_mul_f32_e32 v4, 0.5, v9
	v_rcp_f32_e32 v7, v7
	v_mul_f32_e64 v9, |v5|, -|v5|
	v_fmamk_f32 v8, v7, 0x3f87dc22, v206
	v_mul_f32_e32 v9, 0x3fb8aa3b, v9
	v_fmaak_f32 v8, v8, v7, 0x3fb5f0e3
	v_exp_f32_e32 v9, v9
	v_fmaak_f32 v8, v8, v7, 0xbe91a98e
	v_fmaak_f32 v8, v8, v7, 0x3e827906
	v_mul_f32_e32 v7, v7, v8
	v_mul_f32_e32 v6, v210, v101
	v_fma_f32 v7, -v9, v7, 1.0
	v_fmac_f32_e32 v6, v208, v100
	v_bfi_b32 v5, s86, v7, v5
	v_fmac_f32_e32 v6, v209, v211
	v_add_f32_e32 v5, 1.0, v5
	v_add_f32_e32 v6, v207, v6
	v_mul_f32_e32 v4, v4, v5
	v_mul_f32_e32 v2, v2, v4
	v_mul_f32_e32 v4, 0x3f3504f3, v6
	v_fma_f32 v5, |v4|, s85, 1.0
	v_cvt_pk_bf16_f32 v2, v2, s0
	ds_write_b16 v14, v2 offset:544
	v_mul_f32_e32 v2, 0.5, v6
	v_rcp_f32_e32 v5, v5
	v_mul_f32_e64 v8, |v4|, -|v4|
	v_fmamk_f32 v7, v5, 0x3f87dc22, v206
	v_mul_f32_e32 v8, 0x3fb8aa3b, v8
	v_fmaak_f32 v7, v7, v5, 0x3fb5f0e3
	v_exp_f32_e32 v8, v8
	v_fmaak_f32 v7, v7, v5, 0xbe91a98e
	v_fmaak_f32 v7, v7, v5, 0x3e827906
	v_mul_f32_e32 v5, v5, v7
	v_fma_f32 v5, -v8, v5, 1.0
	v_bfi_b32 v4, s86, v5, v4
	v_add_f32_e32 v4, 1.0, v4
	v_mul_f32_e32 v2, v2, v4
	v_mul_f32_e32 v2, v3, v2
	v_cvt_pk_bf16_f32 v2, v2, s0
	ds_write_b16 v14, v2 offset:816
	s_and_saveexec_b64 s[10:11], s[8:9]
	s_cbranch_execz .LBB0_1146
	v_add_co_u32_e32 v4, vcc, 0x10000, v58
	s_nop 1
	v_addc_co_u32_e32 v5, vcc, 0, v59, vcc
	global_store_dword v[4:5], v6, off offset:2048
	v_add_co_u32_e32 v4, vcc, 0x16000, v58
	s_nop 1
	v_addc_co_u32_e32 v5, vcc, 0, v59, vcc
	global_store_dword v[4:5], v101, off
	v_add_co_u32_e32 v4, vcc, 0x1b000, v58
	s_nop 1
	v_addc_co_u32_e32 v5, vcc, 0, v59, vcc
	global_store_dword v[4:5], v3, off offset:2048
	s_branch .LBB0_1146
